# GEMM load segments: LDS-DMA groups issued first, fragment ds_reads last (longer DMA flight time before the covering vmcnt)
# speedup vs baseline: 1.0226x; 1.0023x over previous
; #define PG8_STAGE(bufoff, gbase) do { _Pragma("unroll") for (int _i = 0; _i < 2; ++_i) \
;         __builtin_amdgcn_global_load_lds((const unsigned*)((const char*)(gbase) + voffA[_i]), (LAS unsigned*)(lds + (bufoff) + ldsw + _i * 8192), 16, 0, 0); } while (0)
; #define PG8_LDA(dst, b, h) do { _Pragma("unroll") for (int m = 0; m < 4; ++m) _Pragma("unroll") for (int k = 0; k < 2; ++k) dst[m][k] = *(const LAS bf16x8*)(lds + PG8_SA(b, h) + aoff + m * 2048 + k * 1024); } while (0)
; #define PG8_LDB(dst, b, h) do { _Pragma("unroll") for (int n = 0; n < 2; ++n) _Pragma("unroll") for (int k = 0; k < 2; ++k) dst[n][k] = *(const LAS bf16x8*)(lds + PG8_SB(b, h) + boff + n * 2048 + k * 1024); } while (0)
; #define PG8_MMA(ai, bj, At, Bt) do { __builtin_amdgcn_s_setprio(1); _Pragma("unroll") for (int m = 0; m < 4; ++m) _Pragma("unroll") for (int n = 0; n < 2; ++n) _Pragma("unroll") for (int k = 0; k < 2; ++k) \
;         acc[ai][bj][m][n] = __builtin_amdgcn_mfma_f32_16x16x32_bf16(Bt[n][k], At[m][k], acc[ai][bj][m][n], 0, 0, 0); __builtin_amdgcn_s_setprio(0); } while (0)
; #define PG8_WAIT_L(n) asm volatile("s_waitcnt lgkmcnt(" #n ")" ::: "memory")
; #define PG8_BAR __builtin_amdgcn_s_barrier()
; #define PG8_SCHED __builtin_amdgcn_sched_barrier(0)
; template <class Epi>
; DI void gemm_phase(const int TID, const int BID, LAS unsigned char* lds, const Gemm g, const Epi& E) {
;     ...
;             const bool last = (t == nt - 2);
;             const char* a1 = cA + (size_t)(t + 1) * kstep;
;             const char* a2 = last ? nA : cA + (size_t)(t + 2) * kstep; const char* b2 = last ? nB : cB + (size_t)(t + 2) * kstep;
;             const char* a3 = a2 + kstep; const char* b3 = b2 + kstep;
;             PG8_LDB(B0, 0, 0); PG8_SCHED; PG8_LDA(At, 0, 0); PG8_STAGE(PG8_SA(1, 1), a1 + hstep);
;             PG8_WAIT_L(8); PG8_BAR; PG8_WAIT_L(0); PG8_MMA(0, 0, At, B0); PG8_BAR; PG8_SCHED;
;             PG8_LDB(B1, 0, 1); PG8_STAGE(PG8_SB(0, 0), b2);
;             PG8_BAR; PG8_WAIT_L(0); PG8_MMA(0, 1, At, B1); PG8_BAR;
;             PG8_LDA(At, 0, 1); PG8_STAGE(PG8_SA(0, 0), a2);
;             PG8_BAR; PG8_WAIT_L(0); PG8_MMA(1, 0, At, B0); PG8_BAR; PG8_SCHED;
;             PG8_STAGE(PG8_SB(0, 1), b2 + hstep);
.LBB0_137:
	s_add_i32 s29, s58, 2
	s_add_u32 s60, s56, 0x80
	s_addc_u32 s59, s57, 0
	s_cmp_eq_u32 vcc_lo, s58
	s_cselect_b32 s58, s54, s60
	s_cselect_b32 s59, s55, s59
	s_cselect_b32 s61, s1, s18
	s_cselect_b32 s60, s0, vcc_hi
	v_lshl_add_u64 v[186:187], s[56:57], 0, v[178:179]
	s_add_i32 m0, s22, 0xc000
	global_load_lds_dwordx4 v[186:187], off
	v_lshl_add_u64 v[186:187], s[56:57], 0, v[180:181]
	s_add_i32 m0, s22, 0xe000
	s_nop 0
	global_load_lds_dwordx4 v[186:187], off
	v_add_u32_e32 v140, s19, v246
	ds_read_b128 v[128:131], v140
	ds_read_b128 v[132:135], v140 offset:1024
	ds_read_b128 v[136:139], v140 offset:2048
	ds_read_b128 v[140:143], v140 offset:3072
	ds_read_b128 v[144:147], v248
	ds_read_b128 v[148:151], v248 offset:1024
	ds_read_b128 v[152:155], v248 offset:2048
	ds_read_b128 v[156:159], v248 offset:3072
	ds_read_b128 v[160:163], v248 offset:4096
	ds_read_b128 v[164:167], v248 offset:5120
	ds_read_b128 v[170:173], v248 offset:6144
	ds_read_b128 v[182:185], v248 offset:7168
	v_add_u32_e32 v198, s24, v246
	ds_read_b128 v[186:189], v198
	ds_read_b128 v[190:193], v198 offset:1024
	ds_read_b128 v[194:197], v198 offset:2048
	ds_read_b128 v[198:201], v198 offset:3072
	s_waitcnt vmcnt(8)
	s_waitcnt lgkmcnt(0)
	s_barrier
	s_setprio 1
	v_mfma_f32_16x16x32_bf16 v[124:127], v[128:131], v[144:147], v[124:127]
	v_mfma_f32_16x16x32_bf16 v[120:123], v[136:139], v[144:147], v[120:123]
	v_mfma_f32_16x16x32_bf16 v[108:111], v[128:131], v[152:155], v[108:111]
	v_mfma_f32_16x16x32_bf16 v[104:107], v[136:139], v[152:155], v[104:107]
	v_mfma_f32_16x16x32_bf16 v[92:95], v[128:131], v[160:163], v[92:95]
	v_mfma_f32_16x16x32_bf16 v[88:91], v[136:139], v[160:163], v[88:91]
	v_mfma_f32_16x16x32_bf16 v[76:79], v[128:131], v[170:173], v[76:79]
	v_mfma_f32_16x16x32_bf16 v[72:75], v[136:139], v[170:173], v[72:75]
	v_mfma_f32_16x16x32_bf16 v[124:127], v[132:135], v[148:151], v[124:127]
	v_mfma_f32_16x16x32_bf16 v[120:123], v[140:143], v[148:151], v[120:123]
	v_mfma_f32_16x16x32_bf16 v[108:111], v[132:135], v[156:159], v[108:111]
	v_mfma_f32_16x16x32_bf16 v[104:107], v[140:143], v[156:159], v[104:107]
	v_mfma_f32_16x16x32_bf16 v[92:95], v[132:135], v[164:167], v[92:95]
	v_mfma_f32_16x16x32_bf16 v[88:91], v[140:143], v[164:167], v[88:91]
	v_mfma_f32_16x16x32_bf16 v[76:79], v[132:135], v[182:185], v[76:79]
	v_mfma_f32_16x16x32_bf16 v[72:75], v[140:143], v[182:185], v[72:75]
	v_mfma_f32_16x16x32_bf16 v[116:119], v[186:189], v[144:147], v[116:119]
	v_mfma_f32_16x16x32_bf16 v[112:115], v[194:197], v[144:147], v[112:115]
	v_mfma_f32_16x16x32_bf16 v[100:103], v[186:189], v[152:155], v[100:103]
	v_mfma_f32_16x16x32_bf16 v[96:99], v[194:197], v[152:155], v[96:99]
	v_mfma_f32_16x16x32_bf16 v[84:87], v[186:189], v[160:163], v[84:87]
	v_mfma_f32_16x16x32_bf16 v[80:83], v[194:197], v[160:163], v[80:83]
	v_mfma_f32_16x16x32_bf16 v[68:71], v[186:189], v[170:173], v[68:71]
	v_mfma_f32_16x16x32_bf16 v[64:67], v[194:197], v[170:173], v[64:67]
	v_mfma_f32_16x16x32_bf16 v[116:119], v[190:193], v[148:151], v[116:119]
	v_mfma_f32_16x16x32_bf16 v[112:115], v[198:201], v[148:151], v[112:115]
	v_mfma_f32_16x16x32_bf16 v[100:103], v[190:193], v[156:159], v[100:103]
	v_mfma_f32_16x16x32_bf16 v[96:99], v[198:201], v[156:159], v[96:99]
	v_mfma_f32_16x16x32_bf16 v[84:87], v[190:193], v[164:167], v[84:87]
	v_mfma_f32_16x16x32_bf16 v[80:83], v[198:201], v[164:167], v[80:83]
	v_mfma_f32_16x16x32_bf16 v[68:71], v[190:193], v[182:185], v[68:71]
	v_mfma_f32_16x16x32_bf16 v[64:67], v[198:201], v[182:185], v[64:67]
	s_setprio 0
	s_barrier
	s_mov_b32 m0, s20
	v_lshl_add_u64 v[202:203], s[60:61], 0, v[168:169]
	global_load_lds_dwordx4 v[202:203], off
	v_lshl_add_u64 v[204:205], s[60:61], 0, v[176:177]
	s_mov_b32 m0, s21
	s_nop 0
	global_load_lds_dwordx4 v[204:205], off
	s_mov_b32 m0, s22
	v_lshl_add_u64 v[206:207], s[58:59], 0, v[168:169]
	global_load_lds_dwordx4 v[206:207], off
	v_lshl_add_u64 v[208:209], s[58:59], 0, v[176:177]
	s_mov_b32 m0, s23
	s_nop 0
	global_load_lds_dwordx4 v[208:209], off
	s_add_u32 s60, s60, s6
	s_addc_u32 s61, s61, s7
	s_mov_b32 m0, s25
	v_lshl_add_u64 v[210:211], s[60:61], 0, v[168:169]
	global_load_lds_dwordx4 v[210:211], off
	v_lshl_add_u64 v[212:213], s[60:61], 0, v[176:177]
	s_mov_b32 m0, s26
	s_nop 0
	global_load_lds_dwordx4 v[212:213], off
	ds_read_b128 v[144:147], v248 offset:16384
	ds_read_b128 v[148:151], v248 offset:17408
	ds_read_b128 v[152:155], v248 offset:18432
	ds_read_b128 v[156:159], v248 offset:19456
	ds_read_b128 v[160:163], v248 offset:20480
	ds_read_b128 v[164:167], v248 offset:21504
	ds_read_b128 v[170:173], v248 offset:22528
	ds_read_b128 v[182:185], v248 offset:23552
	s_waitcnt vmcnt(8)
	s_waitcnt lgkmcnt(0)
	s_barrier
; #define PG8_STAGE(bufoff, gbase) do { _Pragma("unroll") for (int _i = 0; _i < 2; ++_i) \
;         __builtin_amdgcn_global_load_lds((const unsigned*)((const char*)(gbase) + voffA[_i]), (LAS unsigned*)(lds + (bufoff) + ldsw + _i * 8192), 16, 0, 0); } while (0)
; #define PG8_LDA(dst, b, h) do { _Pragma("unroll") for (int m = 0; m < 4; ++m) _Pragma("unroll") for (int k = 0; k < 2; ++k) dst[m][k] = *(const LAS bf16x8*)(lds + PG8_SA(b, h) + aoff + m * 2048 + k * 1024); } while (0)
; #define PG8_LDB(dst, b, h) do { _Pragma("unroll") for (int n = 0; n < 2; ++n) _Pragma("unroll") for (int k = 0; k < 2; ++k) dst[n][k] = *(const LAS bf16x8*)(lds + PG8_SB(b, h) + boff + n * 2048 + k * 1024); } while (0)
; #define PG8_MMA(ai, bj, At, Bt) do { __builtin_amdgcn_s_setprio(1); _Pragma("unroll") for (int m = 0; m < 4; ++m) _Pragma("unroll") for (int n = 0; n < 2; ++n) _Pragma("unroll") for (int k = 0; k < 2; ++k) \
;         acc[ai][bj][m][n] = __builtin_amdgcn_mfma_f32_16x16x32_bf16(Bt[n][k], At[m][k], acc[ai][bj][m][n], 0, 0, 0); __builtin_amdgcn_s_setprio(0); } while (0)
; #define PG8_WAIT_V(n) asm volatile("s_waitcnt vmcnt(" #n ")" ::: "memory")
; #define PG8_WAIT_L(n) asm volatile("s_waitcnt lgkmcnt(" #n ")" ::: "memory")
; #define PG8_BAR __builtin_amdgcn_s_barrier()
; #define PG8_SCHED __builtin_amdgcn_sched_barrier(0)
; template <class Epi>
; DI void gemm_phase(const int TID, const int BID, LAS unsigned char* lds, const Gemm g, const Epi& E) {
;     ...
;             PG8_BAR; PG8_WAIT_L(0); PG8_MMA(0, 1, At, B1); PG8_BAR;
;             PG8_LDA(At, 0, 1); PG8_STAGE(PG8_SA(0, 0), a2);
;             PG8_BAR; PG8_WAIT_L(0); PG8_MMA(1, 0, At, B0); PG8_BAR; PG8_SCHED;
;             PG8_STAGE(PG8_SB(0, 1), b2 + hstep);
;             PG8_WAIT_V(6); PG8_BAR; PG8_MMA(1, 1, At, B1); PG8_BAR;
;             PG8_LDB(B0, 1, 0); PG8_SCHED; PG8_LDA(At, 1, 0); PG8_STAGE(PG8_SA(0, 1), a2 + hstep);
;             PG8_WAIT_L(8); PG8_BAR; PG8_WAIT_L(0); PG8_MMA(0, 0, At, B0); PG8_BAR; PG8_SCHED;
;             PG8_LDB(B1, 1, 1); PG8_STAGE(PG8_SB(1, 0), b3);
	s_setprio 1
	v_mfma_f32_16x16x32_bf16 v[60:63], v[128:131], v[144:147], v[60:63]
	v_mfma_f32_16x16x32_bf16 v[56:59], v[136:139], v[144:147], v[56:59]
	v_mfma_f32_16x16x32_bf16 v[44:47], v[128:131], v[152:155], v[44:47]
	v_mfma_f32_16x16x32_bf16 v[40:43], v[136:139], v[152:155], v[40:43]
	v_mfma_f32_16x16x32_bf16 v[28:31], v[128:131], v[160:163], v[28:31]
	v_mfma_f32_16x16x32_bf16 v[24:27], v[136:139], v[160:163], v[24:27]
	v_mfma_f32_16x16x32_bf16 v[12:15], v[128:131], v[170:173], v[12:15]
	v_mfma_f32_16x16x32_bf16 v[8:11], v[136:139], v[170:173], v[8:11]
	v_mfma_f32_16x16x32_bf16 v[60:63], v[132:135], v[148:151], v[60:63]
	v_mfma_f32_16x16x32_bf16 v[56:59], v[140:143], v[148:151], v[56:59]
	v_mfma_f32_16x16x32_bf16 v[44:47], v[132:135], v[156:159], v[44:47]
	v_mfma_f32_16x16x32_bf16 v[40:43], v[140:143], v[156:159], v[40:43]
	v_mfma_f32_16x16x32_bf16 v[28:31], v[132:135], v[164:167], v[28:31]
	v_mfma_f32_16x16x32_bf16 v[24:27], v[140:143], v[164:167], v[24:27]
	v_mfma_f32_16x16x32_bf16 v[12:15], v[132:135], v[182:185], v[12:15]
	v_mfma_f32_16x16x32_bf16 v[8:11], v[140:143], v[182:185], v[8:11]
	v_mfma_f32_16x16x32_bf16 v[52:55], v[186:189], v[144:147], v[52:55]
	v_mfma_f32_16x16x32_bf16 v[48:51], v[194:197], v[144:147], v[48:51]
	v_mfma_f32_16x16x32_bf16 v[36:39], v[186:189], v[152:155], v[36:39]
	v_mfma_f32_16x16x32_bf16 v[32:35], v[194:197], v[152:155], v[32:35]
	v_mfma_f32_16x16x32_bf16 v[20:23], v[186:189], v[160:163], v[20:23]
	v_mfma_f32_16x16x32_bf16 v[16:19], v[194:197], v[160:163], v[16:19]
	v_mfma_f32_16x16x32_bf16 v[4:7], v[186:189], v[170:173], v[4:7]
	v_mfma_f32_16x16x32_bf16 v[0:3], v[194:197], v[170:173], v[0:3]
	v_mfma_f32_16x16x32_bf16 v[52:55], v[190:193], v[148:151], v[52:55]
	v_mfma_f32_16x16x32_bf16 v[48:51], v[198:201], v[148:151], v[48:51]
	v_mfma_f32_16x16x32_bf16 v[36:39], v[190:193], v[156:159], v[36:39]
	v_mfma_f32_16x16x32_bf16 v[32:35], v[198:201], v[156:159], v[32:35]
	v_mfma_f32_16x16x32_bf16 v[20:23], v[190:193], v[164:167], v[20:23]
	v_mfma_f32_16x16x32_bf16 v[16:19], v[198:201], v[164:167], v[16:19]
	v_mfma_f32_16x16x32_bf16 v[4:7], v[190:193], v[182:185], v[4:7]
	v_mfma_f32_16x16x32_bf16 v[0:3], v[198:201], v[182:185], v[0:3]
	s_setprio 0
	s_barrier
	s_add_u32 s58, s58, s6
	s_addc_u32 s59, s59, s7
	s_mov_b32 m0, s27
	v_lshl_add_u64 v[186:187], s[58:59], 0, v[168:169]
	global_load_lds_dwordx4 v[186:187], off
	v_lshl_add_u64 v[186:187], s[58:59], 0, v[176:177]
	s_mov_b32 m0, s28
	s_nop 0
	global_load_lds_dwordx4 v[186:187], off
	v_add_u32_e32 v140, s33, v246
	ds_read_b128 v[128:131], v140
	ds_read_b128 v[132:135], v140 offset:1024
	ds_read_b128 v[136:139], v140 offset:2048
	ds_read_b128 v[140:143], v140 offset:3072
	ds_read_b128 v[144:147], v248 offset:32768
	ds_read_b128 v[148:151], v248 offset:33792
	ds_read_b128 v[152:155], v248 offset:34816
	ds_read_b128 v[156:159], v248 offset:35840
	ds_read_b128 v[160:163], v248 offset:36864
	ds_read_b128 v[164:167], v248 offset:37888
	ds_read_b128 v[170:173], v248 offset:38912
	ds_read_b128 v[182:185], v248 offset:39936
	v_add_u32_e32 v198, s76, v246
	ds_read_b128 v[186:189], v198
	ds_read_b128 v[190:193], v198 offset:1024
	ds_read_b128 v[194:197], v198 offset:2048
	ds_read_b128 v[198:201], v198 offset:3072
	s_waitcnt vmcnt(8)
	s_waitcnt lgkmcnt(0)
	s_barrier
	s_setprio 1
	v_mfma_f32_16x16x32_bf16 v[124:127], v[128:131], v[144:147], v[124:127]
	v_mfma_f32_16x16x32_bf16 v[120:123], v[136:139], v[144:147], v[120:123]
	v_mfma_f32_16x16x32_bf16 v[108:111], v[128:131], v[152:155], v[108:111]
	v_mfma_f32_16x16x32_bf16 v[104:107], v[136:139], v[152:155], v[104:107]
	v_mfma_f32_16x16x32_bf16 v[92:95], v[128:131], v[160:163], v[92:95]
	v_mfma_f32_16x16x32_bf16 v[88:91], v[136:139], v[160:163], v[88:91]
	v_mfma_f32_16x16x32_bf16 v[76:79], v[128:131], v[170:173], v[76:79]
	v_mfma_f32_16x16x32_bf16 v[72:75], v[136:139], v[170:173], v[72:75]
	v_mfma_f32_16x16x32_bf16 v[124:127], v[132:135], v[148:151], v[124:127]
	v_mfma_f32_16x16x32_bf16 v[120:123], v[140:143], v[148:151], v[120:123]
	v_mfma_f32_16x16x32_bf16 v[108:111], v[132:135], v[156:159], v[108:111]
	v_mfma_f32_16x16x32_bf16 v[104:107], v[140:143], v[156:159], v[104:107]
	v_mfma_f32_16x16x32_bf16 v[92:95], v[132:135], v[164:167], v[92:95]
	v_mfma_f32_16x16x32_bf16 v[88:91], v[140:143], v[164:167], v[88:91]
	v_mfma_f32_16x16x32_bf16 v[76:79], v[132:135], v[182:185], v[76:79]
	v_mfma_f32_16x16x32_bf16 v[72:75], v[140:143], v[182:185], v[72:75]
	v_mfma_f32_16x16x32_bf16 v[116:119], v[186:189], v[144:147], v[116:119]
	v_mfma_f32_16x16x32_bf16 v[112:115], v[194:197], v[144:147], v[112:115]
	v_mfma_f32_16x16x32_bf16 v[100:103], v[186:189], v[152:155], v[100:103]
	v_mfma_f32_16x16x32_bf16 v[96:99], v[194:197], v[152:155], v[96:99]
	v_mfma_f32_16x16x32_bf16 v[84:87], v[186:189], v[160:163], v[84:87]
	v_mfma_f32_16x16x32_bf16 v[80:83], v[194:197], v[160:163], v[80:83]
	v_mfma_f32_16x16x32_bf16 v[68:71], v[186:189], v[170:173], v[68:71]
	v_mfma_f32_16x16x32_bf16 v[64:67], v[194:197], v[170:173], v[64:67]
	v_mfma_f32_16x16x32_bf16 v[116:119], v[190:193], v[148:151], v[116:119]
	v_mfma_f32_16x16x32_bf16 v[112:115], v[198:201], v[148:151], v[112:115]
	v_mfma_f32_16x16x32_bf16 v[100:103], v[190:193], v[156:159], v[100:103]
	v_mfma_f32_16x16x32_bf16 v[96:99], v[198:201], v[156:159], v[96:99]
	v_mfma_f32_16x16x32_bf16 v[84:87], v[190:193], v[164:167], v[84:87]
	v_mfma_f32_16x16x32_bf16 v[80:83], v[198:201], v[164:167], v[80:83]
	v_mfma_f32_16x16x32_bf16 v[68:71], v[190:193], v[182:185], v[68:71]
	v_mfma_f32_16x16x32_bf16 v[64:67], v[198:201], v[182:185], v[64:67]
	s_setprio 0
	s_barrier
; #define PG8_STAGE(bufoff, gbase) do { _Pragma("unroll") for (int _i = 0; _i < 2; ++_i) \
;         __builtin_amdgcn_global_load_lds((const unsigned*)((const char*)(gbase) + voffA[_i]), (LAS unsigned*)(lds + (bufoff) + ldsw + _i * 8192), 16, 0, 0); } while (0)
; #define PG8_LDA(dst, b, h) do { _Pragma("unroll") for (int m = 0; m < 4; ++m) _Pragma("unroll") for (int k = 0; k < 2; ++k) dst[m][k] = *(const LAS bf16x8*)(lds + PG8_SA(b, h) + aoff + m * 2048 + k * 1024); } while (0)
; #define PG8_LDB(dst, b, h) do { _Pragma("unroll") for (int n = 0; n < 2; ++n) _Pragma("unroll") for (int k = 0; k < 2; ++k) dst[n][k] = *(const LAS bf16x8*)(lds + PG8_SB(b, h) + boff + n * 2048 + k * 1024); } while (0)
; #define PG8_MMA(ai, bj, At, Bt) do { __builtin_amdgcn_s_setprio(1); _Pragma("unroll") for (int m = 0; m < 4; ++m) _Pragma("unroll") for (int n = 0; n < 2; ++n) _Pragma("unroll") for (int k = 0; k < 2; ++k) \
;         acc[ai][bj][m][n] = __builtin_amdgcn_mfma_f32_16x16x32_bf16(Bt[n][k], At[m][k], acc[ai][bj][m][n], 0, 0, 0); __builtin_amdgcn_s_setprio(0); } while (0)
; #define PG8_WAIT_V(n) asm volatile("s_waitcnt vmcnt(" #n ")" ::: "memory")
; #define PG8_WAIT_L(n) asm volatile("s_waitcnt lgkmcnt(" #n ")" ::: "memory")
; #define PG8_BAR __builtin_amdgcn_s_barrier()
; #define PG8_SCHED __builtin_amdgcn_sched_barrier(0)
; template <class Epi>
; DI void gemm_phase(const int TID, const int BID, LAS unsigned char* lds, const Gemm g, const Epi& E) {
;     ...
;             PG8_LDB(B1, 1, 1); PG8_STAGE(PG8_SB(1, 0), b3);
;             PG8_BAR; PG8_WAIT_L(0); PG8_MMA(0, 1, At, B1); PG8_BAR;
;             PG8_LDA(At, 1, 1); PG8_STAGE(PG8_SA(1, 0), a3);
;             PG8_BAR; PG8_WAIT_L(0); PG8_MMA(1, 0, At, B0); PG8_BAR; PG8_SCHED;
;             PG8_STAGE(PG8_SB(1, 1), b3 + hstep);
;             PG8_WAIT_V(6); PG8_BAR; PG8_MMA(1, 1, At, B1); PG8_BAR;
;         }
	s_mov_b32 m0, s64
	v_lshl_add_u64 v[202:203], v[202:203], 0, s[92:93]
	global_load_lds_dwordx4 v[202:203], off
	v_lshl_add_u64 v[202:203], v[204:205], 0, s[92:93]
	s_mov_b32 m0, s65
	s_nop 0
	global_load_lds_dwordx4 v[202:203], off
	s_mov_b32 m0, s66
	v_lshl_add_u64 v[202:203], v[206:207], 0, s[92:93]
	global_load_lds_dwordx4 v[202:203], off
	v_lshl_add_u64 v[202:203], v[208:209], 0, s[92:93]
	s_mov_b32 m0, s67
	s_nop 0
	global_load_lds_dwordx4 v[202:203], off
	s_mov_b32 m0, s77
	v_lshl_add_u64 v[202:203], v[210:211], 0, s[92:93]
	global_load_lds_dwordx4 v[202:203], off
	v_lshl_add_u64 v[202:203], v[212:213], 0, s[92:93]
	s_mov_b32 m0, s80
	s_nop 0
	global_load_lds_dwordx4 v[202:203], off
	ds_read_b128 v[144:147], v248 offset:49152
	ds_read_b128 v[148:151], v248 offset:50176
	ds_read_b128 v[152:155], v248 offset:51200
	ds_read_b128 v[156:159], v248 offset:52224
	ds_read_b128 v[160:163], v248 offset:53248
	ds_read_b128 v[164:167], v248 offset:54272
	ds_read_b128 v[170:173], v248 offset:55296
	ds_read_b128 v[182:185], v248 offset:56320
	s_waitcnt vmcnt(8)
	s_waitcnt lgkmcnt(0)
	s_barrier
	s_setprio 1
	v_mfma_f32_16x16x32_bf16 v[60:63], v[128:131], v[144:147], v[60:63]
	v_mfma_f32_16x16x32_bf16 v[56:59], v[136:139], v[144:147], v[56:59]
	v_mfma_f32_16x16x32_bf16 v[44:47], v[128:131], v[152:155], v[44:47]
	v_mfma_f32_16x16x32_bf16 v[40:43], v[136:139], v[152:155], v[40:43]
	v_mfma_f32_16x16x32_bf16 v[28:31], v[128:131], v[160:163], v[28:31]
	v_mfma_f32_16x16x32_bf16 v[24:27], v[136:139], v[160:163], v[24:27]
	v_mfma_f32_16x16x32_bf16 v[12:15], v[128:131], v[170:173], v[12:15]
	v_mfma_f32_16x16x32_bf16 v[8:11], v[136:139], v[170:173], v[8:11]
	v_mfma_f32_16x16x32_bf16 v[60:63], v[132:135], v[148:151], v[60:63]
	v_mfma_f32_16x16x32_bf16 v[56:59], v[140:143], v[148:151], v[56:59]
	v_mfma_f32_16x16x32_bf16 v[44:47], v[132:135], v[156:159], v[44:47]
	v_mfma_f32_16x16x32_bf16 v[40:43], v[140:143], v[156:159], v[40:43]
	v_mfma_f32_16x16x32_bf16 v[28:31], v[132:135], v[164:167], v[28:31]
	v_mfma_f32_16x16x32_bf16 v[24:27], v[140:143], v[164:167], v[24:27]
	v_mfma_f32_16x16x32_bf16 v[12:15], v[132:135], v[182:185], v[12:15]
	v_mfma_f32_16x16x32_bf16 v[8:11], v[140:143], v[182:185], v[8:11]
	v_mfma_f32_16x16x32_bf16 v[52:55], v[186:189], v[144:147], v[52:55]
	v_mfma_f32_16x16x32_bf16 v[48:51], v[194:197], v[144:147], v[48:51]
	v_mfma_f32_16x16x32_bf16 v[36:39], v[186:189], v[152:155], v[36:39]
	v_mfma_f32_16x16x32_bf16 v[32:35], v[194:197], v[152:155], v[32:35]
	v_mfma_f32_16x16x32_bf16 v[20:23], v[186:189], v[160:163], v[20:23]
	v_mfma_f32_16x16x32_bf16 v[16:19], v[194:197], v[160:163], v[16:19]
	v_mfma_f32_16x16x32_bf16 v[4:7], v[186:189], v[170:173], v[4:7]
	v_mfma_f32_16x16x32_bf16 v[0:3], v[194:197], v[170:173], v[0:3]
	v_mfma_f32_16x16x32_bf16 v[52:55], v[190:193], v[148:151], v[52:55]
	v_mfma_f32_16x16x32_bf16 v[48:51], v[198:201], v[148:151], v[48:51]
	v_mfma_f32_16x16x32_bf16 v[36:39], v[190:193], v[156:159], v[36:39]
	v_mfma_f32_16x16x32_bf16 v[32:35], v[198:201], v[156:159], v[32:35]
	v_mfma_f32_16x16x32_bf16 v[20:23], v[190:193], v[164:167], v[20:23]
	v_mfma_f32_16x16x32_bf16 v[16:19], v[198:201], v[164:167], v[16:19]
	v_mfma_f32_16x16x32_bf16 v[4:7], v[190:193], v[182:185], v[4:7]
	v_mfma_f32_16x16x32_bf16 v[0:3], v[198:201], v[182:185], v[0:3]
	s_setprio 0
	s_add_u32 s56, s56, 0x100
	s_addc_u32 s57, s57, 0
	s_add_u32 vcc_hi, vcc_hi, 0x100
	s_addc_u32 s18, s18, 0
	s_cmp_ge_i32 s29, s5
	s_mov_b32 s58, s29
	s_barrier
	s_cbranch_scc0 .LBB0_137
	s_branch .LBB0_141

; #define PG8_STAGE(bufoff, gbase) do { _Pragma("unroll") for (int _i = 0; _i < 2; ++_i) \
;         __builtin_amdgcn_global_load_lds((const unsigned*)((const char*)(gbase) + voffA[_i]), (LAS unsigned*)(lds + (bufoff) + ldsw + _i * 8192), 16, 0, 0); } while (0)
; #define PG8_LDA(dst, b, h) do { _Pragma("unroll") for (int m = 0; m < 4; ++m) _Pragma("unroll") for (int k = 0; k < 2; ++k) dst[m][k] = *(const LAS bf16x8*)(lds + PG8_SA(b, h) + aoff + m * 2048 + k * 1024); } while (0)
; #define PG8_LDB(dst, b, h) do { _Pragma("unroll") for (int n = 0; n < 2; ++n) _Pragma("unroll") for (int k = 0; k < 2; ++k) dst[n][k] = *(const LAS bf16x8*)(lds + PG8_SB(b, h) + boff + n * 2048 + k * 1024); } while (0)
; #define PG8_MMA(ai, bj, At, Bt) do { __builtin_amdgcn_s_setprio(1); _Pragma("unroll") for (int m = 0; m < 4; ++m) _Pragma("unroll") for (int n = 0; n < 2; ++n) _Pragma("unroll") for (int k = 0; k < 2; ++k) \
;         acc[ai][bj][m][n] = __builtin_amdgcn_mfma_f32_16x16x32_bf16(Bt[n][k], At[m][k], acc[ai][bj][m][n], 0, 0, 0); __builtin_amdgcn_s_setprio(0); } while (0)
; #define PG8_WAIT_L(n) asm volatile("s_waitcnt lgkmcnt(" #n ")" ::: "memory")
; #define PG8_BAR __builtin_amdgcn_s_barrier()
; #define PG8_SCHED __builtin_amdgcn_sched_barrier(0)
; template <class Epi>
; DI void gemm_phase(const int TID, const int BID, LAS unsigned char* lds, const Gemm g, const Epi& E) {
;     ...
;             const bool last = (t == nt - 2);
;             const char* a1 = cA + (size_t)(t + 1) * kstep;
;             const char* a2 = last ? nA : cA + (size_t)(t + 2) * kstep; const char* b2 = last ? nB : cB + (size_t)(t + 2) * kstep;
;             const char* a3 = a2 + kstep; const char* b3 = b2 + kstep;
;             PG8_LDB(B0, 0, 0); PG8_SCHED; PG8_LDA(At, 0, 0); PG8_STAGE(PG8_SA(1, 1), a1 + hstep);
;             PG8_WAIT_L(8); PG8_BAR; PG8_WAIT_L(0); PG8_MMA(0, 0, At, B0); PG8_BAR; PG8_SCHED;
;             PG8_LDB(B1, 0, 1); PG8_STAGE(PG8_SB(0, 0), b2);
;             PG8_BAR; PG8_WAIT_L(0); PG8_MMA(0, 1, At, B1); PG8_BAR;
;             PG8_LDA(At, 0, 1); PG8_STAGE(PG8_SA(0, 0), a2);
;             PG8_BAR; PG8_WAIT_L(0); PG8_MMA(1, 0, At, B0); PG8_BAR; PG8_SCHED;
;             PG8_STAGE(PG8_SB(0, 1), b2 + hstep);
.LBB0_164:
	v_add_u32_e32 v138, s16, v141
	ds_read_b128 v[134:137], v138
	ds_read_b128 v[144:147], v138 offset:1024
	ds_read_b128 v[148:151], v138 offset:2048
	ds_read_b128 v[152:155], v138 offset:3072
	s_add_i32 s80, s56, 2
	s_add_u32 s58, s54, 0x80
	s_addc_u32 s57, s55, 0
	s_cmp_eq_u32 s62, s56
	s_cselect_b32 s56, s12, s58
	s_cselect_b32 s57, s13, s57
	s_cselect_b32 s59, s53, s77
	s_cselect_b32 s58, s52, s76
	v_lshl_add_u64 v[138:139], s[54:55], 0, v[130:131]
	s_add_i32 m0, s19, 0xc000
	ds_read_b128 v[156:159], v143
	ds_read_b128 v[160:163], v143 offset:1024
	ds_read_b128 v[164:167], v143 offset:2048
	ds_read_b128 v[170:173], v143 offset:3072
	ds_read_b128 v[176:179], v143 offset:4096
	ds_read_b128 v[180:183], v143 offset:5120
	ds_read_b128 v[184:187], v143 offset:6144
	ds_read_b128 v[188:191], v143 offset:7168
	global_load_lds_dwordx4 v[138:139], off
	v_lshl_add_u64 v[138:139], s[54:55], 0, v[132:133]
	s_add_i32 m0, s19, 0xe000
	s_nop 0
	global_load_lds_dwordx4 v[138:139], off
	v_add_u32_e32 v138, s21, v141
	ds_read_b128 v[192:195], v138
	ds_read_b128 v[196:199], v138 offset:1024
	ds_read_b128 v[200:203], v138 offset:2048
	ds_read_b128 v[204:207], v138 offset:3072
	s_waitcnt vmcnt(8)
	s_waitcnt lgkmcnt(0)
	s_barrier
	s_setprio 1
	v_mfma_f32_16x16x32_bf16 v[124:127], v[134:137], v[156:159], v[124:127]
	v_mfma_f32_16x16x32_bf16 v[120:123], v[148:151], v[156:159], v[120:123]
	v_mfma_f32_16x16x32_bf16 v[108:111], v[134:137], v[164:167], v[108:111]
	v_mfma_f32_16x16x32_bf16 v[104:107], v[148:151], v[164:167], v[104:107]
	v_mfma_f32_16x16x32_bf16 v[92:95], v[134:137], v[176:179], v[92:95]
	v_mfma_f32_16x16x32_bf16 v[88:91], v[148:151], v[176:179], v[88:91]
	v_mfma_f32_16x16x32_bf16 v[76:79], v[134:137], v[184:187], v[76:79]
	v_mfma_f32_16x16x32_bf16 v[72:75], v[148:151], v[184:187], v[72:75]
	v_mfma_f32_16x16x32_bf16 v[124:127], v[144:147], v[160:163], v[124:127]
	v_mfma_f32_16x16x32_bf16 v[120:123], v[152:155], v[160:163], v[120:123]
	v_mfma_f32_16x16x32_bf16 v[108:111], v[144:147], v[170:173], v[108:111]
	v_mfma_f32_16x16x32_bf16 v[104:107], v[152:155], v[170:173], v[104:107]
	v_mfma_f32_16x16x32_bf16 v[92:95], v[144:147], v[180:183], v[92:95]
	v_mfma_f32_16x16x32_bf16 v[88:91], v[152:155], v[180:183], v[88:91]
	v_mfma_f32_16x16x32_bf16 v[76:79], v[144:147], v[188:191], v[76:79]
	v_mfma_f32_16x16x32_bf16 v[72:75], v[152:155], v[188:191], v[72:75]
	v_mfma_f32_16x16x32_bf16 v[116:119], v[192:195], v[156:159], v[116:119]
	v_mfma_f32_16x16x32_bf16 v[112:115], v[200:203], v[156:159], v[112:115]
	v_mfma_f32_16x16x32_bf16 v[100:103], v[192:195], v[164:167], v[100:103]
	v_mfma_f32_16x16x32_bf16 v[96:99], v[200:203], v[164:167], v[96:99]
	v_mfma_f32_16x16x32_bf16 v[84:87], v[192:195], v[176:179], v[84:87]
	v_mfma_f32_16x16x32_bf16 v[80:83], v[200:203], v[176:179], v[80:83]
	v_mfma_f32_16x16x32_bf16 v[68:71], v[192:195], v[184:187], v[68:71]
	v_mfma_f32_16x16x32_bf16 v[64:67], v[200:203], v[184:187], v[64:67]
	v_mfma_f32_16x16x32_bf16 v[116:119], v[196:199], v[160:163], v[116:119]
	v_mfma_f32_16x16x32_bf16 v[112:115], v[204:207], v[160:163], v[112:115]
	v_mfma_f32_16x16x32_bf16 v[100:103], v[196:199], v[170:173], v[100:103]
	v_mfma_f32_16x16x32_bf16 v[96:99], v[204:207], v[170:173], v[96:99]
	v_mfma_f32_16x16x32_bf16 v[84:87], v[196:199], v[180:183], v[84:87]
	v_mfma_f32_16x16x32_bf16 v[80:83], v[204:207], v[180:183], v[80:83]
	v_mfma_f32_16x16x32_bf16 v[68:71], v[196:199], v[188:191], v[68:71]
	v_mfma_f32_16x16x32_bf16 v[64:67], v[204:207], v[188:191], v[64:67]
	s_setprio 0
	s_barrier
	s_mov_b32 m0, s17
	v_lshl_add_u64 v[138:139], s[58:59], 0, v[168:169]
	global_load_lds_dwordx4 v[138:139], off
	v_lshl_add_u64 v[208:209], s[58:59], 0, v[128:129]
	s_mov_b32 m0, s18
	s_nop 0
	global_load_lds_dwordx4 v[208:209], off
	s_mov_b32 m0, s19
	v_lshl_add_u64 v[210:211], s[56:57], 0, v[168:169]
	global_load_lds_dwordx4 v[210:211], off
	v_lshl_add_u64 v[212:213], s[56:57], 0, v[128:129]
	s_mov_b32 m0, s20
	s_nop 0
	global_load_lds_dwordx4 v[212:213], off
	s_add_u32 s58, s58, s0
	s_addc_u32 s59, s59, s1
	s_mov_b32 m0, s22
	v_lshl_add_u64 v[214:215], s[58:59], 0, v[168:169]
	global_load_lds_dwordx4 v[214:215], off
	v_lshl_add_u64 v[216:217], s[58:59], 0, v[128:129]
	s_mov_b32 m0, s23
	s_nop 0
	global_load_lds_dwordx4 v[216:217], off
	ds_read_b128 v[156:159], v143 offset:16384
	ds_read_b128 v[160:163], v143 offset:17408
	ds_read_b128 v[164:167], v143 offset:18432
	ds_read_b128 v[170:173], v143 offset:19456
	ds_read_b128 v[176:179], v143 offset:20480
	ds_read_b128 v[180:183], v143 offset:21504
	ds_read_b128 v[184:187], v143 offset:22528
	ds_read_b128 v[188:191], v143 offset:23552
	s_waitcnt vmcnt(8)
	s_waitcnt lgkmcnt(0)
	s_barrier
; #define PG8_STAGE(bufoff, gbase) do { _Pragma("unroll") for (int _i = 0; _i < 2; ++_i) \
;         __builtin_amdgcn_global_load_lds((const unsigned*)((const char*)(gbase) + voffA[_i]), (LAS unsigned*)(lds + (bufoff) + ldsw + _i * 8192), 16, 0, 0); } while (0)
; #define PG8_LDA(dst, b, h) do { _Pragma("unroll") for (int m = 0; m < 4; ++m) _Pragma("unroll") for (int k = 0; k < 2; ++k) dst[m][k] = *(const LAS bf16x8*)(lds + PG8_SA(b, h) + aoff + m * 2048 + k * 1024); } while (0)
; #define PG8_LDB(dst, b, h) do { _Pragma("unroll") for (int n = 0; n < 2; ++n) _Pragma("unroll") for (int k = 0; k < 2; ++k) dst[n][k] = *(const LAS bf16x8*)(lds + PG8_SB(b, h) + boff + n * 2048 + k * 1024); } while (0)
; #define PG8_MMA(ai, bj, At, Bt) do { __builtin_amdgcn_s_setprio(1); _Pragma("unroll") for (int m = 0; m < 4; ++m) _Pragma("unroll") for (int n = 0; n < 2; ++n) _Pragma("unroll") for (int k = 0; k < 2; ++k) \
;         acc[ai][bj][m][n] = __builtin_amdgcn_mfma_f32_16x16x32_bf16(Bt[n][k], At[m][k], acc[ai][bj][m][n], 0, 0, 0); __builtin_amdgcn_s_setprio(0); } while (0)
; #define PG8_WAIT_V(n) asm volatile("s_waitcnt vmcnt(" #n ")" ::: "memory")
; #define PG8_WAIT_L(n) asm volatile("s_waitcnt lgkmcnt(" #n ")" ::: "memory")
; #define PG8_BAR __builtin_amdgcn_s_barrier()
; #define PG8_SCHED __builtin_amdgcn_sched_barrier(0)
; template <class Epi>
; DI void gemm_phase(const int TID, const int BID, LAS unsigned char* lds, const Gemm g, const Epi& E) {
;     ...
;             PG8_BAR; PG8_WAIT_L(0); PG8_MMA(0, 1, At, B1); PG8_BAR;
;             PG8_LDA(At, 0, 1); PG8_STAGE(PG8_SA(0, 0), a2);
;             PG8_BAR; PG8_WAIT_L(0); PG8_MMA(1, 0, At, B0); PG8_BAR; PG8_SCHED;
;             PG8_STAGE(PG8_SB(0, 1), b2 + hstep);
;             PG8_WAIT_V(6); PG8_BAR; PG8_MMA(1, 1, At, B1); PG8_BAR;
;             PG8_LDB(B0, 1, 0); PG8_SCHED; PG8_LDA(At, 1, 0); PG8_STAGE(PG8_SA(0, 1), a2 + hstep);
;             PG8_WAIT_L(8); PG8_BAR; PG8_WAIT_L(0); PG8_MMA(0, 0, At, B0); PG8_BAR; PG8_SCHED;
;             PG8_LDB(B1, 1, 1); PG8_STAGE(PG8_SB(1, 0), b3);
	s_setprio 1
	v_mfma_f32_16x16x32_bf16 v[60:63], v[134:137], v[156:159], v[60:63]
	v_mfma_f32_16x16x32_bf16 v[56:59], v[148:151], v[156:159], v[56:59]
	v_mfma_f32_16x16x32_bf16 v[44:47], v[134:137], v[164:167], v[44:47]
	v_mfma_f32_16x16x32_bf16 v[40:43], v[148:151], v[164:167], v[40:43]
	v_mfma_f32_16x16x32_bf16 v[28:31], v[134:137], v[176:179], v[28:31]
	v_mfma_f32_16x16x32_bf16 v[24:27], v[148:151], v[176:179], v[24:27]
	v_mfma_f32_16x16x32_bf16 v[12:15], v[134:137], v[184:187], v[12:15]
	v_mfma_f32_16x16x32_bf16 v[8:11], v[148:151], v[184:187], v[8:11]
	v_mfma_f32_16x16x32_bf16 v[60:63], v[144:147], v[160:163], v[60:63]
	v_mfma_f32_16x16x32_bf16 v[56:59], v[152:155], v[160:163], v[56:59]
	v_mfma_f32_16x16x32_bf16 v[44:47], v[144:147], v[170:173], v[44:47]
	v_mfma_f32_16x16x32_bf16 v[40:43], v[152:155], v[170:173], v[40:43]
	v_mfma_f32_16x16x32_bf16 v[28:31], v[144:147], v[180:183], v[28:31]
	v_mfma_f32_16x16x32_bf16 v[24:27], v[152:155], v[180:183], v[24:27]
	v_mfma_f32_16x16x32_bf16 v[12:15], v[144:147], v[188:191], v[12:15]
	v_mfma_f32_16x16x32_bf16 v[8:11], v[152:155], v[188:191], v[8:11]
	v_mfma_f32_16x16x32_bf16 v[52:55], v[192:195], v[156:159], v[52:55]
	v_mfma_f32_16x16x32_bf16 v[48:51], v[200:203], v[156:159], v[48:51]
	v_mfma_f32_16x16x32_bf16 v[36:39], v[192:195], v[164:167], v[36:39]
	v_mfma_f32_16x16x32_bf16 v[32:35], v[200:203], v[164:167], v[32:35]
	v_mfma_f32_16x16x32_bf16 v[20:23], v[192:195], v[176:179], v[20:23]
	v_mfma_f32_16x16x32_bf16 v[16:19], v[200:203], v[176:179], v[16:19]
	v_mfma_f32_16x16x32_bf16 v[4:7], v[192:195], v[184:187], v[4:7]
	v_mfma_f32_16x16x32_bf16 v[0:3], v[200:203], v[184:187], v[0:3]
	v_mfma_f32_16x16x32_bf16 v[52:55], v[196:199], v[160:163], v[52:55]
	v_mfma_f32_16x16x32_bf16 v[48:51], v[204:207], v[160:163], v[48:51]
	v_mfma_f32_16x16x32_bf16 v[36:39], v[196:199], v[170:173], v[36:39]
	v_mfma_f32_16x16x32_bf16 v[32:35], v[204:207], v[170:173], v[32:35]
	v_mfma_f32_16x16x32_bf16 v[20:23], v[196:199], v[180:183], v[20:23]
	v_mfma_f32_16x16x32_bf16 v[16:19], v[204:207], v[180:183], v[16:19]
	v_mfma_f32_16x16x32_bf16 v[4:7], v[196:199], v[188:191], v[4:7]
	v_mfma_f32_16x16x32_bf16 v[0:3], v[204:207], v[188:191], v[0:3]
	s_setprio 0
	s_barrier
	s_add_u32 s56, s56, s0
	s_addc_u32 s57, s57, s1
	s_mov_b32 m0, s24
	v_lshl_add_u64 v[192:193], s[56:57], 0, v[168:169]
	global_load_lds_dwordx4 v[192:193], off
	v_lshl_add_u64 v[192:193], s[56:57], 0, v[128:129]
	s_mov_b32 m0, s25
	s_nop 0
	global_load_lds_dwordx4 v[192:193], off
	v_add_u32_e32 v152, s27, v141
	ds_read_b128 v[134:137], v152
	ds_read_b128 v[144:147], v152 offset:1024
	ds_read_b128 v[148:151], v152 offset:2048
	ds_read_b128 v[152:155], v152 offset:3072
	ds_read_b128 v[156:159], v143 offset:32768
	ds_read_b128 v[160:163], v143 offset:33792
	ds_read_b128 v[164:167], v143 offset:34816
	ds_read_b128 v[170:173], v143 offset:35840
	ds_read_b128 v[176:179], v143 offset:36864
	ds_read_b128 v[180:183], v143 offset:37888
	ds_read_b128 v[184:187], v143 offset:38912
	ds_read_b128 v[188:191], v143 offset:39936
	v_add_u32_e32 v175, s33, v141
	ds_read_b128 v[192:195], v175
	ds_read_b128 v[196:199], v175 offset:1024
	ds_read_b128 v[200:203], v175 offset:2048
	ds_read_b128 v[204:207], v175 offset:3072
	s_waitcnt vmcnt(8)
	s_waitcnt lgkmcnt(0)
	s_barrier
	s_setprio 1
	v_mfma_f32_16x16x32_bf16 v[124:127], v[134:137], v[156:159], v[124:127]
	v_mfma_f32_16x16x32_bf16 v[120:123], v[148:151], v[156:159], v[120:123]
	v_mfma_f32_16x16x32_bf16 v[108:111], v[134:137], v[164:167], v[108:111]
	v_mfma_f32_16x16x32_bf16 v[104:107], v[148:151], v[164:167], v[104:107]
	v_mfma_f32_16x16x32_bf16 v[92:95], v[134:137], v[176:179], v[92:95]
	v_mfma_f32_16x16x32_bf16 v[88:91], v[148:151], v[176:179], v[88:91]
	v_mfma_f32_16x16x32_bf16 v[76:79], v[134:137], v[184:187], v[76:79]
	v_mfma_f32_16x16x32_bf16 v[72:75], v[148:151], v[184:187], v[72:75]
	v_mfma_f32_16x16x32_bf16 v[124:127], v[144:147], v[160:163], v[124:127]
	v_mfma_f32_16x16x32_bf16 v[120:123], v[152:155], v[160:163], v[120:123]
	v_mfma_f32_16x16x32_bf16 v[108:111], v[144:147], v[170:173], v[108:111]
	v_mfma_f32_16x16x32_bf16 v[104:107], v[152:155], v[170:173], v[104:107]
	v_mfma_f32_16x16x32_bf16 v[92:95], v[144:147], v[180:183], v[92:95]
	v_mfma_f32_16x16x32_bf16 v[88:91], v[152:155], v[180:183], v[88:91]
	v_mfma_f32_16x16x32_bf16 v[76:79], v[144:147], v[188:191], v[76:79]
	v_mfma_f32_16x16x32_bf16 v[72:75], v[152:155], v[188:191], v[72:75]
	v_mfma_f32_16x16x32_bf16 v[116:119], v[192:195], v[156:159], v[116:119]
	v_mfma_f32_16x16x32_bf16 v[112:115], v[200:203], v[156:159], v[112:115]
	v_mfma_f32_16x16x32_bf16 v[100:103], v[192:195], v[164:167], v[100:103]
	v_mfma_f32_16x16x32_bf16 v[96:99], v[200:203], v[164:167], v[96:99]
	v_mfma_f32_16x16x32_bf16 v[84:87], v[192:195], v[176:179], v[84:87]
	v_mfma_f32_16x16x32_bf16 v[80:83], v[200:203], v[176:179], v[80:83]
	v_mfma_f32_16x16x32_bf16 v[68:71], v[192:195], v[184:187], v[68:71]
	v_mfma_f32_16x16x32_bf16 v[64:67], v[200:203], v[184:187], v[64:67]
	v_mfma_f32_16x16x32_bf16 v[116:119], v[196:199], v[160:163], v[116:119]
	v_mfma_f32_16x16x32_bf16 v[112:115], v[204:207], v[160:163], v[112:115]
	v_mfma_f32_16x16x32_bf16 v[100:103], v[196:199], v[170:173], v[100:103]
	v_mfma_f32_16x16x32_bf16 v[96:99], v[204:207], v[170:173], v[96:99]
	v_mfma_f32_16x16x32_bf16 v[84:87], v[196:199], v[180:183], v[84:87]
	v_mfma_f32_16x16x32_bf16 v[80:83], v[204:207], v[180:183], v[80:83]
	v_mfma_f32_16x16x32_bf16 v[68:71], v[196:199], v[188:191], v[68:71]
	v_mfma_f32_16x16x32_bf16 v[64:67], v[204:207], v[188:191], v[64:67]
	s_setprio 0
	s_barrier
; #define PG8_STAGE(bufoff, gbase) do { _Pragma("unroll") for (int _i = 0; _i < 2; ++_i) \
;         __builtin_amdgcn_global_load_lds((const unsigned*)((const char*)(gbase) + voffA[_i]), (LAS unsigned*)(lds + (bufoff) + ldsw + _i * 8192), 16, 0, 0); } while (0)
; #define PG8_LDA(dst, b, h) do { _Pragma("unroll") for (int m = 0; m < 4; ++m) _Pragma("unroll") for (int k = 0; k < 2; ++k) dst[m][k] = *(const LAS bf16x8*)(lds + PG8_SA(b, h) + aoff + m * 2048 + k * 1024); } while (0)
; #define PG8_LDB(dst, b, h) do { _Pragma("unroll") for (int n = 0; n < 2; ++n) _Pragma("unroll") for (int k = 0; k < 2; ++k) dst[n][k] = *(const LAS bf16x8*)(lds + PG8_SB(b, h) + boff + n * 2048 + k * 1024); } while (0)
; #define PG8_MMA(ai, bj, At, Bt) do { __builtin_amdgcn_s_setprio(1); _Pragma("unroll") for (int m = 0; m < 4; ++m) _Pragma("unroll") for (int n = 0; n < 2; ++n) _Pragma("unroll") for (int k = 0; k < 2; ++k) \
;         acc[ai][bj][m][n] = __builtin_amdgcn_mfma_f32_16x16x32_bf16(Bt[n][k], At[m][k], acc[ai][bj][m][n], 0, 0, 0); __builtin_amdgcn_s_setprio(0); } while (0)
; #define PG8_WAIT_V(n) asm volatile("s_waitcnt vmcnt(" #n ")" ::: "memory")
; #define PG8_WAIT_L(n) asm volatile("s_waitcnt lgkmcnt(" #n ")" ::: "memory")
; #define PG8_BAR __builtin_amdgcn_s_barrier()
; #define PG8_SCHED __builtin_amdgcn_sched_barrier(0)
; template <class Epi>
; DI void gemm_phase(const int TID, const int BID, LAS unsigned char* lds, const Gemm g, const Epi& E) {
;     ...
;             PG8_LDB(B1, 1, 1); PG8_STAGE(PG8_SB(1, 0), b3);
;             PG8_BAR; PG8_WAIT_L(0); PG8_MMA(0, 1, At, B1); PG8_BAR;
;             PG8_LDA(At, 1, 1); PG8_STAGE(PG8_SA(1, 0), a3);
;             PG8_BAR; PG8_WAIT_L(0); PG8_MMA(1, 0, At, B0); PG8_BAR; PG8_SCHED;
;             PG8_STAGE(PG8_SB(1, 1), b3 + hstep);
;             PG8_WAIT_V(6); PG8_BAR; PG8_MMA(1, 1, At, B1); PG8_BAR;
;         }
	s_mov_b32 m0, s28
	v_lshl_add_u64 v[138:139], v[138:139], 0, s[92:93]
	global_load_lds_dwordx4 v[138:139], off
	v_lshl_add_u64 v[138:139], v[208:209], 0, s[92:93]
	s_mov_b32 m0, s29
	s_nop 0
	global_load_lds_dwordx4 v[138:139], off
	s_mov_b32 m0, s30
	v_lshl_add_u64 v[138:139], v[210:211], 0, s[92:93]
	global_load_lds_dwordx4 v[138:139], off
	v_lshl_add_u64 v[138:139], v[212:213], 0, s[92:93]
	s_mov_b32 m0, s31
	s_nop 0
	global_load_lds_dwordx4 v[138:139], off
	s_mov_b32 m0, s60
	v_lshl_add_u64 v[138:139], v[214:215], 0, s[92:93]
	global_load_lds_dwordx4 v[138:139], off
	v_lshl_add_u64 v[138:139], v[216:217], 0, s[92:93]
	s_mov_b32 m0, s61
	s_nop 0
	global_load_lds_dwordx4 v[138:139], off
	ds_read_b128 v[156:159], v143 offset:49152
	ds_read_b128 v[160:163], v143 offset:50176
	ds_read_b128 v[164:167], v143 offset:51200
	ds_read_b128 v[170:173], v143 offset:52224
	ds_read_b128 v[176:179], v143 offset:53248
	ds_read_b128 v[180:183], v143 offset:54272
	ds_read_b128 v[184:187], v143 offset:55296
	ds_read_b128 v[188:191], v143 offset:56320
	s_waitcnt vmcnt(8)
	s_waitcnt lgkmcnt(0)
	s_barrier
	s_setprio 1
	v_mfma_f32_16x16x32_bf16 v[60:63], v[134:137], v[156:159], v[60:63]
	v_mfma_f32_16x16x32_bf16 v[56:59], v[148:151], v[156:159], v[56:59]
	v_mfma_f32_16x16x32_bf16 v[44:47], v[134:137], v[164:167], v[44:47]
	v_mfma_f32_16x16x32_bf16 v[40:43], v[148:151], v[164:167], v[40:43]
	v_mfma_f32_16x16x32_bf16 v[28:31], v[134:137], v[176:179], v[28:31]
	v_mfma_f32_16x16x32_bf16 v[24:27], v[148:151], v[176:179], v[24:27]
	v_mfma_f32_16x16x32_bf16 v[12:15], v[134:137], v[184:187], v[12:15]
	v_mfma_f32_16x16x32_bf16 v[8:11], v[148:151], v[184:187], v[8:11]
	v_mfma_f32_16x16x32_bf16 v[60:63], v[144:147], v[160:163], v[60:63]
	v_mfma_f32_16x16x32_bf16 v[56:59], v[152:155], v[160:163], v[56:59]
	v_mfma_f32_16x16x32_bf16 v[44:47], v[144:147], v[170:173], v[44:47]
	v_mfma_f32_16x16x32_bf16 v[40:43], v[152:155], v[170:173], v[40:43]
	v_mfma_f32_16x16x32_bf16 v[28:31], v[144:147], v[180:183], v[28:31]
	v_mfma_f32_16x16x32_bf16 v[24:27], v[152:155], v[180:183], v[24:27]
	v_mfma_f32_16x16x32_bf16 v[12:15], v[144:147], v[188:191], v[12:15]
	v_mfma_f32_16x16x32_bf16 v[8:11], v[152:155], v[188:191], v[8:11]
	v_mfma_f32_16x16x32_bf16 v[52:55], v[192:195], v[156:159], v[52:55]
	v_mfma_f32_16x16x32_bf16 v[48:51], v[200:203], v[156:159], v[48:51]
	v_mfma_f32_16x16x32_bf16 v[36:39], v[192:195], v[164:167], v[36:39]
	v_mfma_f32_16x16x32_bf16 v[32:35], v[200:203], v[164:167], v[32:35]
	v_mfma_f32_16x16x32_bf16 v[20:23], v[192:195], v[176:179], v[20:23]
	v_mfma_f32_16x16x32_bf16 v[16:19], v[200:203], v[176:179], v[16:19]
	v_mfma_f32_16x16x32_bf16 v[4:7], v[192:195], v[184:187], v[4:7]
	v_mfma_f32_16x16x32_bf16 v[0:3], v[200:203], v[184:187], v[0:3]
	v_mfma_f32_16x16x32_bf16 v[52:55], v[196:199], v[160:163], v[52:55]
	v_mfma_f32_16x16x32_bf16 v[48:51], v[204:207], v[160:163], v[48:51]
	v_mfma_f32_16x16x32_bf16 v[36:39], v[196:199], v[170:173], v[36:39]
	v_mfma_f32_16x16x32_bf16 v[32:35], v[204:207], v[170:173], v[32:35]
	v_mfma_f32_16x16x32_bf16 v[20:23], v[196:199], v[180:183], v[20:23]
	v_mfma_f32_16x16x32_bf16 v[16:19], v[204:207], v[180:183], v[16:19]
	v_mfma_f32_16x16x32_bf16 v[4:7], v[196:199], v[188:191], v[4:7]
	v_mfma_f32_16x16x32_bf16 v[0:3], v[204:207], v[188:191], v[0:3]
	s_setprio 0
	s_add_u32 s54, s54, 0x100
	s_addc_u32 s55, s55, 0
	s_add_u32 s76, s76, 0x100
	s_addc_u32 s77, s77, 0
	s_cmp_ge_i32 s80, s26
	s_mov_b32 s56, s80
	s_barrier
	s_cbranch_scc0 .LBB0_164
	v_readlane_b32 s76, v255, 9
	v_readlane_b32 s77, v255, 10
	s_branch .LBB0_155

; #define PG8_STAGE(bufoff, gbase) do { _Pragma("unroll") for (int _i = 0; _i < 2; ++_i) \
;         __builtin_amdgcn_global_load_lds((const unsigned*)((const char*)(gbase) + voffA[_i]), (LAS unsigned*)(lds + (bufoff) + ldsw + _i * 8192), 16, 0, 0); } while (0)
; #define PG8_LDA(dst, b, h) do { _Pragma("unroll") for (int m = 0; m < 4; ++m) _Pragma("unroll") for (int k = 0; k < 2; ++k) dst[m][k] = *(const LAS bf16x8*)(lds + PG8_SA(b, h) + aoff + m * 2048 + k * 1024); } while (0)
; #define PG8_LDB(dst, b, h) do { _Pragma("unroll") for (int n = 0; n < 2; ++n) _Pragma("unroll") for (int k = 0; k < 2; ++k) dst[n][k] = *(const LAS bf16x8*)(lds + PG8_SB(b, h) + boff + n * 2048 + k * 1024); } while (0)
; #define PG8_MMA(ai, bj, At, Bt) do { __builtin_amdgcn_s_setprio(1); _Pragma("unroll") for (int m = 0; m < 4; ++m) _Pragma("unroll") for (int n = 0; n < 2; ++n) _Pragma("unroll") for (int k = 0; k < 2; ++k) \
;         acc[ai][bj][m][n] = __builtin_amdgcn_mfma_f32_16x16x32_bf16(Bt[n][k], At[m][k], acc[ai][bj][m][n], 0, 0, 0); __builtin_amdgcn_s_setprio(0); } while (0)
; #define PG8_WAIT_L(n) asm volatile("s_waitcnt lgkmcnt(" #n ")" ::: "memory")
; #define PG8_BAR __builtin_amdgcn_s_barrier()
; #define PG8_SCHED __builtin_amdgcn_sched_barrier(0)
; template <class Epi>
; DI void gemm_phase(const int TID, const int BID, LAS unsigned char* lds, const Gemm g, const Epi& E) {
;     ...
;             const bool last = (t == nt - 2);
;             const char* a1 = cA + (size_t)(t + 1) * kstep;
;             const char* a2 = last ? nA : cA + (size_t)(t + 2) * kstep; const char* b2 = last ? nB : cB + (size_t)(t + 2) * kstep;
;             const char* a3 = a2 + kstep; const char* b3 = b2 + kstep;
;             PG8_LDB(B0, 0, 0); PG8_SCHED; PG8_LDA(At, 0, 0); PG8_STAGE(PG8_SA(1, 1), a1 + hstep);
;             PG8_WAIT_L(8); PG8_BAR; PG8_WAIT_L(0); PG8_MMA(0, 0, At, B0); PG8_BAR; PG8_SCHED;
;             PG8_LDB(B1, 0, 1); PG8_STAGE(PG8_SB(0, 0), b2);
;             PG8_BAR; PG8_WAIT_L(0); PG8_MMA(0, 1, At, B1); PG8_BAR;
;             PG8_LDA(At, 0, 1); PG8_STAGE(PG8_SA(0, 0), a2);
;             PG8_BAR; PG8_WAIT_L(0); PG8_MMA(1, 0, At, B0); PG8_BAR; PG8_SCHED;
;             PG8_STAGE(PG8_SB(0, 1), b2 + hstep);
.LBB0_230:
	s_add_i32 s58, s54, 2
	s_add_u32 s56, s52, 0x80
	s_addc_u32 s55, s53, 0
	s_cmp_eq_u32 vcc_lo, s54
	s_cselect_b32 s54, s12, s56
	s_cselect_b32 s55, s13, s55
	s_cselect_b32 s57, s1, s29
	s_cselect_b32 s56, s0, vcc_hi
	v_lshl_add_u64 v[186:187], s[52:53], 0, v[178:179]
	s_add_i32 m0, s21, 0xc000
	global_load_lds_dwordx4 v[186:187], off
	v_lshl_add_u64 v[186:187], s[52:53], 0, v[180:181]
	s_add_i32 m0, s21, 0xe000
	s_nop 0
	global_load_lds_dwordx4 v[186:187], off
	v_add_u32_e32 v140, s18, v246
	ds_read_b128 v[128:131], v140
	ds_read_b128 v[132:135], v140 offset:1024
	ds_read_b128 v[136:139], v140 offset:2048
	ds_read_b128 v[140:143], v140 offset:3072
	ds_read_b128 v[144:147], v248
	ds_read_b128 v[148:151], v248 offset:1024
	ds_read_b128 v[152:155], v248 offset:2048
	ds_read_b128 v[156:159], v248 offset:3072
	ds_read_b128 v[160:163], v248 offset:4096
	ds_read_b128 v[164:167], v248 offset:5120
	ds_read_b128 v[170:173], v248 offset:6144
	ds_read_b128 v[182:185], v248 offset:7168
	v_add_u32_e32 v198, s23, v246
	ds_read_b128 v[186:189], v198
	ds_read_b128 v[190:193], v198 offset:1024
	ds_read_b128 v[194:197], v198 offset:2048
	ds_read_b128 v[198:201], v198 offset:3072
	s_waitcnt vmcnt(8)
	s_waitcnt lgkmcnt(0)
	s_barrier
	s_setprio 1
	v_mfma_f32_16x16x32_bf16 v[124:127], v[128:131], v[144:147], v[124:127]
	v_mfma_f32_16x16x32_bf16 v[120:123], v[136:139], v[144:147], v[120:123]
	v_mfma_f32_16x16x32_bf16 v[108:111], v[128:131], v[152:155], v[108:111]
	v_mfma_f32_16x16x32_bf16 v[104:107], v[136:139], v[152:155], v[104:107]
	v_mfma_f32_16x16x32_bf16 v[92:95], v[128:131], v[160:163], v[92:95]
	v_mfma_f32_16x16x32_bf16 v[88:91], v[136:139], v[160:163], v[88:91]
	v_mfma_f32_16x16x32_bf16 v[76:79], v[128:131], v[170:173], v[76:79]
	v_mfma_f32_16x16x32_bf16 v[72:75], v[136:139], v[170:173], v[72:75]
	v_mfma_f32_16x16x32_bf16 v[124:127], v[132:135], v[148:151], v[124:127]
	v_mfma_f32_16x16x32_bf16 v[120:123], v[140:143], v[148:151], v[120:123]
	v_mfma_f32_16x16x32_bf16 v[108:111], v[132:135], v[156:159], v[108:111]
	v_mfma_f32_16x16x32_bf16 v[104:107], v[140:143], v[156:159], v[104:107]
	v_mfma_f32_16x16x32_bf16 v[92:95], v[132:135], v[164:167], v[92:95]
	v_mfma_f32_16x16x32_bf16 v[88:91], v[140:143], v[164:167], v[88:91]
	v_mfma_f32_16x16x32_bf16 v[76:79], v[132:135], v[182:185], v[76:79]
	v_mfma_f32_16x16x32_bf16 v[72:75], v[140:143], v[182:185], v[72:75]
	v_mfma_f32_16x16x32_bf16 v[116:119], v[186:189], v[144:147], v[116:119]
	v_mfma_f32_16x16x32_bf16 v[112:115], v[194:197], v[144:147], v[112:115]
	v_mfma_f32_16x16x32_bf16 v[100:103], v[186:189], v[152:155], v[100:103]
	v_mfma_f32_16x16x32_bf16 v[96:99], v[194:197], v[152:155], v[96:99]
	v_mfma_f32_16x16x32_bf16 v[84:87], v[186:189], v[160:163], v[84:87]
	v_mfma_f32_16x16x32_bf16 v[80:83], v[194:197], v[160:163], v[80:83]
	v_mfma_f32_16x16x32_bf16 v[68:71], v[186:189], v[170:173], v[68:71]
	v_mfma_f32_16x16x32_bf16 v[64:67], v[194:197], v[170:173], v[64:67]
	v_mfma_f32_16x16x32_bf16 v[116:119], v[190:193], v[148:151], v[116:119]
	v_mfma_f32_16x16x32_bf16 v[112:115], v[198:201], v[148:151], v[112:115]
	v_mfma_f32_16x16x32_bf16 v[100:103], v[190:193], v[156:159], v[100:103]
	v_mfma_f32_16x16x32_bf16 v[96:99], v[198:201], v[156:159], v[96:99]
	v_mfma_f32_16x16x32_bf16 v[84:87], v[190:193], v[164:167], v[84:87]
	v_mfma_f32_16x16x32_bf16 v[80:83], v[198:201], v[164:167], v[80:83]
	v_mfma_f32_16x16x32_bf16 v[68:71], v[190:193], v[182:185], v[68:71]
	v_mfma_f32_16x16x32_bf16 v[64:67], v[198:201], v[182:185], v[64:67]
	s_setprio 0
	s_barrier
	s_mov_b32 m0, s19
	v_lshl_add_u64 v[202:203], s[56:57], 0, v[168:169]
	global_load_lds_dwordx4 v[202:203], off
	v_lshl_add_u64 v[204:205], s[56:57], 0, v[176:177]
	s_mov_b32 m0, s20
	s_nop 0
	global_load_lds_dwordx4 v[204:205], off
	s_mov_b32 m0, s21
	v_lshl_add_u64 v[206:207], s[54:55], 0, v[168:169]
	global_load_lds_dwordx4 v[206:207], off
	v_lshl_add_u64 v[208:209], s[54:55], 0, v[176:177]
	s_mov_b32 m0, s22
	s_nop 0
	global_load_lds_dwordx4 v[208:209], off
	s_add_u32 s56, s56, s2
	s_addc_u32 s57, s57, s3
	s_mov_b32 m0, s24
	v_lshl_add_u64 v[210:211], s[56:57], 0, v[168:169]
	global_load_lds_dwordx4 v[210:211], off
	v_lshl_add_u64 v[212:213], s[56:57], 0, v[176:177]
	s_mov_b32 m0, s25
	s_nop 0
	global_load_lds_dwordx4 v[212:213], off
	ds_read_b128 v[144:147], v248 offset:16384
	ds_read_b128 v[148:151], v248 offset:17408
	ds_read_b128 v[152:155], v248 offset:18432
	ds_read_b128 v[156:159], v248 offset:19456
	ds_read_b128 v[160:163], v248 offset:20480
	ds_read_b128 v[164:167], v248 offset:21504
	ds_read_b128 v[170:173], v248 offset:22528
	ds_read_b128 v[182:185], v248 offset:23552
	s_waitcnt vmcnt(8)
	s_waitcnt lgkmcnt(0)
	s_barrier
; #define PG8_STAGE(bufoff, gbase) do { _Pragma("unroll") for (int _i = 0; _i < 2; ++_i) \
;         __builtin_amdgcn_global_load_lds((const unsigned*)((const char*)(gbase) + voffA[_i]), (LAS unsigned*)(lds + (bufoff) + ldsw + _i * 8192), 16, 0, 0); } while (0)
; #define PG8_LDA(dst, b, h) do { _Pragma("unroll") for (int m = 0; m < 4; ++m) _Pragma("unroll") for (int k = 0; k < 2; ++k) dst[m][k] = *(const LAS bf16x8*)(lds + PG8_SA(b, h) + aoff + m * 2048 + k * 1024); } while (0)
; #define PG8_LDB(dst, b, h) do { _Pragma("unroll") for (int n = 0; n < 2; ++n) _Pragma("unroll") for (int k = 0; k < 2; ++k) dst[n][k] = *(const LAS bf16x8*)(lds + PG8_SB(b, h) + boff + n * 2048 + k * 1024); } while (0)
; #define PG8_MMA(ai, bj, At, Bt) do { __builtin_amdgcn_s_setprio(1); _Pragma("unroll") for (int m = 0; m < 4; ++m) _Pragma("unroll") for (int n = 0; n < 2; ++n) _Pragma("unroll") for (int k = 0; k < 2; ++k) \
;         acc[ai][bj][m][n] = __builtin_amdgcn_mfma_f32_16x16x32_bf16(Bt[n][k], At[m][k], acc[ai][bj][m][n], 0, 0, 0); __builtin_amdgcn_s_setprio(0); } while (0)
; #define PG8_WAIT_V(n) asm volatile("s_waitcnt vmcnt(" #n ")" ::: "memory")
; #define PG8_WAIT_L(n) asm volatile("s_waitcnt lgkmcnt(" #n ")" ::: "memory")
; #define PG8_BAR __builtin_amdgcn_s_barrier()
; #define PG8_SCHED __builtin_amdgcn_sched_barrier(0)
; template <class Epi>
; DI void gemm_phase(const int TID, const int BID, LAS unsigned char* lds, const Gemm g, const Epi& E) {
;     ...
;             PG8_BAR; PG8_WAIT_L(0); PG8_MMA(0, 1, At, B1); PG8_BAR;
;             PG8_LDA(At, 0, 1); PG8_STAGE(PG8_SA(0, 0), a2);
;             PG8_BAR; PG8_WAIT_L(0); PG8_MMA(1, 0, At, B0); PG8_BAR; PG8_SCHED;
;             PG8_STAGE(PG8_SB(0, 1), b2 + hstep);
;             PG8_WAIT_V(6); PG8_BAR; PG8_MMA(1, 1, At, B1); PG8_BAR;
;             PG8_LDB(B0, 1, 0); PG8_SCHED; PG8_LDA(At, 1, 0); PG8_STAGE(PG8_SA(0, 1), a2 + hstep);
;             PG8_WAIT_L(8); PG8_BAR; PG8_WAIT_L(0); PG8_MMA(0, 0, At, B0); PG8_BAR; PG8_SCHED;
;             PG8_LDB(B1, 1, 1); PG8_STAGE(PG8_SB(1, 0), b3);
	s_setprio 1
	v_mfma_f32_16x16x32_bf16 v[60:63], v[128:131], v[144:147], v[60:63]
	v_mfma_f32_16x16x32_bf16 v[56:59], v[136:139], v[144:147], v[56:59]
	v_mfma_f32_16x16x32_bf16 v[44:47], v[128:131], v[152:155], v[44:47]
	v_mfma_f32_16x16x32_bf16 v[40:43], v[136:139], v[152:155], v[40:43]
	v_mfma_f32_16x16x32_bf16 v[28:31], v[128:131], v[160:163], v[28:31]
	v_mfma_f32_16x16x32_bf16 v[24:27], v[136:139], v[160:163], v[24:27]
	v_mfma_f32_16x16x32_bf16 v[12:15], v[128:131], v[170:173], v[12:15]
	v_mfma_f32_16x16x32_bf16 v[8:11], v[136:139], v[170:173], v[8:11]
	v_mfma_f32_16x16x32_bf16 v[60:63], v[132:135], v[148:151], v[60:63]
	v_mfma_f32_16x16x32_bf16 v[56:59], v[140:143], v[148:151], v[56:59]
	v_mfma_f32_16x16x32_bf16 v[44:47], v[132:135], v[156:159], v[44:47]
	v_mfma_f32_16x16x32_bf16 v[40:43], v[140:143], v[156:159], v[40:43]
	v_mfma_f32_16x16x32_bf16 v[28:31], v[132:135], v[164:167], v[28:31]
	v_mfma_f32_16x16x32_bf16 v[24:27], v[140:143], v[164:167], v[24:27]
	v_mfma_f32_16x16x32_bf16 v[12:15], v[132:135], v[182:185], v[12:15]
	v_mfma_f32_16x16x32_bf16 v[8:11], v[140:143], v[182:185], v[8:11]
	v_mfma_f32_16x16x32_bf16 v[52:55], v[186:189], v[144:147], v[52:55]
	v_mfma_f32_16x16x32_bf16 v[48:51], v[194:197], v[144:147], v[48:51]
	v_mfma_f32_16x16x32_bf16 v[36:39], v[186:189], v[152:155], v[36:39]
	v_mfma_f32_16x16x32_bf16 v[32:35], v[194:197], v[152:155], v[32:35]
	v_mfma_f32_16x16x32_bf16 v[20:23], v[186:189], v[160:163], v[20:23]
	v_mfma_f32_16x16x32_bf16 v[16:19], v[194:197], v[160:163], v[16:19]
	v_mfma_f32_16x16x32_bf16 v[4:7], v[186:189], v[170:173], v[4:7]
	v_mfma_f32_16x16x32_bf16 v[0:3], v[194:197], v[170:173], v[0:3]
	v_mfma_f32_16x16x32_bf16 v[52:55], v[190:193], v[148:151], v[52:55]
	v_mfma_f32_16x16x32_bf16 v[48:51], v[198:201], v[148:151], v[48:51]
	v_mfma_f32_16x16x32_bf16 v[36:39], v[190:193], v[156:159], v[36:39]
	v_mfma_f32_16x16x32_bf16 v[32:35], v[198:201], v[156:159], v[32:35]
	v_mfma_f32_16x16x32_bf16 v[20:23], v[190:193], v[164:167], v[20:23]
	v_mfma_f32_16x16x32_bf16 v[16:19], v[198:201], v[164:167], v[16:19]
	v_mfma_f32_16x16x32_bf16 v[4:7], v[190:193], v[182:185], v[4:7]
	v_mfma_f32_16x16x32_bf16 v[0:3], v[198:201], v[182:185], v[0:3]
	s_setprio 0
	s_barrier
	s_add_u32 s54, s54, s2
	s_addc_u32 s55, s55, s3
	s_mov_b32 m0, s26
	v_lshl_add_u64 v[186:187], s[54:55], 0, v[168:169]
	global_load_lds_dwordx4 v[186:187], off
	v_lshl_add_u64 v[186:187], s[54:55], 0, v[176:177]
	s_mov_b32 m0, s27
	s_nop 0
	global_load_lds_dwordx4 v[186:187], off
	v_add_u32_e32 v140, s31, v246
	ds_read_b128 v[128:131], v140
	ds_read_b128 v[132:135], v140 offset:1024
	ds_read_b128 v[136:139], v140 offset:2048
	ds_read_b128 v[140:143], v140 offset:3072
	ds_read_b128 v[144:147], v248 offset:32768
	ds_read_b128 v[148:151], v248 offset:33792
	ds_read_b128 v[152:155], v248 offset:34816
	ds_read_b128 v[156:159], v248 offset:35840
	ds_read_b128 v[160:163], v248 offset:36864
	ds_read_b128 v[164:167], v248 offset:37888
	ds_read_b128 v[170:173], v248 offset:38912
	ds_read_b128 v[182:185], v248 offset:39936
	v_add_u32_e32 v198, s65, v246
	ds_read_b128 v[186:189], v198
	ds_read_b128 v[190:193], v198 offset:1024
	ds_read_b128 v[194:197], v198 offset:2048
	ds_read_b128 v[198:201], v198 offset:3072
	s_waitcnt vmcnt(8)
	s_waitcnt lgkmcnt(0)
	s_barrier
	s_setprio 1
	v_mfma_f32_16x16x32_bf16 v[124:127], v[128:131], v[144:147], v[124:127]
	v_mfma_f32_16x16x32_bf16 v[120:123], v[136:139], v[144:147], v[120:123]
	v_mfma_f32_16x16x32_bf16 v[108:111], v[128:131], v[152:155], v[108:111]
	v_mfma_f32_16x16x32_bf16 v[104:107], v[136:139], v[152:155], v[104:107]
	v_mfma_f32_16x16x32_bf16 v[92:95], v[128:131], v[160:163], v[92:95]
	v_mfma_f32_16x16x32_bf16 v[88:91], v[136:139], v[160:163], v[88:91]
	v_mfma_f32_16x16x32_bf16 v[76:79], v[128:131], v[170:173], v[76:79]
	v_mfma_f32_16x16x32_bf16 v[72:75], v[136:139], v[170:173], v[72:75]
	v_mfma_f32_16x16x32_bf16 v[124:127], v[132:135], v[148:151], v[124:127]
	v_mfma_f32_16x16x32_bf16 v[120:123], v[140:143], v[148:151], v[120:123]
	v_mfma_f32_16x16x32_bf16 v[108:111], v[132:135], v[156:159], v[108:111]
	v_mfma_f32_16x16x32_bf16 v[104:107], v[140:143], v[156:159], v[104:107]
	v_mfma_f32_16x16x32_bf16 v[92:95], v[132:135], v[164:167], v[92:95]
	v_mfma_f32_16x16x32_bf16 v[88:91], v[140:143], v[164:167], v[88:91]
	v_mfma_f32_16x16x32_bf16 v[76:79], v[132:135], v[182:185], v[76:79]
	v_mfma_f32_16x16x32_bf16 v[72:75], v[140:143], v[182:185], v[72:75]
	v_mfma_f32_16x16x32_bf16 v[116:119], v[186:189], v[144:147], v[116:119]
	v_mfma_f32_16x16x32_bf16 v[112:115], v[194:197], v[144:147], v[112:115]
	v_mfma_f32_16x16x32_bf16 v[100:103], v[186:189], v[152:155], v[100:103]
	v_mfma_f32_16x16x32_bf16 v[96:99], v[194:197], v[152:155], v[96:99]
	v_mfma_f32_16x16x32_bf16 v[84:87], v[186:189], v[160:163], v[84:87]
	v_mfma_f32_16x16x32_bf16 v[80:83], v[194:197], v[160:163], v[80:83]
	v_mfma_f32_16x16x32_bf16 v[68:71], v[186:189], v[170:173], v[68:71]
	v_mfma_f32_16x16x32_bf16 v[64:67], v[194:197], v[170:173], v[64:67]
	v_mfma_f32_16x16x32_bf16 v[116:119], v[190:193], v[148:151], v[116:119]
	v_mfma_f32_16x16x32_bf16 v[112:115], v[198:201], v[148:151], v[112:115]
	v_mfma_f32_16x16x32_bf16 v[100:103], v[190:193], v[156:159], v[100:103]
	v_mfma_f32_16x16x32_bf16 v[96:99], v[198:201], v[156:159], v[96:99]
	v_mfma_f32_16x16x32_bf16 v[84:87], v[190:193], v[164:167], v[84:87]
	v_mfma_f32_16x16x32_bf16 v[80:83], v[198:201], v[164:167], v[80:83]
	v_mfma_f32_16x16x32_bf16 v[68:71], v[190:193], v[182:185], v[68:71]
	v_mfma_f32_16x16x32_bf16 v[64:67], v[198:201], v[182:185], v[64:67]
	s_setprio 0
	s_barrier
; #define PG8_STAGE(bufoff, gbase) do { _Pragma("unroll") for (int _i = 0; _i < 2; ++_i) \
;         __builtin_amdgcn_global_load_lds((const unsigned*)((const char*)(gbase) + voffA[_i]), (LAS unsigned*)(lds + (bufoff) + ldsw + _i * 8192), 16, 0, 0); } while (0)
; #define PG8_LDA(dst, b, h) do { _Pragma("unroll") for (int m = 0; m < 4; ++m) _Pragma("unroll") for (int k = 0; k < 2; ++k) dst[m][k] = *(const LAS bf16x8*)(lds + PG8_SA(b, h) + aoff + m * 2048 + k * 1024); } while (0)
; #define PG8_LDB(dst, b, h) do { _Pragma("unroll") for (int n = 0; n < 2; ++n) _Pragma("unroll") for (int k = 0; k < 2; ++k) dst[n][k] = *(const LAS bf16x8*)(lds + PG8_SB(b, h) + boff + n * 2048 + k * 1024); } while (0)
; #define PG8_MMA(ai, bj, At, Bt) do { __builtin_amdgcn_s_setprio(1); _Pragma("unroll") for (int m = 0; m < 4; ++m) _Pragma("unroll") for (int n = 0; n < 2; ++n) _Pragma("unroll") for (int k = 0; k < 2; ++k) \
;         acc[ai][bj][m][n] = __builtin_amdgcn_mfma_f32_16x16x32_bf16(Bt[n][k], At[m][k], acc[ai][bj][m][n], 0, 0, 0); __builtin_amdgcn_s_setprio(0); } while (0)
; #define PG8_WAIT_V(n) asm volatile("s_waitcnt vmcnt(" #n ")" ::: "memory")
; #define PG8_WAIT_L(n) asm volatile("s_waitcnt lgkmcnt(" #n ")" ::: "memory")
; #define PG8_BAR __builtin_amdgcn_s_barrier()
; #define PG8_SCHED __builtin_amdgcn_sched_barrier(0)
; template <class Epi>
; DI void gemm_phase(const int TID, const int BID, LAS unsigned char* lds, const Gemm g, const Epi& E) {
;     ...
;             PG8_LDB(B1, 1, 1); PG8_STAGE(PG8_SB(1, 0), b3);
;             PG8_BAR; PG8_WAIT_L(0); PG8_MMA(0, 1, At, B1); PG8_BAR;
;             PG8_LDA(At, 1, 1); PG8_STAGE(PG8_SA(1, 0), a3);
;             PG8_BAR; PG8_WAIT_L(0); PG8_MMA(1, 0, At, B0); PG8_BAR; PG8_SCHED;
;             PG8_STAGE(PG8_SB(1, 1), b3 + hstep);
;             PG8_WAIT_V(6); PG8_BAR; PG8_MMA(1, 1, At, B1); PG8_BAR;
;         }
	s_mov_b32 m0, s33
	v_lshl_add_u64 v[202:203], v[202:203], 0, s[92:93]
	global_load_lds_dwordx4 v[202:203], off
	v_lshl_add_u64 v[202:203], v[204:205], 0, s[92:93]
	s_mov_b32 m0, s60
	s_nop 0
	global_load_lds_dwordx4 v[202:203], off
	s_mov_b32 m0, s61
	v_lshl_add_u64 v[202:203], v[206:207], 0, s[92:93]
	global_load_lds_dwordx4 v[202:203], off
	v_lshl_add_u64 v[202:203], v[208:209], 0, s[92:93]
	s_mov_b32 m0, s64
	s_nop 0
	global_load_lds_dwordx4 v[202:203], off
	s_mov_b32 m0, s66
	v_lshl_add_u64 v[202:203], v[210:211], 0, s[92:93]
	global_load_lds_dwordx4 v[202:203], off
	v_lshl_add_u64 v[202:203], v[212:213], 0, s[92:93]
	s_mov_b32 m0, s67
	s_nop 0
	global_load_lds_dwordx4 v[202:203], off
	ds_read_b128 v[144:147], v248 offset:49152
	ds_read_b128 v[148:151], v248 offset:50176
	ds_read_b128 v[152:155], v248 offset:51200
	ds_read_b128 v[156:159], v248 offset:52224
	ds_read_b128 v[160:163], v248 offset:53248
	ds_read_b128 v[164:167], v248 offset:54272
	ds_read_b128 v[170:173], v248 offset:55296
	ds_read_b128 v[182:185], v248 offset:56320
	s_waitcnt vmcnt(8)
	s_waitcnt lgkmcnt(0)
	s_barrier
	s_setprio 1
	v_mfma_f32_16x16x32_bf16 v[60:63], v[128:131], v[144:147], v[60:63]
	v_mfma_f32_16x16x32_bf16 v[56:59], v[136:139], v[144:147], v[56:59]
	v_mfma_f32_16x16x32_bf16 v[44:47], v[128:131], v[152:155], v[44:47]
	v_mfma_f32_16x16x32_bf16 v[40:43], v[136:139], v[152:155], v[40:43]
	v_mfma_f32_16x16x32_bf16 v[28:31], v[128:131], v[160:163], v[28:31]
	v_mfma_f32_16x16x32_bf16 v[24:27], v[136:139], v[160:163], v[24:27]
	v_mfma_f32_16x16x32_bf16 v[12:15], v[128:131], v[170:173], v[12:15]
	v_mfma_f32_16x16x32_bf16 v[8:11], v[136:139], v[170:173], v[8:11]
	v_mfma_f32_16x16x32_bf16 v[60:63], v[132:135], v[148:151], v[60:63]
	v_mfma_f32_16x16x32_bf16 v[56:59], v[140:143], v[148:151], v[56:59]
	v_mfma_f32_16x16x32_bf16 v[44:47], v[132:135], v[156:159], v[44:47]
	v_mfma_f32_16x16x32_bf16 v[40:43], v[140:143], v[156:159], v[40:43]
	v_mfma_f32_16x16x32_bf16 v[28:31], v[132:135], v[164:167], v[28:31]
	v_mfma_f32_16x16x32_bf16 v[24:27], v[140:143], v[164:167], v[24:27]
	v_mfma_f32_16x16x32_bf16 v[12:15], v[132:135], v[182:185], v[12:15]
	v_mfma_f32_16x16x32_bf16 v[8:11], v[140:143], v[182:185], v[8:11]
	v_mfma_f32_16x16x32_bf16 v[52:55], v[186:189], v[144:147], v[52:55]
	v_mfma_f32_16x16x32_bf16 v[48:51], v[194:197], v[144:147], v[48:51]
	v_mfma_f32_16x16x32_bf16 v[36:39], v[186:189], v[152:155], v[36:39]
	v_mfma_f32_16x16x32_bf16 v[32:35], v[194:197], v[152:155], v[32:35]
	v_mfma_f32_16x16x32_bf16 v[20:23], v[186:189], v[160:163], v[20:23]
	v_mfma_f32_16x16x32_bf16 v[16:19], v[194:197], v[160:163], v[16:19]
	v_mfma_f32_16x16x32_bf16 v[4:7], v[186:189], v[170:173], v[4:7]
	v_mfma_f32_16x16x32_bf16 v[0:3], v[194:197], v[170:173], v[0:3]
	v_mfma_f32_16x16x32_bf16 v[52:55], v[190:193], v[148:151], v[52:55]
	v_mfma_f32_16x16x32_bf16 v[48:51], v[198:201], v[148:151], v[48:51]
	v_mfma_f32_16x16x32_bf16 v[36:39], v[190:193], v[156:159], v[36:39]
	v_mfma_f32_16x16x32_bf16 v[32:35], v[198:201], v[156:159], v[32:35]
	v_mfma_f32_16x16x32_bf16 v[20:23], v[190:193], v[164:167], v[20:23]
	v_mfma_f32_16x16x32_bf16 v[16:19], v[198:201], v[164:167], v[16:19]
	v_mfma_f32_16x16x32_bf16 v[4:7], v[190:193], v[182:185], v[4:7]
	v_mfma_f32_16x16x32_bf16 v[0:3], v[198:201], v[182:185], v[0:3]
	s_setprio 0
	s_add_u32 s52, s52, 0x100
	s_addc_u32 s53, s53, 0
	s_add_u32 vcc_hi, vcc_hi, 0x100
	s_addc_u32 s29, s29, 0
	s_cmp_ge_i32 s58, s17
	s_mov_b32 s54, s58
	s_barrier
	s_cbranch_scc0 .LBB0_230
	s_branch .LBB0_234

; #define PG8_STAGE(bufoff, gbase) do { _Pragma("unroll") for (int _i = 0; _i < 2; ++_i) \
;         __builtin_amdgcn_global_load_lds((const unsigned*)((const char*)(gbase) + voffA[_i]), (LAS unsigned*)(lds + (bufoff) + ldsw + _i * 8192), 16, 0, 0); } while (0)
; #define PG8_LDA(dst, b, h) do { _Pragma("unroll") for (int m = 0; m < 4; ++m) _Pragma("unroll") for (int k = 0; k < 2; ++k) dst[m][k] = *(const LAS bf16x8*)(lds + PG8_SA(b, h) + aoff + m * 2048 + k * 1024); } while (0)
; #define PG8_LDB(dst, b, h) do { _Pragma("unroll") for (int n = 0; n < 2; ++n) _Pragma("unroll") for (int k = 0; k < 2; ++k) dst[n][k] = *(const LAS bf16x8*)(lds + PG8_SB(b, h) + boff + n * 2048 + k * 1024); } while (0)
; #define PG8_MMA(ai, bj, At, Bt) do { __builtin_amdgcn_s_setprio(1); _Pragma("unroll") for (int m = 0; m < 4; ++m) _Pragma("unroll") for (int n = 0; n < 2; ++n) _Pragma("unroll") for (int k = 0; k < 2; ++k) \
;         acc[ai][bj][m][n] = __builtin_amdgcn_mfma_f32_16x16x32_bf16(Bt[n][k], At[m][k], acc[ai][bj][m][n], 0, 0, 0); __builtin_amdgcn_s_setprio(0); } while (0)
; #define PG8_WAIT_L(n) asm volatile("s_waitcnt lgkmcnt(" #n ")" ::: "memory")
; #define PG8_BAR __builtin_amdgcn_s_barrier()
; #define PG8_SCHED __builtin_amdgcn_sched_barrier(0)
; template <class Epi>
; DI void gemm_phase(const int TID, const int BID, LAS unsigned char* lds, const Gemm g, const Epi& E) {
;     ...
;             const bool last = (t == nt - 2);
;             const char* a1 = cA + (size_t)(t + 1) * kstep;
;             const char* a2 = last ? nA : cA + (size_t)(t + 2) * kstep; const char* b2 = last ? nB : cB + (size_t)(t + 2) * kstep;
;             const char* a3 = a2 + kstep; const char* b3 = b2 + kstep;
;             PG8_LDB(B0, 0, 0); PG8_SCHED; PG8_LDA(At, 0, 0); PG8_STAGE(PG8_SA(1, 1), a1 + hstep);
;             PG8_WAIT_L(8); PG8_BAR; PG8_WAIT_L(0); PG8_MMA(0, 0, At, B0); PG8_BAR; PG8_SCHED;
;             PG8_LDB(B1, 0, 1); PG8_STAGE(PG8_SB(0, 0), b2);
;             PG8_BAR; PG8_WAIT_L(0); PG8_MMA(0, 1, At, B1); PG8_BAR;
;             PG8_LDA(At, 0, 1); PG8_STAGE(PG8_SA(0, 0), a2);
;             PG8_BAR; PG8_WAIT_L(0); PG8_MMA(1, 0, At, B0); PG8_BAR; PG8_SCHED;
;             PG8_STAGE(PG8_SB(0, 1), b2 + hstep);
.LBB0_271:
	s_add_i32 vcc_hi, s12, 2
	s_add_u32 s52, s0, 0x80
	s_addc_u32 s13, s1, 0
	s_cmp_eq_u32 s54, s12
	s_cselect_b32 s12, s8, s52
	s_cselect_b32 s13, s9, s13
	s_cselect_b32 s53, s11, vcc_lo
	s_cselect_b32 s52, s10, s55
	v_lshl_add_u64 v[170:171], s[0:1], 0, v[164:165]
	s_add_i32 m0, s21, 0xc000
	global_load_lds_dwordx4 v[170:171], off
	v_lshl_add_u64 v[170:171], s[0:1], 0, v[166:167]
	s_add_i32 m0, s21, 0xe000
	s_nop 0
	global_load_lds_dwordx4 v[170:171], off
	v_add_u32_e32 v140, s18, v222
	ds_read_b128 v[128:131], v140
	ds_read_b128 v[132:135], v140 offset:1024
	ds_read_b128 v[136:139], v140 offset:2048
	ds_read_b128 v[140:143], v140 offset:3072
	ds_read_b128 v[144:147], v224
	ds_read_b128 v[148:151], v224 offset:1024
	ds_read_b128 v[152:155], v224 offset:2048
	ds_read_b128 v[156:159], v224 offset:3072
	ds_read_b128 v[176:179], v224 offset:4096
	ds_read_b128 v[180:183], v224 offset:5120
	ds_read_b128 v[184:187], v224 offset:6144
	ds_read_b128 v[188:191], v224 offset:7168
	v_add_u32_e32 v168, s23, v222
	ds_read_b128 v[192:195], v168
	ds_read_b128 v[196:199], v168 offset:1024
	ds_read_b128 v[200:203], v168 offset:2048
	ds_read_b128 v[204:207], v168 offset:3072
	s_waitcnt vmcnt(8)
	s_waitcnt lgkmcnt(0)
	s_barrier
	s_setprio 1
	v_mfma_f32_16x16x32_bf16 v[124:127], v[128:131], v[144:147], v[124:127]
	v_mfma_f32_16x16x32_bf16 v[120:123], v[136:139], v[144:147], v[120:123]
	v_mfma_f32_16x16x32_bf16 v[108:111], v[128:131], v[152:155], v[108:111]
	v_mfma_f32_16x16x32_bf16 v[104:107], v[136:139], v[152:155], v[104:107]
	v_mfma_f32_16x16x32_bf16 v[92:95], v[128:131], v[176:179], v[92:95]
	v_mfma_f32_16x16x32_bf16 v[88:91], v[136:139], v[176:179], v[88:91]
	v_mfma_f32_16x16x32_bf16 v[76:79], v[128:131], v[184:187], v[76:79]
	v_mfma_f32_16x16x32_bf16 v[72:75], v[136:139], v[184:187], v[72:75]
	v_mfma_f32_16x16x32_bf16 v[124:127], v[132:135], v[148:151], v[124:127]
	v_mfma_f32_16x16x32_bf16 v[120:123], v[140:143], v[148:151], v[120:123]
	v_mfma_f32_16x16x32_bf16 v[108:111], v[132:135], v[156:159], v[108:111]
	v_mfma_f32_16x16x32_bf16 v[104:107], v[140:143], v[156:159], v[104:107]
	v_mfma_f32_16x16x32_bf16 v[92:95], v[132:135], v[180:183], v[92:95]
	v_mfma_f32_16x16x32_bf16 v[88:91], v[140:143], v[180:183], v[88:91]
	v_mfma_f32_16x16x32_bf16 v[76:79], v[132:135], v[188:191], v[76:79]
	v_mfma_f32_16x16x32_bf16 v[72:75], v[140:143], v[188:191], v[72:75]
	v_mfma_f32_16x16x32_bf16 v[116:119], v[192:195], v[144:147], v[116:119]
	v_mfma_f32_16x16x32_bf16 v[112:115], v[200:203], v[144:147], v[112:115]
	v_mfma_f32_16x16x32_bf16 v[100:103], v[192:195], v[152:155], v[100:103]
	v_mfma_f32_16x16x32_bf16 v[96:99], v[200:203], v[152:155], v[96:99]
	v_mfma_f32_16x16x32_bf16 v[84:87], v[192:195], v[176:179], v[84:87]
	v_mfma_f32_16x16x32_bf16 v[80:83], v[200:203], v[176:179], v[80:83]
	v_mfma_f32_16x16x32_bf16 v[68:71], v[192:195], v[184:187], v[68:71]
	v_mfma_f32_16x16x32_bf16 v[64:67], v[200:203], v[184:187], v[64:67]
	v_mfma_f32_16x16x32_bf16 v[116:119], v[196:199], v[148:151], v[116:119]
	v_mfma_f32_16x16x32_bf16 v[112:115], v[204:207], v[148:151], v[112:115]
	v_mfma_f32_16x16x32_bf16 v[100:103], v[196:199], v[156:159], v[100:103]
	v_mfma_f32_16x16x32_bf16 v[96:99], v[204:207], v[156:159], v[96:99]
	v_mfma_f32_16x16x32_bf16 v[84:87], v[196:199], v[180:183], v[84:87]
	v_mfma_f32_16x16x32_bf16 v[80:83], v[204:207], v[180:183], v[80:83]
	v_mfma_f32_16x16x32_bf16 v[68:71], v[196:199], v[188:191], v[68:71]
	v_mfma_f32_16x16x32_bf16 v[64:67], v[204:207], v[188:191], v[64:67]
	s_setprio 0
	s_barrier
	s_mov_b32 m0, s19
	v_lshl_add_u64 v[170:171], s[52:53], 0, v[160:161]
	global_load_lds_dwordx4 v[170:171], off
	v_lshl_add_u64 v[172:173], s[52:53], 0, v[162:163]
	s_mov_b32 m0, s20
	s_nop 0
	global_load_lds_dwordx4 v[172:173], off
	s_mov_b32 m0, s21
	v_lshl_add_u64 v[208:209], s[12:13], 0, v[160:161]
	global_load_lds_dwordx4 v[208:209], off
	v_lshl_add_u64 v[210:211], s[12:13], 0, v[162:163]
	s_mov_b32 m0, s22
	s_nop 0
	global_load_lds_dwordx4 v[210:211], off
	s_add_u32 s52, s52, s2
	s_addc_u32 s53, s53, s3
	s_mov_b32 m0, s24
	v_lshl_add_u64 v[212:213], s[52:53], 0, v[160:161]
	global_load_lds_dwordx4 v[212:213], off
	v_lshl_add_u64 v[214:215], s[52:53], 0, v[162:163]
	s_mov_b32 m0, s25
	s_nop 0
	global_load_lds_dwordx4 v[214:215], off
	ds_read_b128 v[144:147], v224 offset:16384
	ds_read_b128 v[148:151], v224 offset:17408
	ds_read_b128 v[152:155], v224 offset:18432
	ds_read_b128 v[156:159], v224 offset:19456
	ds_read_b128 v[176:179], v224 offset:20480
	ds_read_b128 v[180:183], v224 offset:21504
	ds_read_b128 v[184:187], v224 offset:22528
	ds_read_b128 v[188:191], v224 offset:23552
	s_waitcnt vmcnt(8)
	s_waitcnt lgkmcnt(0)
	s_barrier
; #define PG8_STAGE(bufoff, gbase) do { _Pragma("unroll") for (int _i = 0; _i < 2; ++_i) \
;         __builtin_amdgcn_global_load_lds((const unsigned*)((const char*)(gbase) + voffA[_i]), (LAS unsigned*)(lds + (bufoff) + ldsw + _i * 8192), 16, 0, 0); } while (0)
; #define PG8_LDA(dst, b, h) do { _Pragma("unroll") for (int m = 0; m < 4; ++m) _Pragma("unroll") for (int k = 0; k < 2; ++k) dst[m][k] = *(const LAS bf16x8*)(lds + PG8_SA(b, h) + aoff + m * 2048 + k * 1024); } while (0)
; #define PG8_LDB(dst, b, h) do { _Pragma("unroll") for (int n = 0; n < 2; ++n) _Pragma("unroll") for (int k = 0; k < 2; ++k) dst[n][k] = *(const LAS bf16x8*)(lds + PG8_SB(b, h) + boff + n * 2048 + k * 1024); } while (0)
; #define PG8_MMA(ai, bj, At, Bt) do { __builtin_amdgcn_s_setprio(1); _Pragma("unroll") for (int m = 0; m < 4; ++m) _Pragma("unroll") for (int n = 0; n < 2; ++n) _Pragma("unroll") for (int k = 0; k < 2; ++k) \
;         acc[ai][bj][m][n] = __builtin_amdgcn_mfma_f32_16x16x32_bf16(Bt[n][k], At[m][k], acc[ai][bj][m][n], 0, 0, 0); __builtin_amdgcn_s_setprio(0); } while (0)
; #define PG8_WAIT_V(n) asm volatile("s_waitcnt vmcnt(" #n ")" ::: "memory")
; #define PG8_WAIT_L(n) asm volatile("s_waitcnt lgkmcnt(" #n ")" ::: "memory")
; #define PG8_BAR __builtin_amdgcn_s_barrier()
; #define PG8_SCHED __builtin_amdgcn_sched_barrier(0)
; template <class Epi>
; DI void gemm_phase(const int TID, const int BID, LAS unsigned char* lds, const Gemm g, const Epi& E) {
;     ...
;             PG8_BAR; PG8_WAIT_L(0); PG8_MMA(0, 1, At, B1); PG8_BAR;
;             PG8_LDA(At, 0, 1); PG8_STAGE(PG8_SA(0, 0), a2);
;             PG8_BAR; PG8_WAIT_L(0); PG8_MMA(1, 0, At, B0); PG8_BAR; PG8_SCHED;
;             PG8_STAGE(PG8_SB(0, 1), b2 + hstep);
;             PG8_WAIT_V(6); PG8_BAR; PG8_MMA(1, 1, At, B1); PG8_BAR;
;             PG8_LDB(B0, 1, 0); PG8_SCHED; PG8_LDA(At, 1, 0); PG8_STAGE(PG8_SA(0, 1), a2 + hstep);
;             PG8_WAIT_L(8); PG8_BAR; PG8_WAIT_L(0); PG8_MMA(0, 0, At, B0); PG8_BAR; PG8_SCHED;
;             PG8_LDB(B1, 1, 1); PG8_STAGE(PG8_SB(1, 0), b3);
	s_setprio 1
	v_mfma_f32_16x16x32_bf16 v[60:63], v[128:131], v[144:147], v[60:63]
	v_mfma_f32_16x16x32_bf16 v[56:59], v[136:139], v[144:147], v[56:59]
	v_mfma_f32_16x16x32_bf16 v[44:47], v[128:131], v[152:155], v[44:47]
	v_mfma_f32_16x16x32_bf16 v[40:43], v[136:139], v[152:155], v[40:43]
	v_mfma_f32_16x16x32_bf16 v[28:31], v[128:131], v[176:179], v[28:31]
	v_mfma_f32_16x16x32_bf16 v[24:27], v[136:139], v[176:179], v[24:27]
	v_mfma_f32_16x16x32_bf16 v[12:15], v[128:131], v[184:187], v[12:15]
	v_mfma_f32_16x16x32_bf16 v[8:11], v[136:139], v[184:187], v[8:11]
	v_mfma_f32_16x16x32_bf16 v[60:63], v[132:135], v[148:151], v[60:63]
	v_mfma_f32_16x16x32_bf16 v[56:59], v[140:143], v[148:151], v[56:59]
	v_mfma_f32_16x16x32_bf16 v[44:47], v[132:135], v[156:159], v[44:47]
	v_mfma_f32_16x16x32_bf16 v[40:43], v[140:143], v[156:159], v[40:43]
	v_mfma_f32_16x16x32_bf16 v[28:31], v[132:135], v[180:183], v[28:31]
	v_mfma_f32_16x16x32_bf16 v[24:27], v[140:143], v[180:183], v[24:27]
	v_mfma_f32_16x16x32_bf16 v[12:15], v[132:135], v[188:191], v[12:15]
	v_mfma_f32_16x16x32_bf16 v[8:11], v[140:143], v[188:191], v[8:11]
	v_mfma_f32_16x16x32_bf16 v[52:55], v[192:195], v[144:147], v[52:55]
	v_mfma_f32_16x16x32_bf16 v[48:51], v[200:203], v[144:147], v[48:51]
	v_mfma_f32_16x16x32_bf16 v[36:39], v[192:195], v[152:155], v[36:39]
	v_mfma_f32_16x16x32_bf16 v[32:35], v[200:203], v[152:155], v[32:35]
	v_mfma_f32_16x16x32_bf16 v[20:23], v[192:195], v[176:179], v[20:23]
	v_mfma_f32_16x16x32_bf16 v[16:19], v[200:203], v[176:179], v[16:19]
	v_mfma_f32_16x16x32_bf16 v[4:7], v[192:195], v[184:187], v[4:7]
	v_mfma_f32_16x16x32_bf16 v[0:3], v[200:203], v[184:187], v[0:3]
	v_mfma_f32_16x16x32_bf16 v[52:55], v[196:199], v[148:151], v[52:55]
	v_mfma_f32_16x16x32_bf16 v[48:51], v[204:207], v[148:151], v[48:51]
	v_mfma_f32_16x16x32_bf16 v[36:39], v[196:199], v[156:159], v[36:39]
	v_mfma_f32_16x16x32_bf16 v[32:35], v[204:207], v[156:159], v[32:35]
	v_mfma_f32_16x16x32_bf16 v[20:23], v[196:199], v[180:183], v[20:23]
	v_mfma_f32_16x16x32_bf16 v[16:19], v[204:207], v[180:183], v[16:19]
	v_mfma_f32_16x16x32_bf16 v[4:7], v[196:199], v[188:191], v[4:7]
	v_mfma_f32_16x16x32_bf16 v[0:3], v[204:207], v[188:191], v[0:3]
	s_setprio 0
	s_barrier
	s_add_u32 s12, s12, s2
	s_addc_u32 s13, s13, s3
	s_mov_b32 m0, s26
	v_lshl_add_u64 v[192:193], s[12:13], 0, v[160:161]
	global_load_lds_dwordx4 v[192:193], off
	v_lshl_add_u64 v[192:193], s[12:13], 0, v[162:163]
	s_mov_b32 m0, s27
	s_nop 0
	global_load_lds_dwordx4 v[192:193], off
	v_add_u32_e32 v140, s31, v222
	ds_read_b128 v[128:131], v140
	ds_read_b128 v[132:135], v140 offset:1024
	ds_read_b128 v[136:139], v140 offset:2048
	ds_read_b128 v[140:143], v140 offset:3072
	ds_read_b128 v[144:147], v224 offset:32768
	ds_read_b128 v[148:151], v224 offset:33792
	ds_read_b128 v[152:155], v224 offset:34816
	ds_read_b128 v[156:159], v224 offset:35840
	ds_read_b128 v[176:179], v224 offset:36864
	ds_read_b128 v[180:183], v224 offset:37888
	ds_read_b128 v[184:187], v224 offset:38912
	ds_read_b128 v[188:191], v224 offset:39936
	v_add_u32_e32 v168, s61, v222
	ds_read_b128 v[192:195], v168
	ds_read_b128 v[196:199], v168 offset:1024
	ds_read_b128 v[200:203], v168 offset:2048
	ds_read_b128 v[204:207], v168 offset:3072
	s_waitcnt vmcnt(8)
	s_waitcnt lgkmcnt(0)
	s_barrier
	s_setprio 1
	v_mfma_f32_16x16x32_bf16 v[124:127], v[128:131], v[144:147], v[124:127]
	v_mfma_f32_16x16x32_bf16 v[120:123], v[136:139], v[144:147], v[120:123]
	v_mfma_f32_16x16x32_bf16 v[108:111], v[128:131], v[152:155], v[108:111]
	v_mfma_f32_16x16x32_bf16 v[104:107], v[136:139], v[152:155], v[104:107]
	v_mfma_f32_16x16x32_bf16 v[92:95], v[128:131], v[176:179], v[92:95]
	v_mfma_f32_16x16x32_bf16 v[88:91], v[136:139], v[176:179], v[88:91]
	v_mfma_f32_16x16x32_bf16 v[76:79], v[128:131], v[184:187], v[76:79]
	v_mfma_f32_16x16x32_bf16 v[72:75], v[136:139], v[184:187], v[72:75]
	v_mfma_f32_16x16x32_bf16 v[124:127], v[132:135], v[148:151], v[124:127]
	v_mfma_f32_16x16x32_bf16 v[120:123], v[140:143], v[148:151], v[120:123]
	v_mfma_f32_16x16x32_bf16 v[108:111], v[132:135], v[156:159], v[108:111]
	v_mfma_f32_16x16x32_bf16 v[104:107], v[140:143], v[156:159], v[104:107]
	v_mfma_f32_16x16x32_bf16 v[92:95], v[132:135], v[180:183], v[92:95]
	v_mfma_f32_16x16x32_bf16 v[88:91], v[140:143], v[180:183], v[88:91]
	v_mfma_f32_16x16x32_bf16 v[76:79], v[132:135], v[188:191], v[76:79]
	v_mfma_f32_16x16x32_bf16 v[72:75], v[140:143], v[188:191], v[72:75]
	v_mfma_f32_16x16x32_bf16 v[116:119], v[192:195], v[144:147], v[116:119]
	v_mfma_f32_16x16x32_bf16 v[112:115], v[200:203], v[144:147], v[112:115]
	v_mfma_f32_16x16x32_bf16 v[100:103], v[192:195], v[152:155], v[100:103]
	v_mfma_f32_16x16x32_bf16 v[96:99], v[200:203], v[152:155], v[96:99]
	v_mfma_f32_16x16x32_bf16 v[84:87], v[192:195], v[176:179], v[84:87]
	v_mfma_f32_16x16x32_bf16 v[80:83], v[200:203], v[176:179], v[80:83]
	v_mfma_f32_16x16x32_bf16 v[68:71], v[192:195], v[184:187], v[68:71]
	v_mfma_f32_16x16x32_bf16 v[64:67], v[200:203], v[184:187], v[64:67]
	v_mfma_f32_16x16x32_bf16 v[116:119], v[196:199], v[148:151], v[116:119]
	v_mfma_f32_16x16x32_bf16 v[112:115], v[204:207], v[148:151], v[112:115]
	v_mfma_f32_16x16x32_bf16 v[100:103], v[196:199], v[156:159], v[100:103]
	v_mfma_f32_16x16x32_bf16 v[96:99], v[204:207], v[156:159], v[96:99]
	v_mfma_f32_16x16x32_bf16 v[84:87], v[196:199], v[180:183], v[84:87]
	v_mfma_f32_16x16x32_bf16 v[80:83], v[204:207], v[180:183], v[80:83]
	v_mfma_f32_16x16x32_bf16 v[68:71], v[196:199], v[188:191], v[68:71]
	v_mfma_f32_16x16x32_bf16 v[64:67], v[204:207], v[188:191], v[64:67]
	s_setprio 0
	s_barrier
; #define PG8_STAGE(bufoff, gbase) do { _Pragma("unroll") for (int _i = 0; _i < 2; ++_i) \
;         __builtin_amdgcn_global_load_lds((const unsigned*)((const char*)(gbase) + voffA[_i]), (LAS unsigned*)(lds + (bufoff) + ldsw + _i * 8192), 16, 0, 0); } while (0)
; #define PG8_LDA(dst, b, h) do { _Pragma("unroll") for (int m = 0; m < 4; ++m) _Pragma("unroll") for (int k = 0; k < 2; ++k) dst[m][k] = *(const LAS bf16x8*)(lds + PG8_SA(b, h) + aoff + m * 2048 + k * 1024); } while (0)
; #define PG8_LDB(dst, b, h) do { _Pragma("unroll") for (int n = 0; n < 2; ++n) _Pragma("unroll") for (int k = 0; k < 2; ++k) dst[n][k] = *(const LAS bf16x8*)(lds + PG8_SB(b, h) + boff + n * 2048 + k * 1024); } while (0)
; #define PG8_MMA(ai, bj, At, Bt) do { __builtin_amdgcn_s_setprio(1); _Pragma("unroll") for (int m = 0; m < 4; ++m) _Pragma("unroll") for (int n = 0; n < 2; ++n) _Pragma("unroll") for (int k = 0; k < 2; ++k) \
;         acc[ai][bj][m][n] = __builtin_amdgcn_mfma_f32_16x16x32_bf16(Bt[n][k], At[m][k], acc[ai][bj][m][n], 0, 0, 0); __builtin_amdgcn_s_setprio(0); } while (0)
; #define PG8_WAIT_V(n) asm volatile("s_waitcnt vmcnt(" #n ")" ::: "memory")
; #define PG8_WAIT_L(n) asm volatile("s_waitcnt lgkmcnt(" #n ")" ::: "memory")
; #define PG8_BAR __builtin_amdgcn_s_barrier()
; #define PG8_SCHED __builtin_amdgcn_sched_barrier(0)
; template <class Epi>
; DI void gemm_phase(const int TID, const int BID, LAS unsigned char* lds, const Gemm g, const Epi& E) {
;     ...
;             PG8_LDB(B1, 1, 1); PG8_STAGE(PG8_SB(1, 0), b3);
;             PG8_BAR; PG8_WAIT_L(0); PG8_MMA(0, 1, At, B1); PG8_BAR;
;             PG8_LDA(At, 1, 1); PG8_STAGE(PG8_SA(1, 0), a3);
;             PG8_BAR; PG8_WAIT_L(0); PG8_MMA(1, 0, At, B0); PG8_BAR; PG8_SCHED;
;             PG8_STAGE(PG8_SB(1, 1), b3 + hstep);
;             PG8_WAIT_V(6); PG8_BAR; PG8_MMA(1, 1, At, B1); PG8_BAR;
;         }
	s_mov_b32 m0, s33
	v_lshl_add_u64 v[170:171], v[170:171], 0, s[92:93]
	global_load_lds_dwordx4 v[170:171], off
	v_lshl_add_u64 v[170:171], v[172:173], 0, s[92:93]
	s_mov_b32 m0, s56
	s_nop 0
	global_load_lds_dwordx4 v[170:171], off
	s_mov_b32 m0, s57
	v_lshl_add_u64 v[170:171], v[208:209], 0, s[92:93]
	global_load_lds_dwordx4 v[170:171], off
	v_lshl_add_u64 v[170:171], v[210:211], 0, s[92:93]
	s_mov_b32 m0, s60
	s_nop 0
	global_load_lds_dwordx4 v[170:171], off
	s_mov_b32 m0, s62
	v_lshl_add_u64 v[170:171], v[212:213], 0, s[92:93]
	global_load_lds_dwordx4 v[170:171], off
	v_lshl_add_u64 v[170:171], v[214:215], 0, s[92:93]
	s_mov_b32 m0, s63
	s_nop 0
	global_load_lds_dwordx4 v[170:171], off
	ds_read_b128 v[144:147], v224 offset:49152
	ds_read_b128 v[148:151], v224 offset:50176
	ds_read_b128 v[152:155], v224 offset:51200
	ds_read_b128 v[156:159], v224 offset:52224
	ds_read_b128 v[176:179], v224 offset:53248
	ds_read_b128 v[180:183], v224 offset:54272
	ds_read_b128 v[184:187], v224 offset:55296
	ds_read_b128 v[188:191], v224 offset:56320
	s_waitcnt vmcnt(8)
	s_waitcnt lgkmcnt(0)
	s_barrier
	s_setprio 1
	v_mfma_f32_16x16x32_bf16 v[60:63], v[128:131], v[144:147], v[60:63]
	v_mfma_f32_16x16x32_bf16 v[56:59], v[136:139], v[144:147], v[56:59]
	v_mfma_f32_16x16x32_bf16 v[44:47], v[128:131], v[152:155], v[44:47]
	v_mfma_f32_16x16x32_bf16 v[40:43], v[136:139], v[152:155], v[40:43]
	v_mfma_f32_16x16x32_bf16 v[28:31], v[128:131], v[176:179], v[28:31]
	v_mfma_f32_16x16x32_bf16 v[24:27], v[136:139], v[176:179], v[24:27]
	v_mfma_f32_16x16x32_bf16 v[12:15], v[128:131], v[184:187], v[12:15]
	v_mfma_f32_16x16x32_bf16 v[8:11], v[136:139], v[184:187], v[8:11]
	v_mfma_f32_16x16x32_bf16 v[60:63], v[132:135], v[148:151], v[60:63]
	v_mfma_f32_16x16x32_bf16 v[56:59], v[140:143], v[148:151], v[56:59]
	v_mfma_f32_16x16x32_bf16 v[44:47], v[132:135], v[156:159], v[44:47]
	v_mfma_f32_16x16x32_bf16 v[40:43], v[140:143], v[156:159], v[40:43]
	v_mfma_f32_16x16x32_bf16 v[28:31], v[132:135], v[180:183], v[28:31]
	v_mfma_f32_16x16x32_bf16 v[24:27], v[140:143], v[180:183], v[24:27]
	v_mfma_f32_16x16x32_bf16 v[12:15], v[132:135], v[188:191], v[12:15]
	v_mfma_f32_16x16x32_bf16 v[8:11], v[140:143], v[188:191], v[8:11]
	v_mfma_f32_16x16x32_bf16 v[52:55], v[192:195], v[144:147], v[52:55]
	v_mfma_f32_16x16x32_bf16 v[48:51], v[200:203], v[144:147], v[48:51]
	v_mfma_f32_16x16x32_bf16 v[36:39], v[192:195], v[152:155], v[36:39]
	v_mfma_f32_16x16x32_bf16 v[32:35], v[200:203], v[152:155], v[32:35]
	v_mfma_f32_16x16x32_bf16 v[20:23], v[192:195], v[176:179], v[20:23]
	v_mfma_f32_16x16x32_bf16 v[16:19], v[200:203], v[176:179], v[16:19]
	v_mfma_f32_16x16x32_bf16 v[4:7], v[192:195], v[184:187], v[4:7]
	v_mfma_f32_16x16x32_bf16 v[0:3], v[200:203], v[184:187], v[0:3]
	v_mfma_f32_16x16x32_bf16 v[52:55], v[196:199], v[148:151], v[52:55]
	v_mfma_f32_16x16x32_bf16 v[48:51], v[204:207], v[148:151], v[48:51]
	v_mfma_f32_16x16x32_bf16 v[36:39], v[196:199], v[156:159], v[36:39]
	v_mfma_f32_16x16x32_bf16 v[32:35], v[204:207], v[156:159], v[32:35]
	v_mfma_f32_16x16x32_bf16 v[20:23], v[196:199], v[180:183], v[20:23]
	v_mfma_f32_16x16x32_bf16 v[16:19], v[204:207], v[180:183], v[16:19]
	v_mfma_f32_16x16x32_bf16 v[4:7], v[196:199], v[188:191], v[4:7]
	v_mfma_f32_16x16x32_bf16 v[0:3], v[204:207], v[188:191], v[0:3]
	s_setprio 0
	s_add_u32 s0, s0, 0x100
	s_addc_u32 s1, s1, 0
	s_add_u32 s55, s55, 0x100
	s_addc_u32 vcc_lo, vcc_lo, 0
	s_cmp_ge_i32 vcc_hi, s80
	s_mov_b32 s12, vcc_hi
	s_barrier
	s_cbranch_scc0 .LBB0_271
	s_branch .LBB0_275

; #define PG8_STAGE(bufoff, gbase) do { _Pragma("unroll") for (int _i = 0; _i < 2; ++_i) \
;         __builtin_amdgcn_global_load_lds((const unsigned*)((const char*)(gbase) + voffA[_i]), (LAS unsigned*)(lds + (bufoff) + ldsw + _i * 8192), 16, 0, 0); } while (0)
; #define PG8_LDA(dst, b, h) do { _Pragma("unroll") for (int m = 0; m < 4; ++m) _Pragma("unroll") for (int k = 0; k < 2; ++k) dst[m][k] = *(const LAS bf16x8*)(lds + PG8_SA(b, h) + aoff + m * 2048 + k * 1024); } while (0)
; #define PG8_LDB(dst, b, h) do { _Pragma("unroll") for (int n = 0; n < 2; ++n) _Pragma("unroll") for (int k = 0; k < 2; ++k) dst[n][k] = *(const LAS bf16x8*)(lds + PG8_SB(b, h) + boff + n * 2048 + k * 1024); } while (0)
; #define PG8_MMA(ai, bj, At, Bt) do { __builtin_amdgcn_s_setprio(1); _Pragma("unroll") for (int m = 0; m < 4; ++m) _Pragma("unroll") for (int n = 0; n < 2; ++n) _Pragma("unroll") for (int k = 0; k < 2; ++k) \
;         acc[ai][bj][m][n] = __builtin_amdgcn_mfma_f32_16x16x32_bf16(Bt[n][k], At[m][k], acc[ai][bj][m][n], 0, 0, 0); __builtin_amdgcn_s_setprio(0); } while (0)
; #define PG8_WAIT_L(n) asm volatile("s_waitcnt lgkmcnt(" #n ")" ::: "memory")
; #define PG8_BAR __builtin_amdgcn_s_barrier()
; #define PG8_SCHED __builtin_amdgcn_sched_barrier(0)
; template <class Epi>
; DI void gemm_phase(const int TID, const int BID, LAS unsigned char* lds, const Gemm g, const Epi& E) {
;     ...
;             const bool last = (t == nt - 2);
;             const char* a1 = cA + (size_t)(t + 1) * kstep;
;             const char* a2 = last ? nA : cA + (size_t)(t + 2) * kstep; const char* b2 = last ? nB : cB + (size_t)(t + 2) * kstep;
;             const char* a3 = a2 + kstep; const char* b3 = b2 + kstep;
;             PG8_LDB(B0, 0, 0); PG8_SCHED; PG8_LDA(At, 0, 0); PG8_STAGE(PG8_SA(1, 1), a1 + hstep);
;             PG8_WAIT_L(8); PG8_BAR; PG8_WAIT_L(0); PG8_MMA(0, 0, At, B0); PG8_BAR; PG8_SCHED;
;             PG8_LDB(B1, 0, 1); PG8_STAGE(PG8_SB(0, 0), b2);
;             PG8_BAR; PG8_WAIT_L(0); PG8_MMA(0, 1, At, B1); PG8_BAR;
;             PG8_LDA(At, 0, 1); PG8_STAGE(PG8_SA(0, 0), a2);
;             PG8_BAR; PG8_WAIT_L(0); PG8_MMA(1, 0, At, B0); PG8_BAR; PG8_SCHED;
;             PG8_STAGE(PG8_SB(0, 1), b2 + hstep);
.LBB0_359:
	s_add_i32 s17, s8, 2
	s_add_u32 s10, s6, 0x80
	s_addc_u32 s9, s7, 0
	s_cmp_eq_u32 s16, s8
	s_cselect_b32 s8, s60, s10
	s_cselect_b32 s9, s61, s9
	s_cselect_b32 s11, s63, s13
	s_cselect_b32 s10, s62, s12
	v_lshl_add_u64 v[170:171], s[6:7], 0, v[176:177]
	s_add_i32 m0, s22, 0xc000
	global_load_lds_dwordx4 v[170:171], off
	v_lshl_add_u64 v[170:171], s[6:7], 0, v[178:179]
	s_add_i32 m0, s22, 0xe000
	s_nop 0
	global_load_lds_dwordx4 v[170:171], off
	v_add_u32_e32 v140, s19, v192
	ds_read_b128 v[128:131], v140
	ds_read_b128 v[132:135], v140 offset:1024
	ds_read_b128 v[136:139], v140 offset:2048
	ds_read_b128 v[140:143], v140 offset:3072
	ds_read_b128 v[144:147], v203
	ds_read_b128 v[148:151], v203 offset:1024
	ds_read_b128 v[152:155], v203 offset:2048
	ds_read_b128 v[204:207], v203 offset:3072
	ds_read_b128 v[208:211], v203 offset:4096
	ds_read_b128 v[212:215], v203 offset:5120
	ds_read_b128 v[216:219], v203 offset:6144
	ds_read_b128 v[220:223], v203 offset:7168
	v_add_u32_e32 v168, s24, v192
	ds_read_b128 v[224:227], v168
	ds_read_b128 v[228:231], v168 offset:1024
	ds_read_b128 v[246:249], v168 offset:2048
	ds_read_b128 v[232:235], v168 offset:3072
	s_waitcnt vmcnt(8)
	s_waitcnt lgkmcnt(0)
	s_barrier
	s_setprio 1
	v_mfma_f32_16x16x32_bf16 v[124:127], v[128:131], v[144:147], v[124:127]
	v_mfma_f32_16x16x32_bf16 v[120:123], v[136:139], v[144:147], v[120:123]
	v_mfma_f32_16x16x32_bf16 v[108:111], v[128:131], v[152:155], v[108:111]
	v_mfma_f32_16x16x32_bf16 v[104:107], v[136:139], v[152:155], v[104:107]
	v_mfma_f32_16x16x32_bf16 v[92:95], v[128:131], v[208:211], v[92:95]
	v_mfma_f32_16x16x32_bf16 v[88:91], v[136:139], v[208:211], v[88:91]
	v_mfma_f32_16x16x32_bf16 v[76:79], v[128:131], v[216:219], v[76:79]
	v_mfma_f32_16x16x32_bf16 v[72:75], v[136:139], v[216:219], v[72:75]
	v_mfma_f32_16x16x32_bf16 v[124:127], v[132:135], v[148:151], v[124:127]
	v_mfma_f32_16x16x32_bf16 v[120:123], v[140:143], v[148:151], v[120:123]
	v_mfma_f32_16x16x32_bf16 v[108:111], v[132:135], v[204:207], v[108:111]
	v_mfma_f32_16x16x32_bf16 v[104:107], v[140:143], v[204:207], v[104:107]
	v_mfma_f32_16x16x32_bf16 v[92:95], v[132:135], v[212:215], v[92:95]
	v_mfma_f32_16x16x32_bf16 v[88:91], v[140:143], v[212:215], v[88:91]
	v_mfma_f32_16x16x32_bf16 v[76:79], v[132:135], v[220:223], v[76:79]
	v_mfma_f32_16x16x32_bf16 v[72:75], v[140:143], v[220:223], v[72:75]
	v_mfma_f32_16x16x32_bf16 v[116:119], v[224:227], v[144:147], v[116:119]
	v_mfma_f32_16x16x32_bf16 v[112:115], v[246:249], v[144:147], v[112:115]
	v_mfma_f32_16x16x32_bf16 v[100:103], v[224:227], v[152:155], v[100:103]
	v_mfma_f32_16x16x32_bf16 v[96:99], v[246:249], v[152:155], v[96:99]
	v_mfma_f32_16x16x32_bf16 v[84:87], v[224:227], v[208:211], v[84:87]
	v_mfma_f32_16x16x32_bf16 v[80:83], v[246:249], v[208:211], v[80:83]
	v_mfma_f32_16x16x32_bf16 v[68:71], v[224:227], v[216:219], v[68:71]
	v_mfma_f32_16x16x32_bf16 v[64:67], v[246:249], v[216:219], v[64:67]
	v_mfma_f32_16x16x32_bf16 v[116:119], v[228:231], v[148:151], v[116:119]
	v_mfma_f32_16x16x32_bf16 v[112:115], v[232:235], v[148:151], v[112:115]
	v_mfma_f32_16x16x32_bf16 v[100:103], v[228:231], v[204:207], v[100:103]
	v_mfma_f32_16x16x32_bf16 v[96:99], v[232:235], v[204:207], v[96:99]
	v_mfma_f32_16x16x32_bf16 v[84:87], v[228:231], v[212:215], v[84:87]
	v_mfma_f32_16x16x32_bf16 v[80:83], v[232:235], v[212:215], v[80:83]
	v_mfma_f32_16x16x32_bf16 v[68:71], v[228:231], v[220:223], v[68:71]
	v_mfma_f32_16x16x32_bf16 v[64:67], v[232:235], v[220:223], v[64:67]
	s_setprio 0
	s_barrier
	s_mov_b32 m0, s20
	v_lshl_add_u64 v[170:171], s[10:11], 0, v[158:159]
	global_load_lds_dwordx4 v[170:171], off
	v_lshl_add_u64 v[172:173], s[10:11], 0, v[160:161]
	s_mov_b32 m0, s21
	s_nop 0
	global_load_lds_dwordx4 v[172:173], off
	s_mov_b32 m0, s22
	v_lshl_add_u64 v[180:181], s[8:9], 0, v[158:159]
	global_load_lds_dwordx4 v[180:181], off
	v_lshl_add_u64 v[236:237], s[8:9], 0, v[160:161]
	s_mov_b32 m0, s23
	s_nop 0
	global_load_lds_dwordx4 v[236:237], off
	s_add_u32 s10, s10, s52
	s_addc_u32 s11, s11, s53
	s_mov_b32 m0, s25
	v_lshl_add_u64 v[238:239], s[10:11], 0, v[158:159]
	global_load_lds_dwordx4 v[238:239], off
	v_lshl_add_u64 v[184:185], s[10:11], 0, v[160:161]
	s_mov_b32 m0, s26
	s_nop 0
	global_load_lds_dwordx4 v[184:185], off
	ds_read_b128 v[144:147], v203 offset:16384
	ds_read_b128 v[148:151], v203 offset:17408
	ds_read_b128 v[152:155], v203 offset:18432
	ds_read_b128 v[204:207], v203 offset:19456
	ds_read_b128 v[208:211], v203 offset:20480
	ds_read_b128 v[212:215], v203 offset:21504
	ds_read_b128 v[216:219], v203 offset:22528
	ds_read_b128 v[220:223], v203 offset:23552
	s_waitcnt vmcnt(8)
	s_waitcnt lgkmcnt(0)
	s_barrier
; #define PG8_STAGE(bufoff, gbase) do { _Pragma("unroll") for (int _i = 0; _i < 2; ++_i) \
;         __builtin_amdgcn_global_load_lds((const unsigned*)((const char*)(gbase) + voffA[_i]), (LAS unsigned*)(lds + (bufoff) + ldsw + _i * 8192), 16, 0, 0); } while (0)
; #define PG8_LDA(dst, b, h) do { _Pragma("unroll") for (int m = 0; m < 4; ++m) _Pragma("unroll") for (int k = 0; k < 2; ++k) dst[m][k] = *(const LAS bf16x8*)(lds + PG8_SA(b, h) + aoff + m * 2048 + k * 1024); } while (0)
; #define PG8_LDB(dst, b, h) do { _Pragma("unroll") for (int n = 0; n < 2; ++n) _Pragma("unroll") for (int k = 0; k < 2; ++k) dst[n][k] = *(const LAS bf16x8*)(lds + PG8_SB(b, h) + boff + n * 2048 + k * 1024); } while (0)
; #define PG8_MMA(ai, bj, At, Bt) do { __builtin_amdgcn_s_setprio(1); _Pragma("unroll") for (int m = 0; m < 4; ++m) _Pragma("unroll") for (int n = 0; n < 2; ++n) _Pragma("unroll") for (int k = 0; k < 2; ++k) \
;         acc[ai][bj][m][n] = __builtin_amdgcn_mfma_f32_16x16x32_bf16(Bt[n][k], At[m][k], acc[ai][bj][m][n], 0, 0, 0); __builtin_amdgcn_s_setprio(0); } while (0)
; #define PG8_WAIT_V(n) asm volatile("s_waitcnt vmcnt(" #n ")" ::: "memory")
; #define PG8_WAIT_L(n) asm volatile("s_waitcnt lgkmcnt(" #n ")" ::: "memory")
; #define PG8_BAR __builtin_amdgcn_s_barrier()
; #define PG8_SCHED __builtin_amdgcn_sched_barrier(0)
; template <class Epi>
; DI void gemm_phase(const int TID, const int BID, LAS unsigned char* lds, const Gemm g, const Epi& E) {
;     ...
;             PG8_BAR; PG8_WAIT_L(0); PG8_MMA(0, 1, At, B1); PG8_BAR;
;             PG8_LDA(At, 0, 1); PG8_STAGE(PG8_SA(0, 0), a2);
;             PG8_BAR; PG8_WAIT_L(0); PG8_MMA(1, 0, At, B0); PG8_BAR; PG8_SCHED;
;             PG8_STAGE(PG8_SB(0, 1), b2 + hstep);
;             PG8_WAIT_V(6); PG8_BAR; PG8_MMA(1, 1, At, B1); PG8_BAR;
;             PG8_LDB(B0, 1, 0); PG8_SCHED; PG8_LDA(At, 1, 0); PG8_STAGE(PG8_SA(0, 1), a2 + hstep);
;             PG8_WAIT_L(8); PG8_BAR; PG8_WAIT_L(0); PG8_MMA(0, 0, At, B0); PG8_BAR; PG8_SCHED;
;             PG8_LDB(B1, 1, 1); PG8_STAGE(PG8_SB(1, 0), b3);
	s_setprio 1
	v_mfma_f32_16x16x32_bf16 v[60:63], v[128:131], v[144:147], v[60:63]
	v_mfma_f32_16x16x32_bf16 v[56:59], v[136:139], v[144:147], v[56:59]
	v_mfma_f32_16x16x32_bf16 v[44:47], v[128:131], v[152:155], v[44:47]
	v_mfma_f32_16x16x32_bf16 v[40:43], v[136:139], v[152:155], v[40:43]
	v_mfma_f32_16x16x32_bf16 v[28:31], v[128:131], v[208:211], v[28:31]
	v_mfma_f32_16x16x32_bf16 v[24:27], v[136:139], v[208:211], v[24:27]
	v_mfma_f32_16x16x32_bf16 v[12:15], v[128:131], v[216:219], v[12:15]
	v_mfma_f32_16x16x32_bf16 v[8:11], v[136:139], v[216:219], v[8:11]
	v_mfma_f32_16x16x32_bf16 v[60:63], v[132:135], v[148:151], v[60:63]
	v_mfma_f32_16x16x32_bf16 v[56:59], v[140:143], v[148:151], v[56:59]
	v_mfma_f32_16x16x32_bf16 v[44:47], v[132:135], v[204:207], v[44:47]
	v_mfma_f32_16x16x32_bf16 v[40:43], v[140:143], v[204:207], v[40:43]
	v_mfma_f32_16x16x32_bf16 v[28:31], v[132:135], v[212:215], v[28:31]
	v_mfma_f32_16x16x32_bf16 v[24:27], v[140:143], v[212:215], v[24:27]
	v_mfma_f32_16x16x32_bf16 v[12:15], v[132:135], v[220:223], v[12:15]
	v_mfma_f32_16x16x32_bf16 v[8:11], v[140:143], v[220:223], v[8:11]
	v_mfma_f32_16x16x32_bf16 v[52:55], v[224:227], v[144:147], v[52:55]
	v_mfma_f32_16x16x32_bf16 v[48:51], v[246:249], v[144:147], v[48:51]
	v_mfma_f32_16x16x32_bf16 v[36:39], v[224:227], v[152:155], v[36:39]
	v_mfma_f32_16x16x32_bf16 v[32:35], v[246:249], v[152:155], v[32:35]
	v_mfma_f32_16x16x32_bf16 v[20:23], v[224:227], v[208:211], v[20:23]
	v_mfma_f32_16x16x32_bf16 v[16:19], v[246:249], v[208:211], v[16:19]
	v_mfma_f32_16x16x32_bf16 v[4:7], v[224:227], v[216:219], v[4:7]
	v_mfma_f32_16x16x32_bf16 v[0:3], v[246:249], v[216:219], v[0:3]
	v_mfma_f32_16x16x32_bf16 v[52:55], v[228:231], v[148:151], v[52:55]
	v_mfma_f32_16x16x32_bf16 v[48:51], v[232:235], v[148:151], v[48:51]
	v_mfma_f32_16x16x32_bf16 v[36:39], v[228:231], v[204:207], v[36:39]
	v_mfma_f32_16x16x32_bf16 v[32:35], v[232:235], v[204:207], v[32:35]
	v_mfma_f32_16x16x32_bf16 v[20:23], v[228:231], v[212:215], v[20:23]
	v_mfma_f32_16x16x32_bf16 v[16:19], v[232:235], v[212:215], v[16:19]
	v_mfma_f32_16x16x32_bf16 v[4:7], v[228:231], v[220:223], v[4:7]
	v_mfma_f32_16x16x32_bf16 v[0:3], v[232:235], v[220:223], v[0:3]
	s_setprio 0
	s_barrier
	s_add_u32 s8, s8, s52
	s_addc_u32 s9, s9, s53
	s_mov_b32 m0, s27
	v_lshl_add_u64 v[224:225], s[8:9], 0, v[158:159]
	global_load_lds_dwordx4 v[224:225], off
	v_lshl_add_u64 v[224:225], s[8:9], 0, v[160:161]
	s_mov_b32 m0, s28
	s_nop 0
	global_load_lds_dwordx4 v[224:225], off
	v_add_u32_e32 v140, s29, v192
	ds_read_b128 v[128:131], v140
	ds_read_b128 v[132:135], v140 offset:1024
	ds_read_b128 v[136:139], v140 offset:2048
	ds_read_b128 v[140:143], v140 offset:3072
	ds_read_b128 v[144:147], v203 offset:32768
	ds_read_b128 v[148:151], v203 offset:33792
	ds_read_b128 v[152:155], v203 offset:34816
	ds_read_b128 v[204:207], v203 offset:35840
	ds_read_b128 v[208:211], v203 offset:36864
	ds_read_b128 v[212:215], v203 offset:37888
	ds_read_b128 v[216:219], v203 offset:38912
	ds_read_b128 v[220:223], v203 offset:39936
	v_add_u32_e32 v168, s77, v192
	ds_read_b128 v[224:227], v168
	ds_read_b128 v[228:231], v168 offset:1024
	ds_read_b128 v[232:235], v168 offset:2048
	ds_read_b128 v[246:249], v168 offset:3072
	s_waitcnt vmcnt(8)
	s_waitcnt lgkmcnt(0)
	s_barrier
	s_setprio 1
	v_mfma_f32_16x16x32_bf16 v[124:127], v[128:131], v[144:147], v[124:127]
	v_mfma_f32_16x16x32_bf16 v[120:123], v[136:139], v[144:147], v[120:123]
	v_mfma_f32_16x16x32_bf16 v[108:111], v[128:131], v[152:155], v[108:111]
	v_mfma_f32_16x16x32_bf16 v[104:107], v[136:139], v[152:155], v[104:107]
	v_mfma_f32_16x16x32_bf16 v[92:95], v[128:131], v[208:211], v[92:95]
	v_mfma_f32_16x16x32_bf16 v[88:91], v[136:139], v[208:211], v[88:91]
	v_mfma_f32_16x16x32_bf16 v[76:79], v[128:131], v[216:219], v[76:79]
	v_mfma_f32_16x16x32_bf16 v[72:75], v[136:139], v[216:219], v[72:75]
	v_mfma_f32_16x16x32_bf16 v[124:127], v[132:135], v[148:151], v[124:127]
	v_mfma_f32_16x16x32_bf16 v[120:123], v[140:143], v[148:151], v[120:123]
	v_mfma_f32_16x16x32_bf16 v[108:111], v[132:135], v[204:207], v[108:111]
	v_mfma_f32_16x16x32_bf16 v[104:107], v[140:143], v[204:207], v[104:107]
	v_mfma_f32_16x16x32_bf16 v[92:95], v[132:135], v[212:215], v[92:95]
	v_mfma_f32_16x16x32_bf16 v[88:91], v[140:143], v[212:215], v[88:91]
	v_mfma_f32_16x16x32_bf16 v[76:79], v[132:135], v[220:223], v[76:79]
	v_mfma_f32_16x16x32_bf16 v[72:75], v[140:143], v[220:223], v[72:75]
	v_mfma_f32_16x16x32_bf16 v[116:119], v[224:227], v[144:147], v[116:119]
	v_mfma_f32_16x16x32_bf16 v[112:115], v[232:235], v[144:147], v[112:115]
	v_mfma_f32_16x16x32_bf16 v[100:103], v[224:227], v[152:155], v[100:103]
	v_mfma_f32_16x16x32_bf16 v[96:99], v[232:235], v[152:155], v[96:99]
	v_mfma_f32_16x16x32_bf16 v[84:87], v[224:227], v[208:211], v[84:87]
	v_mfma_f32_16x16x32_bf16 v[80:83], v[232:235], v[208:211], v[80:83]
	v_mfma_f32_16x16x32_bf16 v[68:71], v[224:227], v[216:219], v[68:71]
	v_mfma_f32_16x16x32_bf16 v[64:67], v[232:235], v[216:219], v[64:67]
	v_mfma_f32_16x16x32_bf16 v[116:119], v[228:231], v[148:151], v[116:119]
	v_mfma_f32_16x16x32_bf16 v[112:115], v[246:249], v[148:151], v[112:115]
	v_mfma_f32_16x16x32_bf16 v[100:103], v[228:231], v[204:207], v[100:103]
	v_mfma_f32_16x16x32_bf16 v[96:99], v[246:249], v[204:207], v[96:99]
	v_mfma_f32_16x16x32_bf16 v[84:87], v[228:231], v[212:215], v[84:87]
	v_mfma_f32_16x16x32_bf16 v[80:83], v[246:249], v[212:215], v[80:83]
	v_mfma_f32_16x16x32_bf16 v[68:71], v[228:231], v[220:223], v[68:71]
	v_mfma_f32_16x16x32_bf16 v[64:67], v[246:249], v[220:223], v[64:67]
	s_setprio 0
	s_barrier
; #define PG8_STAGE(bufoff, gbase) do { _Pragma("unroll") for (int _i = 0; _i < 2; ++_i) \
;         __builtin_amdgcn_global_load_lds((const unsigned*)((const char*)(gbase) + voffA[_i]), (LAS unsigned*)(lds + (bufoff) + ldsw + _i * 8192), 16, 0, 0); } while (0)
; #define PG8_LDA(dst, b, h) do { _Pragma("unroll") for (int m = 0; m < 4; ++m) _Pragma("unroll") for (int k = 0; k < 2; ++k) dst[m][k] = *(const LAS bf16x8*)(lds + PG8_SA(b, h) + aoff + m * 2048 + k * 1024); } while (0)
; #define PG8_LDB(dst, b, h) do { _Pragma("unroll") for (int n = 0; n < 2; ++n) _Pragma("unroll") for (int k = 0; k < 2; ++k) dst[n][k] = *(const LAS bf16x8*)(lds + PG8_SB(b, h) + boff + n * 2048 + k * 1024); } while (0)
; #define PG8_MMA(ai, bj, At, Bt) do { __builtin_amdgcn_s_setprio(1); _Pragma("unroll") for (int m = 0; m < 4; ++m) _Pragma("unroll") for (int n = 0; n < 2; ++n) _Pragma("unroll") for (int k = 0; k < 2; ++k) \
;         acc[ai][bj][m][n] = __builtin_amdgcn_mfma_f32_16x16x32_bf16(Bt[n][k], At[m][k], acc[ai][bj][m][n], 0, 0, 0); __builtin_amdgcn_s_setprio(0); } while (0)
; #define PG8_WAIT_V(n) asm volatile("s_waitcnt vmcnt(" #n ")" ::: "memory")
; #define PG8_WAIT_L(n) asm volatile("s_waitcnt lgkmcnt(" #n ")" ::: "memory")
; #define PG8_BAR __builtin_amdgcn_s_barrier()
; #define PG8_SCHED __builtin_amdgcn_sched_barrier(0)
; template <class Epi>
; DI void gemm_phase(const int TID, const int BID, LAS unsigned char* lds, const Gemm g, const Epi& E) {
;     ...
;             PG8_LDB(B1, 1, 1); PG8_STAGE(PG8_SB(1, 0), b3);
;             PG8_BAR; PG8_WAIT_L(0); PG8_MMA(0, 1, At, B1); PG8_BAR;
;             PG8_LDA(At, 1, 1); PG8_STAGE(PG8_SA(1, 0), a3);
;             PG8_BAR; PG8_WAIT_L(0); PG8_MMA(1, 0, At, B0); PG8_BAR; PG8_SCHED;
;             PG8_STAGE(PG8_SB(1, 1), b3 + hstep);
;             PG8_WAIT_V(6); PG8_BAR; PG8_MMA(1, 1, At, B1); PG8_BAR;
;         }
	s_mov_b32 m0, s30
	v_lshl_add_u64 v[170:171], v[170:171], 0, s[92:93]
	global_load_lds_dwordx4 v[170:171], off
	v_lshl_add_u64 v[170:171], v[172:173], 0, s[92:93]
	s_mov_b32 m0, s31
	s_nop 0
	global_load_lds_dwordx4 v[170:171], off
	s_mov_b32 m0, s33
	v_lshl_add_u64 v[170:171], v[180:181], 0, s[92:93]
	global_load_lds_dwordx4 v[170:171], off
	v_lshl_add_u64 v[170:171], v[236:237], 0, s[92:93]
	s_mov_b32 m0, s76
	s_nop 0
	global_load_lds_dwordx4 v[170:171], off
	s_mov_b32 m0, s80
	v_lshl_add_u64 v[170:171], v[238:239], 0, s[92:93]
	global_load_lds_dwordx4 v[170:171], off
	v_lshl_add_u64 v[170:171], v[184:185], 0, s[92:93]
	s_mov_b32 m0, s81
	s_nop 0
	global_load_lds_dwordx4 v[170:171], off
	ds_read_b128 v[144:147], v203 offset:49152
	ds_read_b128 v[148:151], v203 offset:50176
	ds_read_b128 v[152:155], v203 offset:51200
	ds_read_b128 v[204:207], v203 offset:52224
	ds_read_b128 v[208:211], v203 offset:53248
	ds_read_b128 v[212:215], v203 offset:54272
	ds_read_b128 v[216:219], v203 offset:55296
	ds_read_b128 v[220:223], v203 offset:56320
	s_waitcnt vmcnt(8)
	s_waitcnt lgkmcnt(0)
	s_barrier
	s_setprio 1
	v_mfma_f32_16x16x32_bf16 v[60:63], v[128:131], v[144:147], v[60:63]
	v_mfma_f32_16x16x32_bf16 v[56:59], v[136:139], v[144:147], v[56:59]
	v_mfma_f32_16x16x32_bf16 v[44:47], v[128:131], v[152:155], v[44:47]
	v_mfma_f32_16x16x32_bf16 v[40:43], v[136:139], v[152:155], v[40:43]
	v_mfma_f32_16x16x32_bf16 v[28:31], v[128:131], v[208:211], v[28:31]
	v_mfma_f32_16x16x32_bf16 v[24:27], v[136:139], v[208:211], v[24:27]
	v_mfma_f32_16x16x32_bf16 v[12:15], v[128:131], v[216:219], v[12:15]
	v_mfma_f32_16x16x32_bf16 v[8:11], v[136:139], v[216:219], v[8:11]
	v_mfma_f32_16x16x32_bf16 v[60:63], v[132:135], v[148:151], v[60:63]
	v_mfma_f32_16x16x32_bf16 v[56:59], v[140:143], v[148:151], v[56:59]
	v_mfma_f32_16x16x32_bf16 v[44:47], v[132:135], v[204:207], v[44:47]
	v_mfma_f32_16x16x32_bf16 v[40:43], v[140:143], v[204:207], v[40:43]
	v_mfma_f32_16x16x32_bf16 v[28:31], v[132:135], v[212:215], v[28:31]
	v_mfma_f32_16x16x32_bf16 v[24:27], v[140:143], v[212:215], v[24:27]
	v_mfma_f32_16x16x32_bf16 v[12:15], v[132:135], v[220:223], v[12:15]
	v_mfma_f32_16x16x32_bf16 v[8:11], v[140:143], v[220:223], v[8:11]
	v_mfma_f32_16x16x32_bf16 v[52:55], v[224:227], v[144:147], v[52:55]
	v_mfma_f32_16x16x32_bf16 v[48:51], v[232:235], v[144:147], v[48:51]
	v_mfma_f32_16x16x32_bf16 v[36:39], v[224:227], v[152:155], v[36:39]
	v_mfma_f32_16x16x32_bf16 v[32:35], v[232:235], v[152:155], v[32:35]
	v_mfma_f32_16x16x32_bf16 v[20:23], v[224:227], v[208:211], v[20:23]
	v_mfma_f32_16x16x32_bf16 v[16:19], v[232:235], v[208:211], v[16:19]
	v_mfma_f32_16x16x32_bf16 v[4:7], v[224:227], v[216:219], v[4:7]
	v_mfma_f32_16x16x32_bf16 v[0:3], v[232:235], v[216:219], v[0:3]
	v_mfma_f32_16x16x32_bf16 v[52:55], v[228:231], v[148:151], v[52:55]
	v_mfma_f32_16x16x32_bf16 v[48:51], v[246:249], v[148:151], v[48:51]
	v_mfma_f32_16x16x32_bf16 v[36:39], v[228:231], v[204:207], v[36:39]
	v_mfma_f32_16x16x32_bf16 v[32:35], v[246:249], v[204:207], v[32:35]
	v_mfma_f32_16x16x32_bf16 v[20:23], v[228:231], v[212:215], v[20:23]
	v_mfma_f32_16x16x32_bf16 v[16:19], v[246:249], v[212:215], v[16:19]
	v_mfma_f32_16x16x32_bf16 v[4:7], v[228:231], v[220:223], v[4:7]
	v_mfma_f32_16x16x32_bf16 v[0:3], v[246:249], v[220:223], v[0:3]
	s_setprio 0
	s_add_u32 s6, s6, 0x100
	s_addc_u32 s7, s7, 0
	s_add_u32 s12, s12, 0x100
	s_addc_u32 s13, s13, 0
	s_cmp_ge_i32 s17, s18
	s_mov_b32 s8, s17
	s_barrier
	s_cbranch_scc0 .LBB0_359

; #define PG8_STAGE(bufoff, gbase) do { _Pragma("unroll") for (int _i = 0; _i < 2; ++_i) \
;         __builtin_amdgcn_global_load_lds((const unsigned*)((const char*)(gbase) + voffA[_i]), (LAS unsigned*)(lds + (bufoff) + ldsw + _i * 8192), 16, 0, 0); } while (0)
; #define PG8_LDA(dst, b, h) do { _Pragma("unroll") for (int m = 0; m < 4; ++m) _Pragma("unroll") for (int k = 0; k < 2; ++k) dst[m][k] = *(const LAS bf16x8*)(lds + PG8_SA(b, h) + aoff + m * 2048 + k * 1024); } while (0)
; #define PG8_LDB(dst, b, h) do { _Pragma("unroll") for (int n = 0; n < 2; ++n) _Pragma("unroll") for (int k = 0; k < 2; ++k) dst[n][k] = *(const LAS bf16x8*)(lds + PG8_SB(b, h) + boff + n * 2048 + k * 1024); } while (0)
; #define PG8_MMA(ai, bj, At, Bt) do { __builtin_amdgcn_s_setprio(1); _Pragma("unroll") for (int m = 0; m < 4; ++m) _Pragma("unroll") for (int n = 0; n < 2; ++n) _Pragma("unroll") for (int k = 0; k < 2; ++k) \
;         acc[ai][bj][m][n] = __builtin_amdgcn_mfma_f32_16x16x32_bf16(Bt[n][k], At[m][k], acc[ai][bj][m][n], 0, 0, 0); __builtin_amdgcn_s_setprio(0); } while (0)
; #define PG8_WAIT_L(n) asm volatile("s_waitcnt lgkmcnt(" #n ")" ::: "memory")
; #define PG8_BAR __builtin_amdgcn_s_barrier()
; #define PG8_SCHED __builtin_amdgcn_sched_barrier(0)
; template <class Epi>
; DI void gemm_phase(const int TID, const int BID, LAS unsigned char* lds, const Gemm g, const Epi& E) {
;     ...
;         for (int t = 0; t < nt; t += 2) {
;             const bool last = (t == nt - 2);
;             const char* a1 = cA + (size_t)(t + 1) * kstep;
;             const char* a2 = last ? nA : cA + (size_t)(t + 2) * kstep; const char* b2 = last ? nB : cB + (size_t)(t + 2) * kstep;
;             const char* a3 = a2 + kstep; const char* b3 = b2 + kstep;
;             PG8_LDB(B0, 0, 0); PG8_SCHED; PG8_LDA(At, 0, 0); PG8_STAGE(PG8_SA(1, 1), a1 + hstep);
;             PG8_WAIT_L(8); PG8_BAR; PG8_WAIT_L(0); PG8_MMA(0, 0, At, B0); PG8_BAR; PG8_SCHED;
;             PG8_LDB(B1, 0, 1); PG8_STAGE(PG8_SB(0, 0), b2);
;             PG8_BAR; PG8_WAIT_L(0); PG8_MMA(0, 1, At, B1); PG8_BAR;
.LBB0_491:
	s_add_i32 s16, s60, 2
	s_add_u32 s62, s4, 0x80
	s_addc_u32 s61, s5, 0
	s_cmp_eq_u32 s76, s60
	s_cselect_b32 s60, s56, s62
	s_cselect_b32 s61, s57, s61
	s_cselect_b32 s63, s59, vcc_hi
	s_cselect_b32 s62, s58, vcc_lo
	v_lshl_add_u64 v[156:157], s[4:5], 0, v[188:189]
	s_add_i32 m0, s21, 0xc000
	global_load_lds_dwordx4 v[156:157], off
	v_lshl_add_u64 v[156:157], s[4:5], 0, v[190:191]
	s_add_i32 m0, s21, 0xe000
	s_nop 0
	global_load_lds_dwordx4 v[156:157], off
	v_add_u32_e32 v140, s18, v192
	ds_read_b128 v[128:131], v140
	ds_read_b128 v[132:135], v140 offset:1024
	ds_read_b128 v[136:139], v140 offset:2048
	ds_read_b128 v[140:143], v140 offset:3072
	ds_read_b128 v[144:147], v175
	ds_read_b128 v[148:151], v175 offset:1024
	ds_read_b128 v[152:155], v175 offset:2048
	ds_read_b128 v[196:199], v175 offset:3072
	ds_read_b128 v[200:203], v175 offset:4096
	ds_read_b128 v[204:207], v175 offset:5120
	ds_read_b128 v[208:211], v175 offset:6144
	ds_read_b128 v[212:215], v175 offset:7168
	v_add_u32_e32 v156, s23, v192
	ds_read_b128 v[216:219], v156
	ds_read_b128 v[220:223], v156 offset:1024
	ds_read_b128 v[224:227], v156 offset:2048
	ds_read_b128 v[228:231], v156 offset:3072
	s_waitcnt vmcnt(8)
	s_waitcnt lgkmcnt(0)
	s_barrier
	s_setprio 1
	v_mfma_f32_16x16x32_bf16 v[124:127], v[128:131], v[144:147], v[124:127]
	v_mfma_f32_16x16x32_bf16 v[120:123], v[136:139], v[144:147], v[120:123]
	v_mfma_f32_16x16x32_bf16 v[108:111], v[128:131], v[152:155], v[108:111]
	v_mfma_f32_16x16x32_bf16 v[104:107], v[136:139], v[152:155], v[104:107]
	v_mfma_f32_16x16x32_bf16 v[92:95], v[128:131], v[200:203], v[92:95]
	v_mfma_f32_16x16x32_bf16 v[88:91], v[136:139], v[200:203], v[88:91]
	v_mfma_f32_16x16x32_bf16 v[76:79], v[128:131], v[208:211], v[76:79]
	v_mfma_f32_16x16x32_bf16 v[72:75], v[136:139], v[208:211], v[72:75]
	v_mfma_f32_16x16x32_bf16 v[124:127], v[132:135], v[148:151], v[124:127]
	v_mfma_f32_16x16x32_bf16 v[120:123], v[140:143], v[148:151], v[120:123]
	v_mfma_f32_16x16x32_bf16 v[108:111], v[132:135], v[196:199], v[108:111]
	v_mfma_f32_16x16x32_bf16 v[104:107], v[140:143], v[196:199], v[104:107]
	v_mfma_f32_16x16x32_bf16 v[92:95], v[132:135], v[204:207], v[92:95]
	v_mfma_f32_16x16x32_bf16 v[88:91], v[140:143], v[204:207], v[88:91]
	v_mfma_f32_16x16x32_bf16 v[76:79], v[132:135], v[212:215], v[76:79]
	v_mfma_f32_16x16x32_bf16 v[72:75], v[140:143], v[212:215], v[72:75]
	v_mfma_f32_16x16x32_bf16 v[116:119], v[216:219], v[144:147], v[116:119]
	v_mfma_f32_16x16x32_bf16 v[112:115], v[224:227], v[144:147], v[112:115]
	v_mfma_f32_16x16x32_bf16 v[100:103], v[216:219], v[152:155], v[100:103]
	v_mfma_f32_16x16x32_bf16 v[96:99], v[224:227], v[152:155], v[96:99]
	v_mfma_f32_16x16x32_bf16 v[84:87], v[216:219], v[200:203], v[84:87]
	v_mfma_f32_16x16x32_bf16 v[80:83], v[224:227], v[200:203], v[80:83]
	v_mfma_f32_16x16x32_bf16 v[68:71], v[216:219], v[208:211], v[68:71]
	v_mfma_f32_16x16x32_bf16 v[64:67], v[224:227], v[208:211], v[64:67]
	v_mfma_f32_16x16x32_bf16 v[116:119], v[220:223], v[148:151], v[116:119]
	v_mfma_f32_16x16x32_bf16 v[112:115], v[228:231], v[148:151], v[112:115]
	v_mfma_f32_16x16x32_bf16 v[100:103], v[220:223], v[196:199], v[100:103]
	v_mfma_f32_16x16x32_bf16 v[96:99], v[228:231], v[196:199], v[96:99]
	v_mfma_f32_16x16x32_bf16 v[84:87], v[220:223], v[204:207], v[84:87]
	v_mfma_f32_16x16x32_bf16 v[80:83], v[228:231], v[204:207], v[80:83]
	v_mfma_f32_16x16x32_bf16 v[68:71], v[220:223], v[212:215], v[68:71]
	v_mfma_f32_16x16x32_bf16 v[64:67], v[228:231], v[212:215], v[64:67]
	s_setprio 0
	s_barrier
	s_mov_b32 m0, s19
	v_lshl_add_u64 v[156:157], s[62:63], 0, v[160:161]
	global_load_lds_dwordx4 v[156:157], off
	v_lshl_add_u64 v[170:171], s[62:63], 0, v[158:159]
	s_mov_b32 m0, s20
	s_nop 0
	global_load_lds_dwordx4 v[170:171], off
	s_mov_b32 m0, s21
	v_lshl_add_u64 v[172:173], s[60:61], 0, v[160:161]
	global_load_lds_dwordx4 v[172:173], off
	v_lshl_add_u64 v[232:233], s[60:61], 0, v[158:159]
	s_mov_b32 m0, s22
	s_nop 0
	global_load_lds_dwordx4 v[232:233], off
	s_add_u32 s62, s62, s6
	s_addc_u32 s63, s63, s7
	s_mov_b32 m0, s24
	v_lshl_add_u64 v[234:235], s[62:63], 0, v[160:161]
	global_load_lds_dwordx4 v[234:235], off
	v_lshl_add_u64 v[236:237], s[62:63], 0, v[158:159]
	s_mov_b32 m0, s25
	s_nop 0
	global_load_lds_dwordx4 v[236:237], off
	ds_read_b128 v[144:147], v175 offset:16384
	ds_read_b128 v[148:151], v175 offset:17408
	ds_read_b128 v[152:155], v175 offset:18432
	ds_read_b128 v[196:199], v175 offset:19456
	ds_read_b128 v[200:203], v175 offset:20480
	ds_read_b128 v[204:207], v175 offset:21504
	ds_read_b128 v[208:211], v175 offset:22528
	ds_read_b128 v[212:215], v175 offset:23552
	s_waitcnt vmcnt(8)
	s_waitcnt lgkmcnt(0)
	s_barrier
; #define PG8_STAGE(bufoff, gbase) do { _Pragma("unroll") for (int _i = 0; _i < 2; ++_i) \
;         __builtin_amdgcn_global_load_lds((const unsigned*)((const char*)(gbase) + voffA[_i]), (LAS unsigned*)(lds + (bufoff) + ldsw + _i * 8192), 16, 0, 0); } while (0)
; #define PG8_LDA(dst, b, h) do { _Pragma("unroll") for (int m = 0; m < 4; ++m) _Pragma("unroll") for (int k = 0; k < 2; ++k) dst[m][k] = *(const LAS bf16x8*)(lds + PG8_SA(b, h) + aoff + m * 2048 + k * 1024); } while (0)
; #define PG8_LDB(dst, b, h) do { _Pragma("unroll") for (int n = 0; n < 2; ++n) _Pragma("unroll") for (int k = 0; k < 2; ++k) dst[n][k] = *(const LAS bf16x8*)(lds + PG8_SB(b, h) + boff + n * 2048 + k * 1024); } while (0)
; #define PG8_MMA(ai, bj, At, Bt) do { __builtin_amdgcn_s_setprio(1); _Pragma("unroll") for (int m = 0; m < 4; ++m) _Pragma("unroll") for (int n = 0; n < 2; ++n) _Pragma("unroll") for (int k = 0; k < 2; ++k) \
;         acc[ai][bj][m][n] = __builtin_amdgcn_mfma_f32_16x16x32_bf16(Bt[n][k], At[m][k], acc[ai][bj][m][n], 0, 0, 0); __builtin_amdgcn_s_setprio(0); } while (0)
; #define PG8_WAIT_V(n) asm volatile("s_waitcnt vmcnt(" #n ")" ::: "memory")
; #define PG8_WAIT_L(n) asm volatile("s_waitcnt lgkmcnt(" #n ")" ::: "memory")
; #define PG8_BAR __builtin_amdgcn_s_barrier()
; #define PG8_SCHED __builtin_amdgcn_sched_barrier(0)
; template <class Epi>
; DI void gemm_phase(const int TID, const int BID, LAS unsigned char* lds, const Gemm g, const Epi& E) {
;     ...
;             PG8_BAR; PG8_WAIT_L(0); PG8_MMA(0, 1, At, B1); PG8_BAR;
;             PG8_LDA(At, 0, 1); PG8_STAGE(PG8_SA(0, 0), a2);
;             PG8_BAR; PG8_WAIT_L(0); PG8_MMA(1, 0, At, B0); PG8_BAR; PG8_SCHED;
;             PG8_STAGE(PG8_SB(0, 1), b2 + hstep);
;             PG8_WAIT_V(6); PG8_BAR; PG8_MMA(1, 1, At, B1); PG8_BAR;
;             PG8_LDB(B0, 1, 0); PG8_SCHED; PG8_LDA(At, 1, 0); PG8_STAGE(PG8_SA(0, 1), a2 + hstep);
;             PG8_WAIT_L(8); PG8_BAR; PG8_WAIT_L(0); PG8_MMA(0, 0, At, B0); PG8_BAR; PG8_SCHED;
	s_setprio 1
	v_mfma_f32_16x16x32_bf16 v[60:63], v[128:131], v[144:147], v[60:63]
	v_mfma_f32_16x16x32_bf16 v[56:59], v[136:139], v[144:147], v[56:59]
	v_mfma_f32_16x16x32_bf16 v[44:47], v[128:131], v[152:155], v[44:47]
	v_mfma_f32_16x16x32_bf16 v[40:43], v[136:139], v[152:155], v[40:43]
	v_mfma_f32_16x16x32_bf16 v[28:31], v[128:131], v[200:203], v[28:31]
	v_mfma_f32_16x16x32_bf16 v[24:27], v[136:139], v[200:203], v[24:27]
	v_mfma_f32_16x16x32_bf16 v[12:15], v[128:131], v[208:211], v[12:15]
	v_mfma_f32_16x16x32_bf16 v[8:11], v[136:139], v[208:211], v[8:11]
	v_mfma_f32_16x16x32_bf16 v[60:63], v[132:135], v[148:151], v[60:63]
	v_mfma_f32_16x16x32_bf16 v[56:59], v[140:143], v[148:151], v[56:59]
	v_mfma_f32_16x16x32_bf16 v[44:47], v[132:135], v[196:199], v[44:47]
	v_mfma_f32_16x16x32_bf16 v[40:43], v[140:143], v[196:199], v[40:43]
	v_mfma_f32_16x16x32_bf16 v[28:31], v[132:135], v[204:207], v[28:31]
	v_mfma_f32_16x16x32_bf16 v[24:27], v[140:143], v[204:207], v[24:27]
	v_mfma_f32_16x16x32_bf16 v[12:15], v[132:135], v[212:215], v[12:15]
	v_mfma_f32_16x16x32_bf16 v[8:11], v[140:143], v[212:215], v[8:11]
	v_mfma_f32_16x16x32_bf16 v[52:55], v[216:219], v[144:147], v[52:55]
	v_mfma_f32_16x16x32_bf16 v[48:51], v[224:227], v[144:147], v[48:51]
	v_mfma_f32_16x16x32_bf16 v[36:39], v[216:219], v[152:155], v[36:39]
	v_mfma_f32_16x16x32_bf16 v[32:35], v[224:227], v[152:155], v[32:35]
	v_mfma_f32_16x16x32_bf16 v[20:23], v[216:219], v[200:203], v[20:23]
	v_mfma_f32_16x16x32_bf16 v[16:19], v[224:227], v[200:203], v[16:19]
	v_mfma_f32_16x16x32_bf16 v[4:7], v[216:219], v[208:211], v[4:7]
	v_mfma_f32_16x16x32_bf16 v[0:3], v[224:227], v[208:211], v[0:3]
	v_mfma_f32_16x16x32_bf16 v[52:55], v[220:223], v[148:151], v[52:55]
	v_mfma_f32_16x16x32_bf16 v[48:51], v[228:231], v[148:151], v[48:51]
	v_mfma_f32_16x16x32_bf16 v[36:39], v[220:223], v[196:199], v[36:39]
	v_mfma_f32_16x16x32_bf16 v[32:35], v[228:231], v[196:199], v[32:35]
	v_mfma_f32_16x16x32_bf16 v[20:23], v[220:223], v[204:207], v[20:23]
	v_mfma_f32_16x16x32_bf16 v[16:19], v[228:231], v[204:207], v[16:19]
	v_mfma_f32_16x16x32_bf16 v[4:7], v[220:223], v[212:215], v[4:7]
	v_mfma_f32_16x16x32_bf16 v[0:3], v[228:231], v[212:215], v[0:3]
	s_setprio 0
	s_barrier
	s_add_u32 s60, s60, s6
	s_addc_u32 s61, s61, s7
	s_mov_b32 m0, s26
	v_lshl_add_u64 v[216:217], s[60:61], 0, v[160:161]
	global_load_lds_dwordx4 v[216:217], off
	v_lshl_add_u64 v[216:217], s[60:61], 0, v[158:159]
	s_mov_b32 m0, s27
	s_nop 0
	global_load_lds_dwordx4 v[216:217], off
	v_add_u32_e32 v140, s28, v192
	ds_read_b128 v[128:131], v140
	ds_read_b128 v[132:135], v140 offset:1024
	ds_read_b128 v[136:139], v140 offset:2048
	ds_read_b128 v[140:143], v140 offset:3072
	ds_read_b128 v[144:147], v175 offset:32768
	ds_read_b128 v[148:151], v175 offset:33792
	ds_read_b128 v[152:155], v175 offset:34816
	ds_read_b128 v[196:199], v175 offset:35840
	ds_read_b128 v[200:203], v175 offset:36864
	ds_read_b128 v[204:207], v175 offset:37888
	ds_read_b128 v[208:211], v175 offset:38912
	ds_read_b128 v[212:215], v175 offset:39936
	v_add_u32_e32 v195, s64, v192
	ds_read_b128 v[216:219], v195
	ds_read_b128 v[220:223], v195 offset:1024
	ds_read_b128 v[224:227], v195 offset:2048
	ds_read_b128 v[228:231], v195 offset:3072
	s_waitcnt vmcnt(8)
	s_waitcnt lgkmcnt(0)
	s_barrier
	s_setprio 1
	v_mfma_f32_16x16x32_bf16 v[124:127], v[128:131], v[144:147], v[124:127]
	v_mfma_f32_16x16x32_bf16 v[120:123], v[136:139], v[144:147], v[120:123]
	v_mfma_f32_16x16x32_bf16 v[108:111], v[128:131], v[152:155], v[108:111]
	v_mfma_f32_16x16x32_bf16 v[104:107], v[136:139], v[152:155], v[104:107]
	v_mfma_f32_16x16x32_bf16 v[92:95], v[128:131], v[200:203], v[92:95]
	v_mfma_f32_16x16x32_bf16 v[88:91], v[136:139], v[200:203], v[88:91]
	v_mfma_f32_16x16x32_bf16 v[76:79], v[128:131], v[208:211], v[76:79]
	v_mfma_f32_16x16x32_bf16 v[72:75], v[136:139], v[208:211], v[72:75]
	v_mfma_f32_16x16x32_bf16 v[124:127], v[132:135], v[148:151], v[124:127]
	v_mfma_f32_16x16x32_bf16 v[120:123], v[140:143], v[148:151], v[120:123]
	v_mfma_f32_16x16x32_bf16 v[108:111], v[132:135], v[196:199], v[108:111]
	v_mfma_f32_16x16x32_bf16 v[104:107], v[140:143], v[196:199], v[104:107]
	v_mfma_f32_16x16x32_bf16 v[92:95], v[132:135], v[204:207], v[92:95]
	v_mfma_f32_16x16x32_bf16 v[88:91], v[140:143], v[204:207], v[88:91]
	v_mfma_f32_16x16x32_bf16 v[76:79], v[132:135], v[212:215], v[76:79]
	v_mfma_f32_16x16x32_bf16 v[72:75], v[140:143], v[212:215], v[72:75]
	v_mfma_f32_16x16x32_bf16 v[116:119], v[216:219], v[144:147], v[116:119]
	v_mfma_f32_16x16x32_bf16 v[112:115], v[224:227], v[144:147], v[112:115]
	v_mfma_f32_16x16x32_bf16 v[100:103], v[216:219], v[152:155], v[100:103]
	v_mfma_f32_16x16x32_bf16 v[96:99], v[224:227], v[152:155], v[96:99]
	v_mfma_f32_16x16x32_bf16 v[84:87], v[216:219], v[200:203], v[84:87]
	v_mfma_f32_16x16x32_bf16 v[80:83], v[224:227], v[200:203], v[80:83]
	v_mfma_f32_16x16x32_bf16 v[68:71], v[216:219], v[208:211], v[68:71]
	v_mfma_f32_16x16x32_bf16 v[64:67], v[224:227], v[208:211], v[64:67]
	v_mfma_f32_16x16x32_bf16 v[116:119], v[220:223], v[148:151], v[116:119]
	v_mfma_f32_16x16x32_bf16 v[112:115], v[228:231], v[148:151], v[112:115]
	v_mfma_f32_16x16x32_bf16 v[100:103], v[220:223], v[196:199], v[100:103]
	v_mfma_f32_16x16x32_bf16 v[96:99], v[228:231], v[196:199], v[96:99]
	v_mfma_f32_16x16x32_bf16 v[84:87], v[220:223], v[204:207], v[84:87]
	v_mfma_f32_16x16x32_bf16 v[80:83], v[228:231], v[204:207], v[80:83]
	v_mfma_f32_16x16x32_bf16 v[68:71], v[220:223], v[212:215], v[68:71]
	v_mfma_f32_16x16x32_bf16 v[64:67], v[228:231], v[212:215], v[64:67]
	s_setprio 0
	s_barrier
; #define PG8_STAGE(bufoff, gbase) do { _Pragma("unroll") for (int _i = 0; _i < 2; ++_i) \
;         __builtin_amdgcn_global_load_lds((const unsigned*)((const char*)(gbase) + voffA[_i]), (LAS unsigned*)(lds + (bufoff) + ldsw + _i * 8192), 16, 0, 0); } while (0)
; #define PG8_LDA(dst, b, h) do { _Pragma("unroll") for (int m = 0; m < 4; ++m) _Pragma("unroll") for (int k = 0; k < 2; ++k) dst[m][k] = *(const LAS bf16x8*)(lds + PG8_SA(b, h) + aoff + m * 2048 + k * 1024); } while (0)
; #define PG8_LDB(dst, b, h) do { _Pragma("unroll") for (int n = 0; n < 2; ++n) _Pragma("unroll") for (int k = 0; k < 2; ++k) dst[n][k] = *(const LAS bf16x8*)(lds + PG8_SB(b, h) + boff + n * 2048 + k * 1024); } while (0)
; #define PG8_MMA(ai, bj, At, Bt) do { __builtin_amdgcn_s_setprio(1); _Pragma("unroll") for (int m = 0; m < 4; ++m) _Pragma("unroll") for (int n = 0; n < 2; ++n) _Pragma("unroll") for (int k = 0; k < 2; ++k) \
;         acc[ai][bj][m][n] = __builtin_amdgcn_mfma_f32_16x16x32_bf16(Bt[n][k], At[m][k], acc[ai][bj][m][n], 0, 0, 0); __builtin_amdgcn_s_setprio(0); } while (0)
; #define PG8_WAIT_V(n) asm volatile("s_waitcnt vmcnt(" #n ")" ::: "memory")
; #define PG8_WAIT_L(n) asm volatile("s_waitcnt lgkmcnt(" #n ")" ::: "memory")
; #define PG8_BAR __builtin_amdgcn_s_barrier()
; #define PG8_SCHED __builtin_amdgcn_sched_barrier(0)
; template <class Epi>
; DI void gemm_phase(const int TID, const int BID, LAS unsigned char* lds, const Gemm g, const Epi& E) {
;     ...
;             PG8_LDB(B1, 1, 1); PG8_STAGE(PG8_SB(1, 0), b3);
;             PG8_BAR; PG8_WAIT_L(0); PG8_MMA(0, 1, At, B1); PG8_BAR;
;             PG8_LDA(At, 1, 1); PG8_STAGE(PG8_SA(1, 0), a3);
;             PG8_BAR; PG8_WAIT_L(0); PG8_MMA(1, 0, At, B0); PG8_BAR; PG8_SCHED;
;             PG8_STAGE(PG8_SB(1, 1), b3 + hstep);
;             PG8_WAIT_V(6); PG8_BAR; PG8_MMA(1, 1, At, B1); PG8_BAR;
;         }
	s_mov_b32 m0, s29
	v_lshl_add_u64 v[156:157], v[156:157], 0, s[92:93]
	global_load_lds_dwordx4 v[156:157], off
	v_lshl_add_u64 v[156:157], v[170:171], 0, s[92:93]
	s_mov_b32 m0, s30
	s_nop 0
	global_load_lds_dwordx4 v[156:157], off
	s_mov_b32 m0, s31
	v_lshl_add_u64 v[156:157], v[172:173], 0, s[92:93]
	global_load_lds_dwordx4 v[156:157], off
	v_lshl_add_u64 v[156:157], v[232:233], 0, s[92:93]
	s_mov_b32 m0, s33
	s_nop 0
	global_load_lds_dwordx4 v[156:157], off
	s_mov_b32 m0, s65
	v_lshl_add_u64 v[156:157], v[234:235], 0, s[92:93]
	global_load_lds_dwordx4 v[156:157], off
	v_lshl_add_u64 v[156:157], v[236:237], 0, s[92:93]
	s_mov_b32 m0, s66
	s_nop 0
	global_load_lds_dwordx4 v[156:157], off
	ds_read_b128 v[144:147], v175 offset:49152
	ds_read_b128 v[148:151], v175 offset:50176
	ds_read_b128 v[152:155], v175 offset:51200
	ds_read_b128 v[196:199], v175 offset:52224
	ds_read_b128 v[200:203], v175 offset:53248
	ds_read_b128 v[204:207], v175 offset:54272
	ds_read_b128 v[208:211], v175 offset:55296
	ds_read_b128 v[212:215], v175 offset:56320
	s_waitcnt vmcnt(8)
	s_waitcnt lgkmcnt(0)
	s_barrier
	s_setprio 1
	v_mfma_f32_16x16x32_bf16 v[60:63], v[128:131], v[144:147], v[60:63]
	v_mfma_f32_16x16x32_bf16 v[56:59], v[136:139], v[144:147], v[56:59]
	v_mfma_f32_16x16x32_bf16 v[44:47], v[128:131], v[152:155], v[44:47]
	v_mfma_f32_16x16x32_bf16 v[40:43], v[136:139], v[152:155], v[40:43]
	v_mfma_f32_16x16x32_bf16 v[28:31], v[128:131], v[200:203], v[28:31]
	v_mfma_f32_16x16x32_bf16 v[24:27], v[136:139], v[200:203], v[24:27]
	v_mfma_f32_16x16x32_bf16 v[12:15], v[128:131], v[208:211], v[12:15]
	v_mfma_f32_16x16x32_bf16 v[8:11], v[136:139], v[208:211], v[8:11]
	v_mfma_f32_16x16x32_bf16 v[60:63], v[132:135], v[148:151], v[60:63]
	v_mfma_f32_16x16x32_bf16 v[56:59], v[140:143], v[148:151], v[56:59]
	v_mfma_f32_16x16x32_bf16 v[44:47], v[132:135], v[196:199], v[44:47]
	v_mfma_f32_16x16x32_bf16 v[40:43], v[140:143], v[196:199], v[40:43]
	v_mfma_f32_16x16x32_bf16 v[28:31], v[132:135], v[204:207], v[28:31]
	v_mfma_f32_16x16x32_bf16 v[24:27], v[140:143], v[204:207], v[24:27]
	v_mfma_f32_16x16x32_bf16 v[12:15], v[132:135], v[212:215], v[12:15]
	v_mfma_f32_16x16x32_bf16 v[8:11], v[140:143], v[212:215], v[8:11]
	v_mfma_f32_16x16x32_bf16 v[52:55], v[216:219], v[144:147], v[52:55]
	v_mfma_f32_16x16x32_bf16 v[48:51], v[224:227], v[144:147], v[48:51]
	v_mfma_f32_16x16x32_bf16 v[36:39], v[216:219], v[152:155], v[36:39]
	v_mfma_f32_16x16x32_bf16 v[32:35], v[224:227], v[152:155], v[32:35]
	v_mfma_f32_16x16x32_bf16 v[20:23], v[216:219], v[200:203], v[20:23]
	v_mfma_f32_16x16x32_bf16 v[16:19], v[224:227], v[200:203], v[16:19]
	v_mfma_f32_16x16x32_bf16 v[4:7], v[216:219], v[208:211], v[4:7]
	v_mfma_f32_16x16x32_bf16 v[0:3], v[224:227], v[208:211], v[0:3]
	v_mfma_f32_16x16x32_bf16 v[52:55], v[220:223], v[148:151], v[52:55]
	v_mfma_f32_16x16x32_bf16 v[48:51], v[228:231], v[148:151], v[48:51]
	v_mfma_f32_16x16x32_bf16 v[36:39], v[220:223], v[196:199], v[36:39]
	v_mfma_f32_16x16x32_bf16 v[32:35], v[228:231], v[196:199], v[32:35]
	v_mfma_f32_16x16x32_bf16 v[20:23], v[220:223], v[204:207], v[20:23]
	v_mfma_f32_16x16x32_bf16 v[16:19], v[228:231], v[204:207], v[16:19]
	v_mfma_f32_16x16x32_bf16 v[4:7], v[220:223], v[212:215], v[4:7]
	v_mfma_f32_16x16x32_bf16 v[0:3], v[228:231], v[212:215], v[0:3]
	s_setprio 0
	s_add_u32 s4, s4, 0x100
	s_addc_u32 s5, s5, 0
	s_add_u32 vcc_lo, vcc_lo, 0x100
	s_addc_u32 vcc_hi, vcc_hi, 0
	s_cmp_ge_i32 s16, s67
	s_mov_b32 s60, s16
	s_barrier
	s_cbranch_scc0 .LBB0_491

; #define PG8_STAGE(bufoff, gbase) do { _Pragma("unroll") for (int _i = 0; _i < 2; ++_i) \
;         __builtin_amdgcn_global_load_lds((const unsigned*)((const char*)(gbase) + voffA[_i]), (LAS unsigned*)(lds + (bufoff) + ldsw + _i * 8192), 16, 0, 0); } while (0)
; #define PG8_LDA(dst, b, h) do { _Pragma("unroll") for (int m = 0; m < 4; ++m) _Pragma("unroll") for (int k = 0; k < 2; ++k) dst[m][k] = *(const LAS bf16x8*)(lds + PG8_SA(b, h) + aoff + m * 2048 + k * 1024); } while (0)
; #define PG8_LDB(dst, b, h) do { _Pragma("unroll") for (int n = 0; n < 2; ++n) _Pragma("unroll") for (int k = 0; k < 2; ++k) dst[n][k] = *(const LAS bf16x8*)(lds + PG8_SB(b, h) + boff + n * 2048 + k * 1024); } while (0)
; #define PG8_MMA(ai, bj, At, Bt) do { __builtin_amdgcn_s_setprio(1); _Pragma("unroll") for (int m = 0; m < 4; ++m) _Pragma("unroll") for (int n = 0; n < 2; ++n) _Pragma("unroll") for (int k = 0; k < 2; ++k) \
;         acc[ai][bj][m][n] = __builtin_amdgcn_mfma_f32_16x16x32_bf16(Bt[n][k], At[m][k], acc[ai][bj][m][n], 0, 0, 0); __builtin_amdgcn_s_setprio(0); } while (0)
; #define PG8_WAIT_L(n) asm volatile("s_waitcnt lgkmcnt(" #n ")" ::: "memory")
; #define PG8_BAR __builtin_amdgcn_s_barrier()
; #define PG8_SCHED __builtin_amdgcn_sched_barrier(0)
; template <class Epi>
; DI void gemm_phase(const int TID, const int BID, LAS unsigned char* lds, const Gemm g, const Epi& E) {
;     ...
;         for (int t = 0; t < nt; t += 2) {
;             const bool last = (t == nt - 2);
;             const char* a1 = cA + (size_t)(t + 1) * kstep;
;             const char* a2 = last ? nA : cA + (size_t)(t + 2) * kstep; const char* b2 = last ? nB : cB + (size_t)(t + 2) * kstep;
;             const char* a3 = a2 + kstep; const char* b3 = b2 + kstep;
;             PG8_LDB(B0, 0, 0); PG8_SCHED; PG8_LDA(At, 0, 0); PG8_STAGE(PG8_SA(1, 1), a1 + hstep);
;             PG8_WAIT_L(8); PG8_BAR; PG8_WAIT_L(0); PG8_MMA(0, 0, At, B0); PG8_BAR; PG8_SCHED;
;             PG8_LDB(B1, 0, 1); PG8_STAGE(PG8_SB(0, 0), b2);
;             PG8_BAR; PG8_WAIT_L(0); PG8_MMA(0, 1, At, B1); PG8_BAR;
.LBB0_568:
	s_add_i32 s31, s30, 2
	s_add_u32 s56, s4, 0x80
	s_addc_u32 s57, s5, 0
	s_cmp_eq_u32 s22, s30
	s_cselect_b32 s57, s53, s57
	s_cselect_b32 s56, s52, s56
	s_cselect_b32 s59, s55, s29
	s_cselect_b32 s58, s54, s28
	v_lshl_add_u64 v[170:171], s[4:5], 0, v[152:153]
	s_add_i32 m0, s62, 0xc000
	global_load_lds_dwordx4 v[170:171], off
	v_lshl_add_u64 v[170:171], s[4:5], 0, v[154:155]
	s_add_i32 m0, s62, 0xe000
	s_nop 0
	global_load_lds_dwordx4 v[170:171], off
	v_add_u32_e32 v168, s65, v161
	ds_read_b128 v[156:159], v168
	ds_read_b128 v[176:179], v168 offset:1024
	ds_read_b128 v[180:183], v168 offset:2048
	ds_read_b128 v[184:187], v168 offset:3072
	ds_read_b128 v[188:191], v175
	ds_read_b128 v[192:195], v175 offset:1024
	ds_read_b128 v[196:199], v175 offset:2048
	ds_read_b128 v[200:203], v175 offset:3072
	ds_read_b128 v[204:207], v175 offset:4096
	ds_read_b128 v[208:211], v175 offset:5120
	ds_read_b128 v[212:215], v175 offset:6144
	ds_read_b128 v[216:219], v175 offset:7168
	v_add_u32_e32 v168, s64, v161
	ds_read_b128 v[220:223], v168
	ds_read_b128 v[224:227], v168 offset:1024
	ds_read_b128 v[228:231], v168 offset:2048
	ds_read_b128 v[246:249], v168 offset:3072
	s_waitcnt vmcnt(8)
	s_waitcnt lgkmcnt(0)
	s_barrier
	s_setprio 1
	v_mfma_f32_16x16x32_bf16 v[124:127], v[156:159], v[188:191], v[124:127]
	v_mfma_f32_16x16x32_bf16 v[120:123], v[180:183], v[188:191], v[120:123]
	v_mfma_f32_16x16x32_bf16 v[116:119], v[156:159], v[196:199], v[116:119]
	v_mfma_f32_16x16x32_bf16 v[112:115], v[180:183], v[196:199], v[112:115]
	v_mfma_f32_16x16x32_bf16 v[108:111], v[156:159], v[204:207], v[108:111]
	v_mfma_f32_16x16x32_bf16 v[104:107], v[180:183], v[204:207], v[104:107]
	v_mfma_f32_16x16x32_bf16 v[100:103], v[156:159], v[212:215], v[100:103]
	v_mfma_f32_16x16x32_bf16 v[96:99], v[180:183], v[212:215], v[96:99]
	v_mfma_f32_16x16x32_bf16 v[124:127], v[176:179], v[192:195], v[124:127]
	v_mfma_f32_16x16x32_bf16 v[120:123], v[184:187], v[192:195], v[120:123]
	v_mfma_f32_16x16x32_bf16 v[116:119], v[176:179], v[200:203], v[116:119]
	v_mfma_f32_16x16x32_bf16 v[112:115], v[184:187], v[200:203], v[112:115]
	v_mfma_f32_16x16x32_bf16 v[108:111], v[176:179], v[208:211], v[108:111]
	v_mfma_f32_16x16x32_bf16 v[104:107], v[184:187], v[208:211], v[104:107]
	v_mfma_f32_16x16x32_bf16 v[100:103], v[176:179], v[216:219], v[100:103]
	v_mfma_f32_16x16x32_bf16 v[96:99], v[184:187], v[216:219], v[96:99]
	v_mfma_f32_16x16x32_bf16 v[56:59], v[220:223], v[188:191], v[56:59]
	v_mfma_f32_16x16x32_bf16 v[60:63], v[228:231], v[188:191], v[60:63]
	v_mfma_f32_16x16x32_bf16 v[52:55], v[220:223], v[196:199], v[52:55]
	v_mfma_f32_16x16x32_bf16 v[48:51], v[228:231], v[196:199], v[48:51]
	v_mfma_f32_16x16x32_bf16 v[44:47], v[220:223], v[204:207], v[44:47]
	v_mfma_f32_16x16x32_bf16 v[40:43], v[228:231], v[204:207], v[40:43]
	v_mfma_f32_16x16x32_bf16 v[36:39], v[220:223], v[212:215], v[36:39]
	v_mfma_f32_16x16x32_bf16 v[32:35], v[228:231], v[212:215], v[32:35]
	v_mfma_f32_16x16x32_bf16 v[56:59], v[224:227], v[192:195], v[56:59]
	v_mfma_f32_16x16x32_bf16 v[60:63], v[246:249], v[192:195], v[60:63]
	v_mfma_f32_16x16x32_bf16 v[52:55], v[224:227], v[200:203], v[52:55]
	v_mfma_f32_16x16x32_bf16 v[48:51], v[246:249], v[200:203], v[48:51]
	v_mfma_f32_16x16x32_bf16 v[44:47], v[224:227], v[208:211], v[44:47]
	v_mfma_f32_16x16x32_bf16 v[40:43], v[246:249], v[208:211], v[40:43]
	v_mfma_f32_16x16x32_bf16 v[36:39], v[224:227], v[216:219], v[36:39]
	v_mfma_f32_16x16x32_bf16 v[32:35], v[246:249], v[216:219], v[32:35]
	s_setprio 0
	s_barrier
	s_mov_b32 m0, s66
	v_lshl_add_u64 v[170:171], s[58:59], 0, v[128:129]
	global_load_lds_dwordx4 v[170:171], off
	v_lshl_add_u64 v[172:173], s[58:59], 0, v[130:131]
	s_mov_b32 m0, s67
	s_nop 0
	global_load_lds_dwordx4 v[172:173], off
	s_mov_b32 m0, s62
	v_lshl_add_u64 v[232:233], s[56:57], 0, v[128:129]
	global_load_lds_dwordx4 v[232:233], off
	v_lshl_add_u64 v[234:235], s[56:57], 0, v[130:131]
	s_mov_b32 m0, s63
	s_nop 0
	global_load_lds_dwordx4 v[234:235], off
	s_add_u32 s58, s58, s6
	s_addc_u32 s59, s59, s7
	s_mov_b32 m0, s10
	v_lshl_add_u64 v[236:237], s[58:59], 0, v[128:129]
	global_load_lds_dwordx4 v[236:237], off
	v_lshl_add_u64 v[238:239], s[58:59], 0, v[130:131]
	s_mov_b32 m0, s11
	s_nop 0
	global_load_lds_dwordx4 v[238:239], off
	ds_read_b128 v[188:191], v175 offset:16384
	ds_read_b128 v[192:195], v175 offset:17408
	ds_read_b128 v[196:199], v175 offset:18432
	ds_read_b128 v[200:203], v175 offset:19456
	ds_read_b128 v[204:207], v175 offset:20480
	ds_read_b128 v[208:211], v175 offset:21504
	ds_read_b128 v[212:215], v175 offset:22528
	ds_read_b128 v[216:219], v175 offset:23552
	s_waitcnt vmcnt(8)
	s_waitcnt lgkmcnt(0)
	s_barrier
; #define PG8_STAGE(bufoff, gbase) do { _Pragma("unroll") for (int _i = 0; _i < 2; ++_i) \
;         __builtin_amdgcn_global_load_lds((const unsigned*)((const char*)(gbase) + voffA[_i]), (LAS unsigned*)(lds + (bufoff) + ldsw + _i * 8192), 16, 0, 0); } while (0)
; #define PG8_LDA(dst, b, h) do { _Pragma("unroll") for (int m = 0; m < 4; ++m) _Pragma("unroll") for (int k = 0; k < 2; ++k) dst[m][k] = *(const LAS bf16x8*)(lds + PG8_SA(b, h) + aoff + m * 2048 + k * 1024); } while (0)
; #define PG8_LDB(dst, b, h) do { _Pragma("unroll") for (int n = 0; n < 2; ++n) _Pragma("unroll") for (int k = 0; k < 2; ++k) dst[n][k] = *(const LAS bf16x8*)(lds + PG8_SB(b, h) + boff + n * 2048 + k * 1024); } while (0)
; #define PG8_MMA(ai, bj, At, Bt) do { __builtin_amdgcn_s_setprio(1); _Pragma("unroll") for (int m = 0; m < 4; ++m) _Pragma("unroll") for (int n = 0; n < 2; ++n) _Pragma("unroll") for (int k = 0; k < 2; ++k) \
;         acc[ai][bj][m][n] = __builtin_amdgcn_mfma_f32_16x16x32_bf16(Bt[n][k], At[m][k], acc[ai][bj][m][n], 0, 0, 0); __builtin_amdgcn_s_setprio(0); } while (0)
; #define PG8_WAIT_V(n) asm volatile("s_waitcnt vmcnt(" #n ")" ::: "memory")
; #define PG8_WAIT_L(n) asm volatile("s_waitcnt lgkmcnt(" #n ")" ::: "memory")
; #define PG8_BAR __builtin_amdgcn_s_barrier()
; #define PG8_SCHED __builtin_amdgcn_sched_barrier(0)
; template <class Epi>
; DI void gemm_phase(const int TID, const int BID, LAS unsigned char* lds, const Gemm g, const Epi& E) {
;     ...
;             PG8_BAR; PG8_WAIT_L(0); PG8_MMA(0, 1, At, B1); PG8_BAR;
;             PG8_LDA(At, 0, 1); PG8_STAGE(PG8_SA(0, 0), a2);
;             PG8_BAR; PG8_WAIT_L(0); PG8_MMA(1, 0, At, B0); PG8_BAR; PG8_SCHED;
;             PG8_STAGE(PG8_SB(0, 1), b2 + hstep);
;             PG8_WAIT_V(6); PG8_BAR; PG8_MMA(1, 1, At, B1); PG8_BAR;
;             PG8_LDB(B0, 1, 0); PG8_SCHED; PG8_LDA(At, 1, 0); PG8_STAGE(PG8_SA(0, 1), a2 + hstep);
;             PG8_WAIT_L(8); PG8_BAR; PG8_WAIT_L(0); PG8_MMA(0, 0, At, B0); PG8_BAR; PG8_SCHED;
	s_setprio 1
	v_mfma_f32_16x16x32_bf16 v[92:95], v[156:159], v[188:191], v[92:95]
	v_mfma_f32_16x16x32_bf16 v[88:91], v[180:183], v[188:191], v[88:91]
	v_mfma_f32_16x16x32_bf16 v[84:87], v[156:159], v[196:199], v[84:87]
	v_mfma_f32_16x16x32_bf16 v[80:83], v[180:183], v[196:199], v[80:83]
	v_mfma_f32_16x16x32_bf16 v[76:79], v[156:159], v[204:207], v[76:79]
	v_mfma_f32_16x16x32_bf16 v[72:75], v[180:183], v[204:207], v[72:75]
	v_mfma_f32_16x16x32_bf16 v[68:71], v[156:159], v[212:215], v[68:71]
	v_mfma_f32_16x16x32_bf16 v[64:67], v[180:183], v[212:215], v[64:67]
	v_mfma_f32_16x16x32_bf16 v[92:95], v[176:179], v[192:195], v[92:95]
	v_mfma_f32_16x16x32_bf16 v[88:91], v[184:187], v[192:195], v[88:91]
	v_mfma_f32_16x16x32_bf16 v[84:87], v[176:179], v[200:203], v[84:87]
	v_mfma_f32_16x16x32_bf16 v[80:83], v[184:187], v[200:203], v[80:83]
	v_mfma_f32_16x16x32_bf16 v[76:79], v[176:179], v[208:211], v[76:79]
	v_mfma_f32_16x16x32_bf16 v[72:75], v[184:187], v[208:211], v[72:75]
	v_mfma_f32_16x16x32_bf16 v[68:71], v[176:179], v[216:219], v[68:71]
	v_mfma_f32_16x16x32_bf16 v[64:67], v[184:187], v[216:219], v[64:67]
	v_mfma_f32_16x16x32_bf16 v[28:31], v[220:223], v[188:191], v[28:31]
	v_mfma_f32_16x16x32_bf16 v[24:27], v[228:231], v[188:191], v[24:27]
	v_mfma_f32_16x16x32_bf16 v[20:23], v[220:223], v[196:199], v[20:23]
	v_mfma_f32_16x16x32_bf16 v[16:19], v[228:231], v[196:199], v[16:19]
	v_mfma_f32_16x16x32_bf16 v[12:15], v[220:223], v[204:207], v[12:15]
	v_mfma_f32_16x16x32_bf16 v[8:11], v[228:231], v[204:207], v[8:11]
	v_mfma_f32_16x16x32_bf16 v[4:7], v[220:223], v[212:215], v[4:7]
	v_mfma_f32_16x16x32_bf16 v[0:3], v[228:231], v[212:215], v[0:3]
	v_mfma_f32_16x16x32_bf16 v[28:31], v[224:227], v[192:195], v[28:31]
	v_mfma_f32_16x16x32_bf16 v[24:27], v[246:249], v[192:195], v[24:27]
	v_mfma_f32_16x16x32_bf16 v[20:23], v[224:227], v[200:203], v[20:23]
	v_mfma_f32_16x16x32_bf16 v[16:19], v[246:249], v[200:203], v[16:19]
	v_mfma_f32_16x16x32_bf16 v[12:15], v[224:227], v[208:211], v[12:15]
	v_mfma_f32_16x16x32_bf16 v[8:11], v[246:249], v[208:211], v[8:11]
	v_mfma_f32_16x16x32_bf16 v[4:7], v[224:227], v[216:219], v[4:7]
	v_mfma_f32_16x16x32_bf16 v[0:3], v[246:249], v[216:219], v[0:3]
	s_setprio 0
	s_barrier
	s_add_u32 s56, s56, s6
	s_addc_u32 s57, s57, s7
	s_mov_b32 m0, s33
	v_lshl_add_u64 v[220:221], s[56:57], 0, v[128:129]
	global_load_lds_dwordx4 v[220:221], off
	v_lshl_add_u64 v[220:221], s[56:57], 0, v[130:131]
	s_mov_b32 m0, s15
	s_nop 0
	global_load_lds_dwordx4 v[220:221], off
	v_add_u32_e32 v168, s76, v161
	ds_read_b128 v[156:159], v168
	ds_read_b128 v[176:179], v168 offset:1024
	ds_read_b128 v[180:183], v168 offset:2048
	ds_read_b128 v[184:187], v168 offset:3072
	ds_read_b128 v[188:191], v175 offset:32768
	ds_read_b128 v[192:195], v175 offset:33792
	ds_read_b128 v[196:199], v175 offset:34816
	ds_read_b128 v[200:203], v175 offset:35840
	ds_read_b128 v[204:207], v175 offset:36864
	ds_read_b128 v[208:211], v175 offset:37888
	ds_read_b128 v[212:215], v175 offset:38912
	ds_read_b128 v[216:219], v175 offset:39936
	v_add_u32_e32 v168, s9, v161
	ds_read_b128 v[220:223], v168
	ds_read_b128 v[224:227], v168 offset:1024
	ds_read_b128 v[228:231], v168 offset:2048
	ds_read_b128 v[246:249], v168 offset:3072
	s_waitcnt vmcnt(8)
	s_waitcnt lgkmcnt(0)
	s_barrier
	s_setprio 1
	v_mfma_f32_16x16x32_bf16 v[124:127], v[156:159], v[188:191], v[124:127]
	v_mfma_f32_16x16x32_bf16 v[120:123], v[180:183], v[188:191], v[120:123]
	v_mfma_f32_16x16x32_bf16 v[116:119], v[156:159], v[196:199], v[116:119]
	v_mfma_f32_16x16x32_bf16 v[112:115], v[180:183], v[196:199], v[112:115]
	v_mfma_f32_16x16x32_bf16 v[108:111], v[156:159], v[204:207], v[108:111]
	v_mfma_f32_16x16x32_bf16 v[104:107], v[180:183], v[204:207], v[104:107]
	v_mfma_f32_16x16x32_bf16 v[100:103], v[156:159], v[212:215], v[100:103]
	v_mfma_f32_16x16x32_bf16 v[96:99], v[180:183], v[212:215], v[96:99]
	v_mfma_f32_16x16x32_bf16 v[124:127], v[176:179], v[192:195], v[124:127]
	v_mfma_f32_16x16x32_bf16 v[120:123], v[184:187], v[192:195], v[120:123]
	v_mfma_f32_16x16x32_bf16 v[116:119], v[176:179], v[200:203], v[116:119]
	v_mfma_f32_16x16x32_bf16 v[112:115], v[184:187], v[200:203], v[112:115]
	v_mfma_f32_16x16x32_bf16 v[108:111], v[176:179], v[208:211], v[108:111]
	v_mfma_f32_16x16x32_bf16 v[104:107], v[184:187], v[208:211], v[104:107]
	v_mfma_f32_16x16x32_bf16 v[100:103], v[176:179], v[216:219], v[100:103]
	v_mfma_f32_16x16x32_bf16 v[96:99], v[184:187], v[216:219], v[96:99]
	v_mfma_f32_16x16x32_bf16 v[56:59], v[220:223], v[188:191], v[56:59]
	v_mfma_f32_16x16x32_bf16 v[60:63], v[228:231], v[188:191], v[60:63]
	v_mfma_f32_16x16x32_bf16 v[52:55], v[220:223], v[196:199], v[52:55]
	v_mfma_f32_16x16x32_bf16 v[48:51], v[228:231], v[196:199], v[48:51]
	v_mfma_f32_16x16x32_bf16 v[44:47], v[220:223], v[204:207], v[44:47]
	v_mfma_f32_16x16x32_bf16 v[40:43], v[228:231], v[204:207], v[40:43]
	v_mfma_f32_16x16x32_bf16 v[36:39], v[220:223], v[212:215], v[36:39]
	v_mfma_f32_16x16x32_bf16 v[32:35], v[228:231], v[212:215], v[32:35]
	v_mfma_f32_16x16x32_bf16 v[56:59], v[224:227], v[192:195], v[56:59]
	v_mfma_f32_16x16x32_bf16 v[60:63], v[246:249], v[192:195], v[60:63]
	v_mfma_f32_16x16x32_bf16 v[52:55], v[224:227], v[200:203], v[52:55]
	v_mfma_f32_16x16x32_bf16 v[48:51], v[246:249], v[200:203], v[48:51]
	v_mfma_f32_16x16x32_bf16 v[44:47], v[224:227], v[208:211], v[44:47]
	v_mfma_f32_16x16x32_bf16 v[40:43], v[246:249], v[208:211], v[40:43]
	v_mfma_f32_16x16x32_bf16 v[36:39], v[224:227], v[216:219], v[36:39]
	v_mfma_f32_16x16x32_bf16 v[32:35], v[246:249], v[216:219], v[32:35]
	s_setprio 0
	s_barrier
; #define PG8_STAGE(bufoff, gbase) do { _Pragma("unroll") for (int _i = 0; _i < 2; ++_i) \
;         __builtin_amdgcn_global_load_lds((const unsigned*)((const char*)(gbase) + voffA[_i]), (LAS unsigned*)(lds + (bufoff) + ldsw + _i * 8192), 16, 0, 0); } while (0)
; #define PG8_LDA(dst, b, h) do { _Pragma("unroll") for (int m = 0; m < 4; ++m) _Pragma("unroll") for (int k = 0; k < 2; ++k) dst[m][k] = *(const LAS bf16x8*)(lds + PG8_SA(b, h) + aoff + m * 2048 + k * 1024); } while (0)
; #define PG8_LDB(dst, b, h) do { _Pragma("unroll") for (int n = 0; n < 2; ++n) _Pragma("unroll") for (int k = 0; k < 2; ++k) dst[n][k] = *(const LAS bf16x8*)(lds + PG8_SB(b, h) + boff + n * 2048 + k * 1024); } while (0)
; #define PG8_MMA(ai, bj, At, Bt) do { __builtin_amdgcn_s_setprio(1); _Pragma("unroll") for (int m = 0; m < 4; ++m) _Pragma("unroll") for (int n = 0; n < 2; ++n) _Pragma("unroll") for (int k = 0; k < 2; ++k) \
;         acc[ai][bj][m][n] = __builtin_amdgcn_mfma_f32_16x16x32_bf16(Bt[n][k], At[m][k], acc[ai][bj][m][n], 0, 0, 0); __builtin_amdgcn_s_setprio(0); } while (0)
; #define PG8_WAIT_V(n) asm volatile("s_waitcnt vmcnt(" #n ")" ::: "memory")
; #define PG8_WAIT_L(n) asm volatile("s_waitcnt lgkmcnt(" #n ")" ::: "memory")
; #define PG8_BAR __builtin_amdgcn_s_barrier()
; #define PG8_SCHED __builtin_amdgcn_sched_barrier(0)
; template <class Epi>
; DI void gemm_phase(const int TID, const int BID, LAS unsigned char* lds, const Gemm g, const Epi& E) {
;     ...
;             PG8_LDB(B1, 1, 1); PG8_STAGE(PG8_SB(1, 0), b3);
;             PG8_BAR; PG8_WAIT_L(0); PG8_MMA(0, 1, At, B1); PG8_BAR;
;             PG8_LDA(At, 1, 1); PG8_STAGE(PG8_SA(1, 0), a3);
;             PG8_BAR; PG8_WAIT_L(0); PG8_MMA(1, 0, At, B0); PG8_BAR; PG8_SCHED;
;             PG8_STAGE(PG8_SB(1, 1), b3 + hstep);
;             PG8_WAIT_V(6); PG8_BAR; PG8_MMA(1, 1, At, B1); PG8_BAR;
;         }
	s_mov_b32 m0, s77
	v_lshl_add_u64 v[170:171], v[170:171], 0, s[92:93]
	global_load_lds_dwordx4 v[170:171], off
	v_lshl_add_u64 v[170:171], v[172:173], 0, s[92:93]
	s_mov_b32 m0, s80
	s_nop 0
	global_load_lds_dwordx4 v[170:171], off
	s_mov_b32 m0, s81
	v_lshl_add_u64 v[170:171], v[232:233], 0, s[92:93]
	global_load_lds_dwordx4 v[170:171], off
	v_lshl_add_u64 v[170:171], v[234:235], 0, s[92:93]
	s_mov_b32 m0, s8
	s_nop 0
	global_load_lds_dwordx4 v[170:171], off
	s_mov_b32 m0, s16
	v_lshl_add_u64 v[170:171], v[236:237], 0, s[92:93]
	global_load_lds_dwordx4 v[170:171], off
	v_lshl_add_u64 v[170:171], v[238:239], 0, s[92:93]
	s_mov_b32 m0, s17
	s_nop 0
	global_load_lds_dwordx4 v[170:171], off
	ds_read_b128 v[188:191], v175 offset:49152
	ds_read_b128 v[192:195], v175 offset:50176
	ds_read_b128 v[196:199], v175 offset:51200
	ds_read_b128 v[200:203], v175 offset:52224
	ds_read_b128 v[204:207], v175 offset:53248
	ds_read_b128 v[208:211], v175 offset:54272
	ds_read_b128 v[212:215], v175 offset:55296
	ds_read_b128 v[216:219], v175 offset:56320
	s_waitcnt vmcnt(8)
	s_waitcnt lgkmcnt(0)
	s_barrier
	s_setprio 1
	v_mfma_f32_16x16x32_bf16 v[92:95], v[156:159], v[188:191], v[92:95]
	v_mfma_f32_16x16x32_bf16 v[88:91], v[180:183], v[188:191], v[88:91]
	v_mfma_f32_16x16x32_bf16 v[84:87], v[156:159], v[196:199], v[84:87]
	v_mfma_f32_16x16x32_bf16 v[80:83], v[180:183], v[196:199], v[80:83]
	v_mfma_f32_16x16x32_bf16 v[76:79], v[156:159], v[204:207], v[76:79]
	v_mfma_f32_16x16x32_bf16 v[72:75], v[180:183], v[204:207], v[72:75]
	v_mfma_f32_16x16x32_bf16 v[68:71], v[156:159], v[212:215], v[68:71]
	v_mfma_f32_16x16x32_bf16 v[64:67], v[180:183], v[212:215], v[64:67]
	v_mfma_f32_16x16x32_bf16 v[92:95], v[176:179], v[192:195], v[92:95]
	v_mfma_f32_16x16x32_bf16 v[88:91], v[184:187], v[192:195], v[88:91]
	v_mfma_f32_16x16x32_bf16 v[84:87], v[176:179], v[200:203], v[84:87]
	v_mfma_f32_16x16x32_bf16 v[80:83], v[184:187], v[200:203], v[80:83]
	v_mfma_f32_16x16x32_bf16 v[76:79], v[176:179], v[208:211], v[76:79]
	v_mfma_f32_16x16x32_bf16 v[72:75], v[184:187], v[208:211], v[72:75]
	v_mfma_f32_16x16x32_bf16 v[68:71], v[176:179], v[216:219], v[68:71]
	v_mfma_f32_16x16x32_bf16 v[64:67], v[184:187], v[216:219], v[64:67]
	v_mfma_f32_16x16x32_bf16 v[28:31], v[220:223], v[188:191], v[28:31]
	v_mfma_f32_16x16x32_bf16 v[24:27], v[228:231], v[188:191], v[24:27]
	v_mfma_f32_16x16x32_bf16 v[20:23], v[220:223], v[196:199], v[20:23]
	v_mfma_f32_16x16x32_bf16 v[16:19], v[228:231], v[196:199], v[16:19]
	v_mfma_f32_16x16x32_bf16 v[12:15], v[220:223], v[204:207], v[12:15]
	v_mfma_f32_16x16x32_bf16 v[8:11], v[228:231], v[204:207], v[8:11]
	v_mfma_f32_16x16x32_bf16 v[4:7], v[220:223], v[212:215], v[4:7]
	v_mfma_f32_16x16x32_bf16 v[0:3], v[228:231], v[212:215], v[0:3]
	v_mfma_f32_16x16x32_bf16 v[28:31], v[224:227], v[192:195], v[28:31]
	v_mfma_f32_16x16x32_bf16 v[24:27], v[246:249], v[192:195], v[24:27]
	v_mfma_f32_16x16x32_bf16 v[20:23], v[224:227], v[200:203], v[20:23]
	v_mfma_f32_16x16x32_bf16 v[16:19], v[246:249], v[200:203], v[16:19]
	v_mfma_f32_16x16x32_bf16 v[12:15], v[224:227], v[208:211], v[12:15]
	v_mfma_f32_16x16x32_bf16 v[8:11], v[246:249], v[208:211], v[8:11]
	v_mfma_f32_16x16x32_bf16 v[4:7], v[224:227], v[216:219], v[4:7]
	v_mfma_f32_16x16x32_bf16 v[0:3], v[246:249], v[216:219], v[0:3]
	s_setprio 0
	s_add_u32 s4, s4, 0x100
	s_addc_u32 s5, s5, 0
	s_add_u32 s28, s28, 0x100
	s_addc_u32 s29, s29, 0
	s_cmp_ge_i32 s31, s21
	s_mov_b32 s30, s31
	s_barrier
	s_cbranch_scc0 .LBB0_568
	v_readlane_b32 s31, v255, 8

; #define PG8_STAGE(bufoff, gbase) do { _Pragma("unroll") for (int _i = 0; _i < 2; ++_i) \
;         __builtin_amdgcn_global_load_lds((const unsigned*)((const char*)(gbase) + voffA[_i]), (LAS unsigned*)(lds + (bufoff) + ldsw + _i * 8192), 16, 0, 0); } while (0)
; #define PG8_LDA(dst, b, h) do { _Pragma("unroll") for (int m = 0; m < 4; ++m) _Pragma("unroll") for (int k = 0; k < 2; ++k) dst[m][k] = *(const LAS bf16x8*)(lds + PG8_SA(b, h) + aoff + m * 2048 + k * 1024); } while (0)
; #define PG8_LDB(dst, b, h) do { _Pragma("unroll") for (int n = 0; n < 2; ++n) _Pragma("unroll") for (int k = 0; k < 2; ++k) dst[n][k] = *(const LAS bf16x8*)(lds + PG8_SB(b, h) + boff + n * 2048 + k * 1024); } while (0)
; #define PG8_MMA(ai, bj, At, Bt) do { __builtin_amdgcn_s_setprio(1); _Pragma("unroll") for (int m = 0; m < 4; ++m) _Pragma("unroll") for (int n = 0; n < 2; ++n) _Pragma("unroll") for (int k = 0; k < 2; ++k) \
;         acc[ai][bj][m][n] = __builtin_amdgcn_mfma_f32_16x16x32_bf16(Bt[n][k], At[m][k], acc[ai][bj][m][n], 0, 0, 0); __builtin_amdgcn_s_setprio(0); } while (0)
; #define PG8_WAIT_L(n) asm volatile("s_waitcnt lgkmcnt(" #n ")" ::: "memory")
; #define PG8_BAR __builtin_amdgcn_s_barrier()
; #define PG8_SCHED __builtin_amdgcn_sched_barrier(0)
; template <class Epi>
; DI void gemm_phase(const int TID, const int BID, LAS unsigned char* lds, const Gemm g, const Epi& E) {
;     ...
;         for (int t = 0; t < nt; t += 2) {
;             const bool last = (t == nt - 2);
;             const char* a1 = cA + (size_t)(t + 1) * kstep;
;             const char* a2 = last ? nA : cA + (size_t)(t + 2) * kstep; const char* b2 = last ? nB : cB + (size_t)(t + 2) * kstep;
;             const char* a3 = a2 + kstep; const char* b3 = b2 + kstep;
;             PG8_LDB(B0, 0, 0); PG8_SCHED; PG8_LDA(At, 0, 0); PG8_STAGE(PG8_SA(1, 1), a1 + hstep);
;             PG8_WAIT_L(8); PG8_BAR; PG8_WAIT_L(0); PG8_MMA(0, 0, At, B0); PG8_BAR; PG8_SCHED;
;             PG8_LDB(B1, 0, 1); PG8_STAGE(PG8_SB(0, 0), b2);
;             PG8_BAR; PG8_WAIT_L(0); PG8_MMA(0, 1, At, B1); PG8_BAR;
.LBB0_746:
	s_add_i32 s24, s23, 2
	s_add_u32 s4, s2, 0x80
	s_addc_u32 s5, s3, 0
	s_cmp_eq_u32 s0, s23
	s_cselect_b32 s5, s55, s5
	s_cselect_b32 s4, s54, s4
	s_cselect_b32 s59, s57, s20
	s_cselect_b32 s58, s56, s19
	v_lshl_add_u64 v[170:171], s[2:3], 0, v[176:177]
	s_add_i32 m0, s84, 0xc000
	global_load_lds_dwordx4 v[170:171], off
	v_lshl_add_u64 v[170:171], s[2:3], 0, v[178:179]
	s_add_i32 m0, s84, 0xe000
	s_nop 0
	global_load_lds_dwordx4 v[170:171], off
	v_add_u32_e32 v76, s65, v175
	ds_read_b128 v[64:67], v76
	ds_read_b128 v[68:71], v76 offset:1024
	ds_read_b128 v[72:75], v76 offset:2048
	ds_read_b128 v[76:79], v76 offset:3072
	ds_read_b128 v[188:191], v187
	ds_read_b128 v[192:195], v187 offset:1024
	ds_read_b128 v[196:199], v187 offset:2048
	ds_read_b128 v[200:203], v187 offset:3072
	ds_read_b128 v[204:207], v187 offset:4096
	ds_read_b128 v[208:211], v187 offset:5120
	ds_read_b128 v[212:215], v187 offset:6144
	ds_read_b128 v[216:219], v187 offset:7168
	v_add_u32_e32 v168, s63, v175
	ds_read_b128 v[220:223], v168
	ds_read_b128 v[224:227], v168 offset:1024
	ds_read_b128 v[228:231], v168 offset:2048
	ds_read_b128 v[246:249], v168 offset:3072
	s_waitcnt vmcnt(8)
	s_waitcnt lgkmcnt(0)
	s_barrier
	s_setprio 1
	v_mfma_f32_16x16x32_bf16 v[140:143], v[64:67], v[188:191], v[140:143]
	v_mfma_f32_16x16x32_bf16 v[136:139], v[72:75], v[188:191], v[136:139]
	v_mfma_f32_16x16x32_bf16 v[124:127], v[64:67], v[196:199], v[124:127]
	v_mfma_f32_16x16x32_bf16 v[120:123], v[72:75], v[196:199], v[120:123]
	v_mfma_f32_16x16x32_bf16 v[108:111], v[64:67], v[204:207], v[108:111]
	v_mfma_f32_16x16x32_bf16 v[104:107], v[72:75], v[204:207], v[104:107]
	v_mfma_f32_16x16x32_bf16 v[92:95], v[64:67], v[212:215], v[92:95]
	v_mfma_f32_16x16x32_bf16 v[88:91], v[72:75], v[212:215], v[88:91]
	v_mfma_f32_16x16x32_bf16 v[140:143], v[68:71], v[192:195], v[140:143]
	v_mfma_f32_16x16x32_bf16 v[136:139], v[76:79], v[192:195], v[136:139]
	v_mfma_f32_16x16x32_bf16 v[124:127], v[68:71], v[200:203], v[124:127]
	v_mfma_f32_16x16x32_bf16 v[120:123], v[76:79], v[200:203], v[120:123]
	v_mfma_f32_16x16x32_bf16 v[108:111], v[68:71], v[208:211], v[108:111]
	v_mfma_f32_16x16x32_bf16 v[104:107], v[76:79], v[208:211], v[104:107]
	v_mfma_f32_16x16x32_bf16 v[92:95], v[68:71], v[216:219], v[92:95]
	v_mfma_f32_16x16x32_bf16 v[88:91], v[76:79], v[216:219], v[88:91]
	v_mfma_f32_16x16x32_bf16 v[132:135], v[220:223], v[188:191], v[132:135]
	v_mfma_f32_16x16x32_bf16 v[128:131], v[228:231], v[188:191], v[128:131]
	v_mfma_f32_16x16x32_bf16 v[116:119], v[220:223], v[196:199], v[116:119]
	v_mfma_f32_16x16x32_bf16 v[112:115], v[228:231], v[196:199], v[112:115]
	v_mfma_f32_16x16x32_bf16 v[100:103], v[220:223], v[204:207], v[100:103]
	v_mfma_f32_16x16x32_bf16 v[96:99], v[228:231], v[204:207], v[96:99]
	v_mfma_f32_16x16x32_bf16 v[84:87], v[220:223], v[212:215], v[84:87]
	v_mfma_f32_16x16x32_bf16 v[80:83], v[228:231], v[212:215], v[80:83]
	v_mfma_f32_16x16x32_bf16 v[132:135], v[224:227], v[192:195], v[132:135]
	v_mfma_f32_16x16x32_bf16 v[128:131], v[246:249], v[192:195], v[128:131]
	v_mfma_f32_16x16x32_bf16 v[116:119], v[224:227], v[200:203], v[116:119]
	v_mfma_f32_16x16x32_bf16 v[112:115], v[246:249], v[200:203], v[112:115]
	v_mfma_f32_16x16x32_bf16 v[100:103], v[224:227], v[208:211], v[100:103]
	v_mfma_f32_16x16x32_bf16 v[96:99], v[246:249], v[208:211], v[96:99]
	v_mfma_f32_16x16x32_bf16 v[84:87], v[224:227], v[216:219], v[84:87]
	v_mfma_f32_16x16x32_bf16 v[80:83], v[246:249], v[216:219], v[80:83]
	s_setprio 0
	s_barrier
	s_mov_b32 m0, s66
	v_lshl_add_u64 v[170:171], s[58:59], 0, v[144:145]
	global_load_lds_dwordx4 v[170:171], off
	v_lshl_add_u64 v[172:173], s[58:59], 0, v[146:147]
	s_mov_b32 m0, s67
	s_nop 0
	global_load_lds_dwordx4 v[172:173], off
	s_mov_b32 m0, s84
	v_lshl_add_u64 v[232:233], s[4:5], 0, v[144:145]
	global_load_lds_dwordx4 v[232:233], off
	v_lshl_add_u64 v[234:235], s[4:5], 0, v[146:147]
	s_mov_b32 m0, s62
	s_nop 0
	global_load_lds_dwordx4 v[234:235], off
	s_add_u32 s26, s58, s6
	s_addc_u32 s27, s59, s7
	s_mov_b32 m0, s64
	v_lshl_add_u64 v[236:237], s[26:27], 0, v[144:145]
	global_load_lds_dwordx4 v[236:237], off
	v_lshl_add_u64 v[238:239], s[26:27], 0, v[146:147]
	s_mov_b32 m0, s10
	s_nop 0
	global_load_lds_dwordx4 v[238:239], off
	ds_read_b128 v[188:191], v187 offset:16384
	ds_read_b128 v[192:195], v187 offset:17408
	ds_read_b128 v[196:199], v187 offset:18432
	ds_read_b128 v[200:203], v187 offset:19456
	ds_read_b128 v[204:207], v187 offset:20480
	ds_read_b128 v[208:211], v187 offset:21504
	ds_read_b128 v[212:215], v187 offset:22528
	ds_read_b128 v[216:219], v187 offset:23552
	s_waitcnt vmcnt(8)
	s_waitcnt lgkmcnt(0)
	s_barrier
; #define PG8_STAGE(bufoff, gbase) do { _Pragma("unroll") for (int _i = 0; _i < 2; ++_i) \
;         __builtin_amdgcn_global_load_lds((const unsigned*)((const char*)(gbase) + voffA[_i]), (LAS unsigned*)(lds + (bufoff) + ldsw + _i * 8192), 16, 0, 0); } while (0)
; #define PG8_LDA(dst, b, h) do { _Pragma("unroll") for (int m = 0; m < 4; ++m) _Pragma("unroll") for (int k = 0; k < 2; ++k) dst[m][k] = *(const LAS bf16x8*)(lds + PG8_SA(b, h) + aoff + m * 2048 + k * 1024); } while (0)
; #define PG8_LDB(dst, b, h) do { _Pragma("unroll") for (int n = 0; n < 2; ++n) _Pragma("unroll") for (int k = 0; k < 2; ++k) dst[n][k] = *(const LAS bf16x8*)(lds + PG8_SB(b, h) + boff + n * 2048 + k * 1024); } while (0)
; #define PG8_MMA(ai, bj, At, Bt) do { __builtin_amdgcn_s_setprio(1); _Pragma("unroll") for (int m = 0; m < 4; ++m) _Pragma("unroll") for (int n = 0; n < 2; ++n) _Pragma("unroll") for (int k = 0; k < 2; ++k) \
;         acc[ai][bj][m][n] = __builtin_amdgcn_mfma_f32_16x16x32_bf16(Bt[n][k], At[m][k], acc[ai][bj][m][n], 0, 0, 0); __builtin_amdgcn_s_setprio(0); } while (0)
; #define PG8_WAIT_V(n) asm volatile("s_waitcnt vmcnt(" #n ")" ::: "memory")
; #define PG8_WAIT_L(n) asm volatile("s_waitcnt lgkmcnt(" #n ")" ::: "memory")
; #define PG8_BAR __builtin_amdgcn_s_barrier()
; #define PG8_SCHED __builtin_amdgcn_sched_barrier(0)
; template <class Epi>
; DI void gemm_phase(const int TID, const int BID, LAS unsigned char* lds, const Gemm g, const Epi& E) {
;     ...
;             PG8_BAR; PG8_WAIT_L(0); PG8_MMA(0, 1, At, B1); PG8_BAR;
;             PG8_LDA(At, 0, 1); PG8_STAGE(PG8_SA(0, 0), a2);
;             PG8_BAR; PG8_WAIT_L(0); PG8_MMA(1, 0, At, B0); PG8_BAR; PG8_SCHED;
;             PG8_STAGE(PG8_SB(0, 1), b2 + hstep);
;             PG8_WAIT_V(6); PG8_BAR; PG8_MMA(1, 1, At, B1); PG8_BAR;
;             PG8_LDB(B0, 1, 0); PG8_SCHED; PG8_LDA(At, 1, 0); PG8_STAGE(PG8_SA(0, 1), a2 + hstep);
;             PG8_WAIT_L(8); PG8_BAR; PG8_WAIT_L(0); PG8_MMA(0, 0, At, B0); PG8_BAR; PG8_SCHED;
	s_setprio 1
	v_mfma_f32_16x16x32_bf16 v[60:63], v[64:67], v[188:191], v[60:63]
	v_mfma_f32_16x16x32_bf16 v[56:59], v[72:75], v[188:191], v[56:59]
	v_mfma_f32_16x16x32_bf16 v[44:47], v[64:67], v[196:199], v[44:47]
	v_mfma_f32_16x16x32_bf16 v[40:43], v[72:75], v[196:199], v[40:43]
	v_mfma_f32_16x16x32_bf16 v[28:31], v[64:67], v[204:207], v[28:31]
	v_mfma_f32_16x16x32_bf16 v[24:27], v[72:75], v[204:207], v[24:27]
	v_mfma_f32_16x16x32_bf16 v[12:15], v[64:67], v[212:215], v[12:15]
	v_mfma_f32_16x16x32_bf16 v[8:11], v[72:75], v[212:215], v[8:11]
	v_mfma_f32_16x16x32_bf16 v[60:63], v[68:71], v[192:195], v[60:63]
	v_mfma_f32_16x16x32_bf16 v[56:59], v[76:79], v[192:195], v[56:59]
	v_mfma_f32_16x16x32_bf16 v[44:47], v[68:71], v[200:203], v[44:47]
	v_mfma_f32_16x16x32_bf16 v[40:43], v[76:79], v[200:203], v[40:43]
	v_mfma_f32_16x16x32_bf16 v[28:31], v[68:71], v[208:211], v[28:31]
	v_mfma_f32_16x16x32_bf16 v[24:27], v[76:79], v[208:211], v[24:27]
	v_mfma_f32_16x16x32_bf16 v[12:15], v[68:71], v[216:219], v[12:15]
	v_mfma_f32_16x16x32_bf16 v[8:11], v[76:79], v[216:219], v[8:11]
	v_mfma_f32_16x16x32_bf16 v[52:55], v[220:223], v[188:191], v[52:55]
	v_mfma_f32_16x16x32_bf16 v[48:51], v[228:231], v[188:191], v[48:51]
	v_mfma_f32_16x16x32_bf16 v[36:39], v[220:223], v[196:199], v[36:39]
	v_mfma_f32_16x16x32_bf16 v[32:35], v[228:231], v[196:199], v[32:35]
	v_mfma_f32_16x16x32_bf16 v[20:23], v[220:223], v[204:207], v[20:23]
	v_mfma_f32_16x16x32_bf16 v[16:19], v[228:231], v[204:207], v[16:19]
	v_mfma_f32_16x16x32_bf16 v[0:3], v[220:223], v[212:215], v[0:3]
	v_mfma_f32_16x16x32_bf16 v[4:7], v[228:231], v[212:215], v[4:7]
	v_mfma_f32_16x16x32_bf16 v[52:55], v[224:227], v[192:195], v[52:55]
	v_mfma_f32_16x16x32_bf16 v[48:51], v[246:249], v[192:195], v[48:51]
	v_mfma_f32_16x16x32_bf16 v[36:39], v[224:227], v[200:203], v[36:39]
	v_mfma_f32_16x16x32_bf16 v[32:35], v[246:249], v[200:203], v[32:35]
	v_mfma_f32_16x16x32_bf16 v[20:23], v[224:227], v[208:211], v[20:23]
	v_mfma_f32_16x16x32_bf16 v[16:19], v[246:249], v[208:211], v[16:19]
	v_mfma_f32_16x16x32_bf16 v[0:3], v[224:227], v[216:219], v[0:3]
	v_mfma_f32_16x16x32_bf16 v[4:7], v[246:249], v[216:219], v[4:7]
	s_setprio 0
	s_barrier
	s_add_u32 s4, s4, s6
	s_addc_u32 s5, s5, s7
	s_mov_b32 m0, s11
	v_lshl_add_u64 v[220:221], s[4:5], 0, v[144:145]
	global_load_lds_dwordx4 v[220:221], off
	v_lshl_add_u64 v[220:221], s[4:5], 0, v[146:147]
	s_mov_b32 m0, s12
	s_nop 0
	global_load_lds_dwordx4 v[220:221], off
	v_add_u32_e32 v76, s13, v175
	ds_read_b128 v[64:67], v76
	ds_read_b128 v[68:71], v76 offset:1024
	ds_read_b128 v[72:75], v76 offset:2048
	ds_read_b128 v[76:79], v76 offset:3072
	ds_read_b128 v[188:191], v187 offset:32768
	ds_read_b128 v[192:195], v187 offset:33792
	ds_read_b128 v[196:199], v187 offset:34816
	ds_read_b128 v[200:203], v187 offset:35840
	ds_read_b128 v[204:207], v187 offset:36864
	ds_read_b128 v[208:211], v187 offset:37888
	ds_read_b128 v[212:215], v187 offset:38912
	ds_read_b128 v[216:219], v187 offset:39936
	v_add_u32_e32 v168, s80, v175
	ds_read_b128 v[220:223], v168
	ds_read_b128 v[224:227], v168 offset:1024
	ds_read_b128 v[228:231], v168 offset:2048
	ds_read_b128 v[246:249], v168 offset:3072
	s_waitcnt vmcnt(8)
	s_waitcnt lgkmcnt(0)
	s_barrier
	s_setprio 1
	v_mfma_f32_16x16x32_bf16 v[140:143], v[64:67], v[188:191], v[140:143]
	v_mfma_f32_16x16x32_bf16 v[136:139], v[72:75], v[188:191], v[136:139]
	v_mfma_f32_16x16x32_bf16 v[124:127], v[64:67], v[196:199], v[124:127]
	v_mfma_f32_16x16x32_bf16 v[120:123], v[72:75], v[196:199], v[120:123]
	v_mfma_f32_16x16x32_bf16 v[108:111], v[64:67], v[204:207], v[108:111]
	v_mfma_f32_16x16x32_bf16 v[104:107], v[72:75], v[204:207], v[104:107]
	v_mfma_f32_16x16x32_bf16 v[92:95], v[64:67], v[212:215], v[92:95]
	v_mfma_f32_16x16x32_bf16 v[88:91], v[72:75], v[212:215], v[88:91]
	v_mfma_f32_16x16x32_bf16 v[140:143], v[68:71], v[192:195], v[140:143]
	v_mfma_f32_16x16x32_bf16 v[136:139], v[76:79], v[192:195], v[136:139]
	v_mfma_f32_16x16x32_bf16 v[124:127], v[68:71], v[200:203], v[124:127]
	v_mfma_f32_16x16x32_bf16 v[120:123], v[76:79], v[200:203], v[120:123]
	v_mfma_f32_16x16x32_bf16 v[108:111], v[68:71], v[208:211], v[108:111]
	v_mfma_f32_16x16x32_bf16 v[104:107], v[76:79], v[208:211], v[104:107]
	v_mfma_f32_16x16x32_bf16 v[92:95], v[68:71], v[216:219], v[92:95]
	v_mfma_f32_16x16x32_bf16 v[88:91], v[76:79], v[216:219], v[88:91]
	v_mfma_f32_16x16x32_bf16 v[132:135], v[220:223], v[188:191], v[132:135]
	v_mfma_f32_16x16x32_bf16 v[128:131], v[228:231], v[188:191], v[128:131]
	v_mfma_f32_16x16x32_bf16 v[116:119], v[220:223], v[196:199], v[116:119]
	v_mfma_f32_16x16x32_bf16 v[112:115], v[228:231], v[196:199], v[112:115]
	v_mfma_f32_16x16x32_bf16 v[100:103], v[220:223], v[204:207], v[100:103]
	v_mfma_f32_16x16x32_bf16 v[96:99], v[228:231], v[204:207], v[96:99]
	v_mfma_f32_16x16x32_bf16 v[84:87], v[220:223], v[212:215], v[84:87]
	v_mfma_f32_16x16x32_bf16 v[80:83], v[228:231], v[212:215], v[80:83]
	v_mfma_f32_16x16x32_bf16 v[132:135], v[224:227], v[192:195], v[132:135]
	v_mfma_f32_16x16x32_bf16 v[128:131], v[246:249], v[192:195], v[128:131]
	v_mfma_f32_16x16x32_bf16 v[116:119], v[224:227], v[200:203], v[116:119]
	v_mfma_f32_16x16x32_bf16 v[112:115], v[246:249], v[200:203], v[112:115]
	v_mfma_f32_16x16x32_bf16 v[100:103], v[224:227], v[208:211], v[100:103]
	v_mfma_f32_16x16x32_bf16 v[96:99], v[246:249], v[208:211], v[96:99]
	v_mfma_f32_16x16x32_bf16 v[84:87], v[224:227], v[216:219], v[84:87]
	v_mfma_f32_16x16x32_bf16 v[80:83], v[246:249], v[216:219], v[80:83]
	s_setprio 0
	s_barrier
; #define PG8_STAGE(bufoff, gbase) do { _Pragma("unroll") for (int _i = 0; _i < 2; ++_i) \
;         __builtin_amdgcn_global_load_lds((const unsigned*)((const char*)(gbase) + voffA[_i]), (LAS unsigned*)(lds + (bufoff) + ldsw + _i * 8192), 16, 0, 0); } while (0)
; #define PG8_LDA(dst, b, h) do { _Pragma("unroll") for (int m = 0; m < 4; ++m) _Pragma("unroll") for (int k = 0; k < 2; ++k) dst[m][k] = *(const LAS bf16x8*)(lds + PG8_SA(b, h) + aoff + m * 2048 + k * 1024); } while (0)
; #define PG8_LDB(dst, b, h) do { _Pragma("unroll") for (int n = 0; n < 2; ++n) _Pragma("unroll") for (int k = 0; k < 2; ++k) dst[n][k] = *(const LAS bf16x8*)(lds + PG8_SB(b, h) + boff + n * 2048 + k * 1024); } while (0)
; #define PG8_MMA(ai, bj, At, Bt) do { __builtin_amdgcn_s_setprio(1); _Pragma("unroll") for (int m = 0; m < 4; ++m) _Pragma("unroll") for (int n = 0; n < 2; ++n) _Pragma("unroll") for (int k = 0; k < 2; ++k) \
;         acc[ai][bj][m][n] = __builtin_amdgcn_mfma_f32_16x16x32_bf16(Bt[n][k], At[m][k], acc[ai][bj][m][n], 0, 0, 0); __builtin_amdgcn_s_setprio(0); } while (0)
; #define PG8_WAIT_V(n) asm volatile("s_waitcnt vmcnt(" #n ")" ::: "memory")
; #define PG8_WAIT_L(n) asm volatile("s_waitcnt lgkmcnt(" #n ")" ::: "memory")
; #define PG8_BAR __builtin_amdgcn_s_barrier()
; #define PG8_SCHED __builtin_amdgcn_sched_barrier(0)
; template <class Epi>
; DI void gemm_phase(const int TID, const int BID, LAS unsigned char* lds, const Gemm g, const Epi& E) {
;     ...
;             PG8_LDB(B1, 1, 1); PG8_STAGE(PG8_SB(1, 0), b3);
;             PG8_BAR; PG8_WAIT_L(0); PG8_MMA(0, 1, At, B1); PG8_BAR;
;             PG8_LDA(At, 1, 1); PG8_STAGE(PG8_SA(1, 0), a3);
;             PG8_BAR; PG8_WAIT_L(0); PG8_MMA(1, 0, At, B0); PG8_BAR; PG8_SCHED;
;             PG8_STAGE(PG8_SB(1, 1), b3 + hstep);
;             PG8_WAIT_V(6); PG8_BAR; PG8_MMA(1, 1, At, B1); PG8_BAR;
;         }
	s_mov_b32 m0, s76
	v_lshl_add_u64 v[170:171], v[170:171], 0, s[92:93]
	global_load_lds_dwordx4 v[170:171], off
	v_lshl_add_u64 v[170:171], v[172:173], 0, s[92:93]
	s_mov_b32 m0, s77
	s_nop 0
	global_load_lds_dwordx4 v[170:171], off
	s_mov_b32 m0, s33
	v_lshl_add_u64 v[170:171], v[232:233], 0, s[92:93]
	global_load_lds_dwordx4 v[170:171], off
	v_lshl_add_u64 v[170:171], v[234:235], 0, s[92:93]
	s_mov_b32 m0, s15
	s_nop 0
	global_load_lds_dwordx4 v[170:171], off
	s_mov_b32 m0, s81
	v_lshl_add_u64 v[170:171], v[236:237], 0, s[92:93]
	global_load_lds_dwordx4 v[170:171], off
	v_lshl_add_u64 v[170:171], v[238:239], 0, s[92:93]
	s_mov_b32 m0, s8
	s_nop 0
	global_load_lds_dwordx4 v[170:171], off
	ds_read_b128 v[188:191], v187 offset:49152
	ds_read_b128 v[192:195], v187 offset:50176
	ds_read_b128 v[196:199], v187 offset:51200
	ds_read_b128 v[200:203], v187 offset:52224
	ds_read_b128 v[204:207], v187 offset:53248
	ds_read_b128 v[208:211], v187 offset:54272
	ds_read_b128 v[212:215], v187 offset:55296
	ds_read_b128 v[216:219], v187 offset:56320
	s_waitcnt vmcnt(8)
	s_waitcnt lgkmcnt(0)
	s_barrier
	s_setprio 1
	v_mfma_f32_16x16x32_bf16 v[60:63], v[64:67], v[188:191], v[60:63]
	v_mfma_f32_16x16x32_bf16 v[56:59], v[72:75], v[188:191], v[56:59]
	v_mfma_f32_16x16x32_bf16 v[44:47], v[64:67], v[196:199], v[44:47]
	v_mfma_f32_16x16x32_bf16 v[40:43], v[72:75], v[196:199], v[40:43]
	v_mfma_f32_16x16x32_bf16 v[28:31], v[64:67], v[204:207], v[28:31]
	v_mfma_f32_16x16x32_bf16 v[24:27], v[72:75], v[204:207], v[24:27]
	v_mfma_f32_16x16x32_bf16 v[12:15], v[64:67], v[212:215], v[12:15]
	v_mfma_f32_16x16x32_bf16 v[8:11], v[72:75], v[212:215], v[8:11]
	v_mfma_f32_16x16x32_bf16 v[60:63], v[68:71], v[192:195], v[60:63]
	v_mfma_f32_16x16x32_bf16 v[56:59], v[76:79], v[192:195], v[56:59]
	v_mfma_f32_16x16x32_bf16 v[44:47], v[68:71], v[200:203], v[44:47]
	v_mfma_f32_16x16x32_bf16 v[40:43], v[76:79], v[200:203], v[40:43]
	v_mfma_f32_16x16x32_bf16 v[28:31], v[68:71], v[208:211], v[28:31]
	v_mfma_f32_16x16x32_bf16 v[24:27], v[76:79], v[208:211], v[24:27]
	v_mfma_f32_16x16x32_bf16 v[12:15], v[68:71], v[216:219], v[12:15]
	v_mfma_f32_16x16x32_bf16 v[8:11], v[76:79], v[216:219], v[8:11]
	v_mfma_f32_16x16x32_bf16 v[52:55], v[220:223], v[188:191], v[52:55]
	v_mfma_f32_16x16x32_bf16 v[48:51], v[228:231], v[188:191], v[48:51]
	v_mfma_f32_16x16x32_bf16 v[36:39], v[220:223], v[196:199], v[36:39]
	v_mfma_f32_16x16x32_bf16 v[32:35], v[228:231], v[196:199], v[32:35]
	v_mfma_f32_16x16x32_bf16 v[20:23], v[220:223], v[204:207], v[20:23]
	v_mfma_f32_16x16x32_bf16 v[16:19], v[228:231], v[204:207], v[16:19]
	v_mfma_f32_16x16x32_bf16 v[0:3], v[220:223], v[212:215], v[0:3]
	v_mfma_f32_16x16x32_bf16 v[4:7], v[228:231], v[212:215], v[4:7]
	v_mfma_f32_16x16x32_bf16 v[52:55], v[224:227], v[192:195], v[52:55]
	v_mfma_f32_16x16x32_bf16 v[48:51], v[246:249], v[192:195], v[48:51]
	v_mfma_f32_16x16x32_bf16 v[36:39], v[224:227], v[200:203], v[36:39]
	v_mfma_f32_16x16x32_bf16 v[32:35], v[246:249], v[200:203], v[32:35]
	v_mfma_f32_16x16x32_bf16 v[20:23], v[224:227], v[208:211], v[20:23]
	v_mfma_f32_16x16x32_bf16 v[16:19], v[246:249], v[208:211], v[16:19]
	v_mfma_f32_16x16x32_bf16 v[0:3], v[224:227], v[216:219], v[0:3]
	v_mfma_f32_16x16x32_bf16 v[4:7], v[246:249], v[216:219], v[4:7]
	s_setprio 0
	s_add_u32 s2, s2, 0x100
	s_addc_u32 s3, s3, 0
	s_add_u32 s19, s19, 0x100
	s_addc_u32 s20, s20, 0
	s_cmp_ge_i32 s24, s9
	s_mov_b32 s23, s24
	s_barrier
	s_cbranch_scc0 .LBB0_746
	v_readlane_b32 s26, v255, 16
	v_readlane_b32 s27, v255, 17
